# all GEMM epilogue bf16 stores without nt hint (write-back L2 absorbs the per-unit store burst); MFMA blocks 8B aligned
# speedup vs baseline: 1.0188x; 1.0091x over previous
; #define PG8_STAGE(bufoff, gbase, voff) do { _Pragma("unroll") for (int _i = 0; _i < 2; ++_i) \
;         __builtin_amdgcn_global_load_lds((const unsigned*)((const char*)(gbase) + (voff)[_i]), (LAS unsigned*)(lds + (bufoff) + ldsw + _i * 8192), 16, 0, 0); } while (0)
; #define PG8_LDA(dst, b, h) do { _Pragma("unroll") for (int m = 0; m < 4; ++m) _Pragma("unroll") for (int k = 0; k < 2; ++k) dst[m][k] = *(const LAS bf16x8*)(lds + PG8_SA(b, h) + aoff + m * 2048 + k * 1024); } while (0)
; #define PG8_LDB(dst, b, h) do { _Pragma("unroll") for (int n = 0; n < 2; ++n) _Pragma("unroll") for (int k = 0; k < 2; ++k) dst[n][k] = *(const LAS bf16x8*)(lds + PG8_SB(b, h) + boff + n * 2048 + k * 1024); } while (0)
; #define PG8_WAIT_V(n) asm volatile("s_waitcnt vmcnt(" #n ")" ::: "memory")
; #define PG8_WAIT_L(n) asm volatile("s_waitcnt lgkmcnt(" #n ")" ::: "memory")
; #define PG8_BAR __builtin_amdgcn_s_barrier()
; template <class Epi>
; __device__ __forceinline__ void gemm_phase(LAS unsigned char* lds, const GSched& S, const int K, const int lda, const int ldb, const Epi& E) {
;     ...
;         for (int t = 0; t < nt; t += 2) {
;             const bool last = (t == nt - 2);
;             const char* a1 = cA + (size_t)(t + 1) * kstep;
;             const char* a2 = last ? nA : cA + (size_t)(t + 2) * kstep; const char* b2 = last ? nB : cB + (size_t)(t + 2) * kstep;
;             const char* a3 = a2 + kstep; const char* b3 = b2 + kstep;
;             PG8_LDB(B0, 0, 0); PG8_SCHED; PG8_LDA(At, 0, 0); PG8_STAGE(PG8_SA(1, 1), a1 + hstepA, voffA);
;             PG8_WAIT_L(8); PG8_BAR; PG8_WAIT_L(0); PG8_MMA(0, 0, At, B0); PG8_BAR; PG8_SCHED;
;             if constexpr (!Epi::NARROW) PG8_LDB(B1, 0, 1); PG8_STAGE(PG8_SB(0, 0), b2, voffB);
;             PG8_BAR; PG8_WAIT_L(0); if constexpr (!Epi::NARROW) PG8_MMA(0, 1, At, B1); PG8_BAR;
;             PG8_LDA(At, 0, 1); PG8_STAGE(PG8_SA(0, 0), a2, voffA);
;             PG8_BAR; PG8_WAIT_L(0); PG8_MMA(1, 0, At, B0); PG8_BAR; PG8_SCHED;
;             PG8_STAGE(PG8_SB(0, 1), b2 + hstepB, voffB);
;             PG8_WAIT_V(6); PG8_BAR; if constexpr (!Epi::NARROW) PG8_MMA(1, 1, At, B1); PG8_BAR;
;             PG8_LDB(B0, 1, 0); PG8_SCHED; PG8_LDA(At, 1, 0); PG8_STAGE(PG8_SA(0, 1), a2 + hstepA, voffA);
;             PG8_WAIT_L(8); PG8_BAR; PG8_WAIT_L(0); PG8_MMA(0, 0, At, B0); PG8_BAR; PG8_SCHED;
.LBB0_438:
	ds_read_b128 v[166:169], v161
	ds_read_b128 v[170:173], v161 offset:1024
	ds_read_b128 v[174:177], v161 offset:2048
	ds_read_b128 v[178:181], v161 offset:3072
	s_add_u32 s6, s14, 0x100
	s_addc_u32 s7, s15, 0
	s_cmp_eq_u32 s48, 28
	s_cselect_b32 s45, s41, s7
	s_cselect_b32 s44, s40, s6
	s_cselect_b32 s13, s43, s47
	s_cselect_b32 s12, s42, s46
	v_lshl_add_u64 v[162:163], s[14:15], 0, v[142:143]
	s_add_i32 m0, s56, 0xc000
	ds_read_b128 v[182:185], v164
	ds_read_b128 v[186:189], v164 offset:1024
	ds_read_b128 v[190:193], v164 offset:2048
	ds_read_b128 v[194:197], v164 offset:3072
	ds_read_b128 v[198:201], v164 offset:4096
	ds_read_b128 v[202:205], v164 offset:5120
	ds_read_b128 v[206:209], v164 offset:6144
	ds_read_b128 v[210:213], v164 offset:7168
	global_load_lds_dwordx4 v[162:163], off
	v_lshl_add_u64 v[162:163], s[14:15], 0, v[140:141]
	s_add_i32 m0, s56, 0xe000
	s_nop 0
	global_load_lds_dwordx4 v[162:163], off
	s_waitcnt lgkmcnt(8)
	s_barrier
	s_waitcnt lgkmcnt(0)
	s_setprio 1
	s_waitcnt lgkmcnt(0)
	v_mfma_f32_16x16x32_bf16 v[124:127], v[166:169], v[182:185], v[124:127]
	v_mfma_f32_16x16x32_bf16 v[120:123], v[174:177], v[182:185], v[120:123]
	v_mfma_f32_16x16x32_bf16 v[108:111], v[166:169], v[190:193], v[108:111]
	v_mfma_f32_16x16x32_bf16 v[104:107], v[174:177], v[190:193], v[104:107]
	v_mfma_f32_16x16x32_bf16 v[92:95], v[166:169], v[198:201], v[92:95]
	v_mfma_f32_16x16x32_bf16 v[88:91], v[174:177], v[198:201], v[88:91]
	v_mfma_f32_16x16x32_bf16 v[76:79], v[166:169], v[206:209], v[76:79]
	v_mfma_f32_16x16x32_bf16 v[72:75], v[174:177], v[206:209], v[72:75]
	v_mfma_f32_16x16x32_bf16 v[124:127], v[170:173], v[186:189], v[124:127]
	v_mfma_f32_16x16x32_bf16 v[120:123], v[178:181], v[186:189], v[120:123]
	v_mfma_f32_16x16x32_bf16 v[108:111], v[170:173], v[194:197], v[108:111]
	v_mfma_f32_16x16x32_bf16 v[104:107], v[178:181], v[194:197], v[104:107]
	v_mfma_f32_16x16x32_bf16 v[92:95], v[170:173], v[202:205], v[92:95]
	v_mfma_f32_16x16x32_bf16 v[88:91], v[178:181], v[202:205], v[88:91]
	v_mfma_f32_16x16x32_bf16 v[76:79], v[170:173], v[210:213], v[76:79]
	v_mfma_f32_16x16x32_bf16 v[72:75], v[178:181], v[210:213], v[72:75]
	s_setprio 0
	s_barrier
	s_add_i32 s3, s0, s55
	v_lshl_add_u64 v[162:163], s[12:13], 0, v[130:131]
	s_mov_b32 m0, s3
	ds_read_b128 v[214:217], v165
	ds_read_b128 v[218:221], v165 offset:1024
	ds_read_b128 v[222:225], v165 offset:2048
	ds_read_b128 v[226:229], v165 offset:3072
	global_load_lds_dwordx4 v[162:163], off
	v_lshl_add_u64 v[230:231], s[12:13], 0, v[134:135]
	s_add_i32 m0, s3, 0x2000
	s_nop 0
	global_load_lds_dwordx4 v[230:231], off
	s_barrier
	s_waitcnt lgkmcnt(0)
	s_setprio 1
	v_mfma_f32_16x16x32_bf16 v[116:119], v[214:217], v[182:185], v[116:119]
	v_mfma_f32_16x16x32_bf16 v[112:115], v[222:225], v[182:185], v[112:115]
	v_mfma_f32_16x16x32_bf16 v[100:103], v[214:217], v[190:193], v[100:103]
	v_mfma_f32_16x16x32_bf16 v[96:99], v[222:225], v[190:193], v[96:99]
	v_mfma_f32_16x16x32_bf16 v[84:87], v[214:217], v[198:201], v[84:87]
	v_mfma_f32_16x16x32_bf16 v[80:83], v[222:225], v[198:201], v[80:83]
	v_mfma_f32_16x16x32_bf16 v[68:71], v[214:217], v[206:209], v[68:71]
	v_mfma_f32_16x16x32_bf16 v[64:67], v[222:225], v[206:209], v[64:67]
	v_mfma_f32_16x16x32_bf16 v[116:119], v[218:221], v[186:189], v[116:119]
	v_mfma_f32_16x16x32_bf16 v[112:115], v[226:229], v[186:189], v[112:115]
	v_mfma_f32_16x16x32_bf16 v[100:103], v[218:221], v[194:197], v[100:103]
	v_mfma_f32_16x16x32_bf16 v[96:99], v[226:229], v[194:197], v[96:99]
	v_mfma_f32_16x16x32_bf16 v[84:87], v[218:221], v[202:205], v[84:87]
	v_mfma_f32_16x16x32_bf16 v[80:83], v[226:229], v[202:205], v[80:83]
	v_mfma_f32_16x16x32_bf16 v[68:71], v[218:221], v[210:213], v[68:71]
	v_mfma_f32_16x16x32_bf16 v[64:67], v[226:229], v[210:213], v[64:67]
	s_setprio 0
	s_mov_b32 m0, s56
	v_lshl_add_u64 v[234:235], s[44:45], 0, v[128:129]
	s_barrier
	ds_read_b128 v[182:185], v164 offset:16384
	ds_read_b128 v[186:189], v164 offset:17408
	ds_read_b128 v[190:193], v164 offset:18432
	ds_read_b128 v[194:197], v164 offset:19456
	ds_read_b128 v[198:201], v164 offset:20480
	ds_read_b128 v[202:205], v164 offset:21504
	ds_read_b128 v[206:209], v164 offset:22528
	ds_read_b128 v[210:213], v164 offset:23552
	global_load_lds_dwordx4 v[234:235], off
	v_lshl_add_u64 v[236:237], s[44:45], 0, v[132:133]
	s_mov_b32 m0, s57
	s_nop 0
	global_load_lds_dwordx4 v[236:237], off
	s_barrier
	s_waitcnt lgkmcnt(0)
	s_setprio 1
	v_mfma_f32_16x16x32_bf16 v[60:63], v[166:169], v[182:185], v[60:63]
	v_mfma_f32_16x16x32_bf16 v[56:59], v[174:177], v[182:185], v[56:59]
	v_mfma_f32_16x16x32_bf16 v[44:47], v[166:169], v[190:193], v[44:47]
	v_mfma_f32_16x16x32_bf16 v[40:43], v[174:177], v[190:193], v[40:43]
	v_mfma_f32_16x16x32_bf16 v[28:31], v[166:169], v[198:201], v[28:31]
	v_mfma_f32_16x16x32_bf16 v[24:27], v[174:177], v[198:201], v[24:27]
	v_mfma_f32_16x16x32_bf16 v[12:15], v[166:169], v[206:209], v[12:15]
	v_mfma_f32_16x16x32_bf16 v[8:11], v[174:177], v[206:209], v[8:11]
	v_mfma_f32_16x16x32_bf16 v[60:63], v[170:173], v[186:189], v[60:63]
	v_mfma_f32_16x16x32_bf16 v[56:59], v[178:181], v[186:189], v[56:59]
	v_mfma_f32_16x16x32_bf16 v[44:47], v[170:173], v[194:197], v[44:47]
	v_mfma_f32_16x16x32_bf16 v[40:43], v[178:181], v[194:197], v[40:43]
	v_mfma_f32_16x16x32_bf16 v[28:31], v[170:173], v[202:205], v[28:31]
	v_mfma_f32_16x16x32_bf16 v[24:27], v[178:181], v[202:205], v[24:27]
	v_mfma_f32_16x16x32_bf16 v[12:15], v[170:173], v[210:213], v[12:15]
	v_mfma_f32_16x16x32_bf16 v[8:11], v[178:181], v[210:213], v[8:11]
	s_setprio 0
	s_barrier
; #define PG8_STAGE(bufoff, gbase, voff) do { _Pragma("unroll") for (int _i = 0; _i < 2; ++_i) \
;         __builtin_amdgcn_global_load_lds((const unsigned*)((const char*)(gbase) + (voff)[_i]), (LAS unsigned*)(lds + (bufoff) + ldsw + _i * 8192), 16, 0, 0); } while (0)
; #define PG8_LDA(dst, b, h) do { _Pragma("unroll") for (int m = 0; m < 4; ++m) _Pragma("unroll") for (int k = 0; k < 2; ++k) dst[m][k] = *(const LAS bf16x8*)(lds + PG8_SA(b, h) + aoff + m * 2048 + k * 1024); } while (0)
; #define PG8_LDB(dst, b, h) do { _Pragma("unroll") for (int n = 0; n < 2; ++n) _Pragma("unroll") for (int k = 0; k < 2; ++k) dst[n][k] = *(const LAS bf16x8*)(lds + PG8_SB(b, h) + boff + n * 2048 + k * 1024); } while (0)
; #define PG8_MMA(ai, bj, At, Bt) do { __builtin_amdgcn_s_setprio(1); _Pragma("unroll") for (int m = 0; m < 4; ++m) _Pragma("unroll") for (int n = 0; n < 2; ++n) _Pragma("unroll") for (int k = 0; k < 2; ++k) \
;         acc[ai][bj][m][n] = __builtin_amdgcn_mfma_f32_16x16x32_bf16(Bt[n][k], At[m][k], acc[ai][bj][m][n], 0, 0, 0); __builtin_amdgcn_s_setprio(0); } while (0)
; #define PG8_WAIT_V(n) asm volatile("s_waitcnt vmcnt(" #n ")" ::: "memory")
; #define PG8_WAIT_L(n) asm volatile("s_waitcnt lgkmcnt(" #n ")" ::: "memory")
; #define PG8_BAR __builtin_amdgcn_s_barrier()
; #define PG8_SCHED __builtin_amdgcn_sched_barrier(0)
; template <class Epi>
; __device__ __forceinline__ void gemm_phase(LAS unsigned char* lds, const GSched& S, const int K, const int lda, const int ldb, const Epi& E) {
;     ...
;             PG8_STAGE(PG8_SB(0, 1), b2 + hstepB, voffB);
;             PG8_WAIT_V(6); PG8_BAR; if constexpr (!Epi::NARROW) PG8_MMA(1, 1, At, B1); PG8_BAR;
;             PG8_LDB(B0, 1, 0); PG8_SCHED; PG8_LDA(At, 1, 0); PG8_STAGE(PG8_SA(0, 1), a2 + hstepA, voffA);
;             PG8_WAIT_L(8); PG8_BAR; PG8_WAIT_L(0); PG8_MMA(0, 0, At, B0); PG8_BAR; PG8_SCHED;
;             if constexpr (!Epi::NARROW) PG8_LDB(B1, 1, 1); PG8_STAGE(PG8_SB(1, 0), b3, voffB);
;             PG8_BAR; PG8_WAIT_L(0); if constexpr (!Epi::NARROW) PG8_MMA(0, 1, At, B1); PG8_BAR;
;             PG8_LDA(At, 1, 1); PG8_STAGE(PG8_SA(1, 0), a3, voffA);
;             PG8_BAR; PG8_WAIT_L(0); PG8_MMA(1, 0, At, B0); PG8_BAR; PG8_SCHED;
;             PG8_STAGE(PG8_SB(1, 1), b3 + hstepB, voffB);
	s_add_u32 s14, s12, 0x84000
	s_addc_u32 s15, s13, 0
	s_add_i32 s3, s1, s55
	v_lshl_add_u64 v[166:167], s[14:15], 0, v[130:131]
	s_mov_b32 m0, s3
	s_nop 0
	global_load_lds_dwordx4 v[166:167], off
	v_lshl_add_u64 v[166:167], s[14:15], 0, v[134:135]
	s_add_i32 m0, s3, 0x2000
	s_nop 0
	global_load_lds_dwordx4 v[166:167], off
	s_waitcnt vmcnt(6)
	s_barrier
	s_setprio 1
	v_mfma_f32_16x16x32_bf16 v[52:55], v[214:217], v[182:185], v[52:55]
	v_mfma_f32_16x16x32_bf16 v[48:51], v[222:225], v[182:185], v[48:51]
	v_mfma_f32_16x16x32_bf16 v[36:39], v[214:217], v[190:193], v[36:39]
	v_mfma_f32_16x16x32_bf16 v[32:35], v[222:225], v[190:193], v[32:35]
	v_mfma_f32_16x16x32_bf16 v[20:23], v[214:217], v[198:201], v[20:23]
	v_mfma_f32_16x16x32_bf16 v[16:19], v[222:225], v[198:201], v[16:19]
	v_mfma_f32_16x16x32_bf16 v[4:7], v[214:217], v[206:209], v[4:7]
	v_mfma_f32_16x16x32_bf16 v[0:3], v[222:225], v[206:209], v[0:3]
	v_mfma_f32_16x16x32_bf16 v[52:55], v[218:221], v[186:189], v[52:55]
	v_mfma_f32_16x16x32_bf16 v[48:51], v[226:229], v[186:189], v[48:51]
	v_mfma_f32_16x16x32_bf16 v[36:39], v[218:221], v[194:197], v[36:39]
	v_mfma_f32_16x16x32_bf16 v[32:35], v[226:229], v[194:197], v[32:35]
	v_mfma_f32_16x16x32_bf16 v[20:23], v[218:221], v[202:205], v[20:23]
	v_mfma_f32_16x16x32_bf16 v[16:19], v[226:229], v[202:205], v[16:19]
	v_mfma_f32_16x16x32_bf16 v[4:7], v[218:221], v[210:213], v[4:7]
	v_mfma_f32_16x16x32_bf16 v[0:3], v[226:229], v[210:213], v[0:3]
	s_setprio 0
	s_add_i32 s3, 0, 0x18000
	v_add_u32_e32 v178, s3, v159
	s_barrier
	ds_read_b128 v[166:169], v178
	ds_read_b128 v[170:173], v178 offset:1024
	ds_read_b128 v[174:177], v178 offset:2048
	ds_read_b128 v[178:181], v178 offset:3072
	s_add_u32 s14, s44, 0x94000
	s_addc_u32 s15, s45, 0
	s_mov_b32 m0, s58
	v_lshl_add_u64 v[214:215], s[14:15], 0, v[128:129]
	ds_read_b128 v[182:185], v164 offset:32768
	ds_read_b128 v[186:189], v164 offset:33792
	ds_read_b128 v[190:193], v164 offset:34816
	ds_read_b128 v[194:197], v164 offset:35840
	ds_read_b128 v[198:201], v164 offset:36864
	ds_read_b128 v[202:205], v164 offset:37888
	ds_read_b128 v[206:209], v164 offset:38912
	ds_read_b128 v[210:213], v164 offset:39936
	global_load_lds_dwordx4 v[214:215], off
	v_lshl_add_u64 v[214:215], s[14:15], 0, v[132:133]
	s_mov_b32 m0, s59
	s_nop 0
	global_load_lds_dwordx4 v[214:215], off
	s_waitcnt lgkmcnt(8)
	s_barrier
	s_waitcnt lgkmcnt(0)
	s_setprio 1
	s_waitcnt lgkmcnt(0)
	v_mfma_f32_16x16x32_bf16 v[124:127], v[166:169], v[182:185], v[124:127]
	v_mfma_f32_16x16x32_bf16 v[120:123], v[174:177], v[182:185], v[120:123]
	v_mfma_f32_16x16x32_bf16 v[108:111], v[166:169], v[190:193], v[108:111]
	v_mfma_f32_16x16x32_bf16 v[104:107], v[174:177], v[190:193], v[104:107]
	v_mfma_f32_16x16x32_bf16 v[92:95], v[166:169], v[198:201], v[92:95]
	v_mfma_f32_16x16x32_bf16 v[88:91], v[174:177], v[198:201], v[88:91]
	v_mfma_f32_16x16x32_bf16 v[76:79], v[166:169], v[206:209], v[76:79]
	v_mfma_f32_16x16x32_bf16 v[72:75], v[174:177], v[206:209], v[72:75]
	v_mfma_f32_16x16x32_bf16 v[124:127], v[170:173], v[186:189], v[124:127]
	v_mfma_f32_16x16x32_bf16 v[120:123], v[178:181], v[186:189], v[120:123]
	v_mfma_f32_16x16x32_bf16 v[108:111], v[170:173], v[194:197], v[108:111]
	v_mfma_f32_16x16x32_bf16 v[104:107], v[178:181], v[194:197], v[104:107]
	v_mfma_f32_16x16x32_bf16 v[92:95], v[170:173], v[202:205], v[92:95]
	v_mfma_f32_16x16x32_bf16 v[88:91], v[178:181], v[202:205], v[88:91]
	v_mfma_f32_16x16x32_bf16 v[76:79], v[170:173], v[210:213], v[76:79]
	v_mfma_f32_16x16x32_bf16 v[72:75], v[178:181], v[210:213], v[72:75]
	s_setprio 0
	s_barrier
	s_add_i32 s14, 0, 0x1c000
	s_add_i32 s3, s3, s55
	v_add_u32_e32 v226, s14, v159
	v_lshl_add_u64 v[162:163], v[162:163], 0, s[38:39]
	s_mov_b32 m0, s3
	ds_read_b128 v[214:217], v226
	ds_read_b128 v[218:221], v226 offset:1024
	ds_read_b128 v[222:225], v226 offset:2048
	ds_read_b128 v[226:229], v226 offset:3072
	global_load_lds_dwordx4 v[162:163], off
	v_lshl_add_u64 v[162:163], v[230:231], 0, s[38:39]
	s_add_i32 m0, s3, 0x2000
	s_nop 0
	global_load_lds_dwordx4 v[162:163], off
	s_barrier
	s_waitcnt lgkmcnt(0)
	s_setprio 1
	s_waitcnt lgkmcnt(0)
	v_mfma_f32_16x16x32_bf16 v[116:119], v[214:217], v[182:185], v[116:119]
	v_mfma_f32_16x16x32_bf16 v[112:115], v[222:225], v[182:185], v[112:115]
	v_mfma_f32_16x16x32_bf16 v[100:103], v[214:217], v[190:193], v[100:103]
	v_mfma_f32_16x16x32_bf16 v[96:99], v[222:225], v[190:193], v[96:99]
	v_mfma_f32_16x16x32_bf16 v[84:87], v[214:217], v[198:201], v[84:87]
	v_mfma_f32_16x16x32_bf16 v[80:83], v[222:225], v[198:201], v[80:83]
	v_mfma_f32_16x16x32_bf16 v[68:71], v[214:217], v[206:209], v[68:71]
	v_mfma_f32_16x16x32_bf16 v[64:67], v[222:225], v[206:209], v[64:67]
	v_mfma_f32_16x16x32_bf16 v[116:119], v[218:221], v[186:189], v[116:119]
	v_mfma_f32_16x16x32_bf16 v[112:115], v[226:229], v[186:189], v[112:115]
	v_mfma_f32_16x16x32_bf16 v[100:103], v[218:221], v[194:197], v[100:103]
	v_mfma_f32_16x16x32_bf16 v[96:99], v[226:229], v[194:197], v[96:99]
	v_mfma_f32_16x16x32_bf16 v[84:87], v[218:221], v[202:205], v[84:87]
	v_mfma_f32_16x16x32_bf16 v[80:83], v[226:229], v[202:205], v[80:83]
	v_mfma_f32_16x16x32_bf16 v[68:71], v[218:221], v[210:213], v[68:71]
	v_mfma_f32_16x16x32_bf16 v[64:67], v[226:229], v[210:213], v[64:67]
	s_setprio 0
	s_mov_b32 m0, s64
	v_lshl_add_u64 v[162:163], v[234:235], 0, s[38:39]
	s_barrier
	ds_read_b128 v[182:185], v164 offset:49152
	ds_read_b128 v[186:189], v164 offset:50176
	ds_read_b128 v[190:193], v164 offset:51200
	ds_read_b128 v[194:197], v164 offset:52224
	ds_read_b128 v[198:201], v164 offset:53248
	ds_read_b128 v[202:205], v164 offset:54272
	ds_read_b128 v[206:209], v164 offset:55296
	ds_read_b128 v[210:213], v164 offset:56320
	global_load_lds_dwordx4 v[162:163], off
	v_lshl_add_u64 v[162:163], v[236:237], 0, s[38:39]
	s_mov_b32 m0, s65
	s_nop 0
	global_load_lds_dwordx4 v[162:163], off
	s_barrier
; __device__ __forceinline__ void st_nt(float* p, f32x4 v) { __builtin_nontemporal_store(v, (f32x4*)p); }
; __device__ __forceinline__ void st_nt(bf16_t* p, u32x4 v) { __builtin_nontemporal_store(v, (u32x4*)p); }
; __device__ __forceinline__ float sumsq4(const f32x4 v) { return (v[0] * v[0] + v[1] * v[1]) + (v[2] * v[2] + v[3] * v[3]); }
; __device__ __forceinline__ u32x4 pack8(const f32x4 a, const f32x4 b) { u32x4 w; w.x = cvt_pk_bf16(a[0], a[1]); w.y = cvt_pk_bf16(a[2], a[3]); w.z = cvt_pk_bf16(b[0], b[1]); w.w = cvt_pk_bf16(b[2], b[3]); return w; }
; #define PG8_LDA(dst, b, h) do { _Pragma("unroll") for (int m = 0; m < 4; ++m) _Pragma("unroll") for (int k = 0; k < 2; ++k) dst[m][k] = *(const LAS bf16x8*)(lds + PG8_SA(b, h) + aoff + m * 2048 + k * 1024); } while (0)
;     __device__ __forceinline__ void operator()(Acc& acc, const Unit& u, int wr, int wc, int fr, int fq, const float (&rsv)[8]) const {
;         const int row0 = u.pm * BM + wr * 64 + fr, cin = wc * 32 + 8 * fq;
;         const bool is_lat = u.pn >= 12;
; #pragma unroll
;         for (int ai = 0; ai < 2; ++ai)
; #pragma unroll
;             for (int m = 0; m < 4; ++m) {
;                 const int row = row0 + ai * HALF + m * 16; const float rs = rsv[ai * 4 + m]; float ss = 0.f;
; #pragma unroll
;                 for (int bj = 0; bj < 2; ++bj) { const f32x4 v0 = acc[ai][bj][m][0] * rs, v1 = acc[ai][bj][m][1] * rs; ss += sumsq4(v0) + sumsq4(v1);
;                     bf16_t* dst = is_lat ? lat + (size_t)row * 1024 + (u.pn - 12) * BM + cin + bj * HALF : qkv + (size_t)row * 3072 + u.pn * BM + cin + bj * HALF;
;                     st_nt(dst, pack8(v0, v1)); }
;                 if (is_lat) { ss += __shfl_xor(ss, 16); ss += __shfl_xor(ss, 32); if (fq == 0) latpart[(size_t)row * 16 + (u.pn - 12) * 4 + wc] = ss; }
;             }
; template <class Epi>
; __device__ __forceinline__ void gemm_phase(LAS unsigned char* lds, const GSched& S, const int K, const int lda, const int ldb, const Epi& E) {
;     ...
;             PG8_BAR; PG8_WAIT_L(0); if constexpr (!Epi::NARROW) PG8_MMA(0, 1, At, B1); PG8_BAR;
;             PG8_LDA(At, 1, 1); PG8_STAGE(PG8_SA(1, 0), a3, voffA);
;             PG8_BAR; PG8_WAIT_L(0); PG8_MMA(1, 0, At, B0); PG8_BAR; PG8_SCHED;
;             PG8_STAGE(PG8_SB(1, 1), b3 + hstepB, voffB);
;             PG8_WAIT_V(6); PG8_BAR; if constexpr (!Epi::NARROW) PG8_MMA(1, 1, At, B1); PG8_BAR;
	s_waitcnt lgkmcnt(0)
	s_setprio 1
	v_mfma_f32_16x16x32_bf16 v[60:63], v[166:169], v[182:185], v[60:63]
	v_mfma_f32_16x16x32_bf16 v[56:59], v[174:177], v[182:185], v[56:59]
	v_mfma_f32_16x16x32_bf16 v[44:47], v[166:169], v[190:193], v[44:47]
	v_mfma_f32_16x16x32_bf16 v[40:43], v[174:177], v[190:193], v[40:43]
	v_mfma_f32_16x16x32_bf16 v[28:31], v[166:169], v[198:201], v[28:31]
	v_mfma_f32_16x16x32_bf16 v[24:27], v[174:177], v[198:201], v[24:27]
	v_mfma_f32_16x16x32_bf16 v[12:15], v[166:169], v[206:209], v[12:15]
	v_mfma_f32_16x16x32_bf16 v[8:11], v[174:177], v[206:209], v[8:11]
	v_mfma_f32_16x16x32_bf16 v[60:63], v[170:173], v[186:189], v[60:63]
	v_mfma_f32_16x16x32_bf16 v[56:59], v[178:181], v[186:189], v[56:59]
	v_mfma_f32_16x16x32_bf16 v[44:47], v[170:173], v[194:197], v[44:47]
	v_mfma_f32_16x16x32_bf16 v[40:43], v[178:181], v[194:197], v[40:43]
	v_mfma_f32_16x16x32_bf16 v[28:31], v[170:173], v[202:205], v[28:31]
	v_mfma_f32_16x16x32_bf16 v[24:27], v[178:181], v[202:205], v[24:27]
	v_mfma_f32_16x16x32_bf16 v[12:15], v[170:173], v[210:213], v[12:15]
	v_mfma_f32_16x16x32_bf16 v[8:11], v[178:181], v[210:213], v[8:11]
	s_setprio 0
	s_barrier
	s_add_u32 s12, s12, 0x84080
	s_addc_u32 s13, s13, 0
	s_add_i32 s3, s14, s55
	v_lshl_add_u64 v[162:163], s[12:13], 0, v[130:131]
	s_mov_b32 m0, s3
	s_nop 0
	global_load_lds_dwordx4 v[162:163], off
	v_lshl_add_u64 v[162:163], s[12:13], 0, v[134:135]
	s_add_i32 m0, s3, 0x2000
	s_nop 0
	global_load_lds_dwordx4 v[162:163], off
	s_waitcnt vmcnt(6)
	s_barrier
	s_setprio 1
	v_mfma_f32_16x16x32_bf16 v[52:55], v[214:217], v[182:185], v[52:55]
	v_mfma_f32_16x16x32_bf16 v[48:51], v[222:225], v[182:185], v[48:51]
	v_mfma_f32_16x16x32_bf16 v[36:39], v[214:217], v[190:193], v[36:39]
	v_mfma_f32_16x16x32_bf16 v[32:35], v[222:225], v[190:193], v[32:35]
	v_mfma_f32_16x16x32_bf16 v[20:23], v[214:217], v[198:201], v[20:23]
	v_mfma_f32_16x16x32_bf16 v[16:19], v[222:225], v[198:201], v[16:19]
	v_mfma_f32_16x16x32_bf16 v[4:7], v[214:217], v[206:209], v[4:7]
	v_mfma_f32_16x16x32_bf16 v[0:3], v[222:225], v[206:209], v[0:3]
	v_mfma_f32_16x16x32_bf16 v[52:55], v[218:221], v[186:189], v[52:55]
	v_mfma_f32_16x16x32_bf16 v[48:51], v[226:229], v[186:189], v[48:51]
	v_mfma_f32_16x16x32_bf16 v[36:39], v[218:221], v[194:197], v[36:39]
	v_mfma_f32_16x16x32_bf16 v[32:35], v[226:229], v[194:197], v[32:35]
	v_mfma_f32_16x16x32_bf16 v[20:23], v[218:221], v[202:205], v[20:23]
	v_mfma_f32_16x16x32_bf16 v[16:19], v[226:229], v[202:205], v[16:19]
	v_mfma_f32_16x16x32_bf16 v[4:7], v[218:221], v[210:213], v[4:7]
	v_mfma_f32_16x16x32_bf16 v[0:3], v[226:229], v[210:213], v[0:3]
	s_setprio 0
	s_add_i32 s48, s48, 2
	s_add_u32 s46, s46, 0x100
	s_addc_u32 s47, s47, 0
	s_cmp_gt_u32 s48, 29
	s_mov_b64 s[14:15], s[6:7]
	s_barrier
	s_cbranch_scc0 .LBB0_438
	v_lshl_add_u32 v162, s62, 8, v157
	s_cmp_gt_i32 s18, 11
	s_cselect_b64 s[12:13], -1, 0
	s_lshl_b32 s44, s18, 8
	v_ashrrev_i32_e32 v163, 31, v162
	s_add_i32 s46, s44, 0xfffff400
	v_lshlrev_b64 v[166:167], 11, v[162:163]
	v_mov_b64_e32 v[168:169], s[30:31]
	s_ashr_i32 s45, s44, 31
	s_ashr_i32 s47, s46, 31
	v_lshl_add_u64 v[166:167], s[34:35], 0, v[166:167]
	v_mad_i64_i32 v[168:169], s[14:15], v162, s67, v[168:169]
	s_lshl_b32 s3, s18, 2
	v_lshl_add_u64 v[166:167], s[46:47], 1, v[166:167]
	v_lshl_add_u64 v[168:169], s[44:45], 1, v[168:169]
	s_sub_i32 s6, s3, 48
	v_pk_mul_f32 v[126:127], v[148:149], v[126:127] op_sel_hi:[0,1]
	v_pk_mul_f32 v[124:125], v[148:149], v[124:125] op_sel_hi:[0,1]
	v_pk_mul_f32 v[122:123], v[148:149], v[122:123] op_sel_hi:[0,1]
	v_pk_mul_f32 v[120:121], v[148:149], v[120:121] op_sel_hi:[0,1]
	v_cndmask_b32_e64 v167, v169, v167, s[12:13]
	v_cndmask_b32_e64 v166, v168, v166, s[12:13]
	s_ashr_i32 s7, s6, 31
	v_lshl_add_u64 v[170:171], v[166:167], 0, v[136:137]
	v_cvt_pk_bf16_f32 v166, v124, v125
	v_cvt_pk_bf16_f32 v167, v126, v127
	v_cvt_pk_bf16_f32 v168, v120, v121
	v_cvt_pk_bf16_f32 v169, v122, v123
	v_pk_mul_f32 v[118:119], v[148:149], v[118:119] op_sel_hi:[0,1]
	v_pk_mul_f32 v[116:117], v[148:149], v[116:117] op_sel_hi:[0,1]
	v_pk_mul_f32 v[114:115], v[148:149], v[114:115] op_sel_hi:[0,1]
	v_pk_mul_f32 v[112:113], v[148:149], v[112:113] op_sel_hi:[0,1]
	s_cmp_lt_i32 s18, 12
	global_store_dwordx4 v[170:171], v[166:169], off
	s_nop 1
	v_cvt_pk_bf16_f32 v166, v116, v117
	v_cvt_pk_bf16_f32 v167, v118, v119
	v_cvt_pk_bf16_f32 v168, v112, v113
	v_cvt_pk_bf16_f32 v169, v114, v115
	global_store_dwordx4 v[170:171], v[166:169], off offset:256
	s_cbranch_scc1 .LBB0_443
	v_mul_f32_e32 v125, v125, v125
	v_mul_f32_e32 v121, v121, v121
	v_mul_f32_e32 v117, v117, v117
	v_mul_f32_e32 v113, v113, v113
	v_fmac_f32_e32 v125, v124, v124
	v_mul_f32_e32 v124, v127, v127
	v_fmac_f32_e32 v121, v120, v120
	v_mul_f32_e32 v120, v123, v123
	v_fmac_f32_e32 v117, v116, v116
	v_mul_f32_e32 v116, v119, v119
	v_fmac_f32_e32 v113, v112, v112
	v_mul_f32_e32 v112, v115, v115
	v_fmac_f32_e32 v124, v126, v126
	v_fmac_f32_e32 v120, v122, v122
	v_fmac_f32_e32 v116, v118, v118
	v_fmac_f32_e32 v112, v114, v114
	v_add_f32_e32 v124, v125, v124
	v_add_f32_e32 v120, v121, v120
	v_add_f32_e32 v116, v117, v116
	v_add_f32_e32 v112, v113, v112
	v_add_f32_e32 v120, v124, v120
	v_add_f32_e32 v112, v116, v112
	v_add_f32_e32 v112, v120, v112
	ds_bpermute_b32 v113, v153, v112
	s_waitcnt lgkmcnt(0)
	v_add_f32_e32 v112, v112, v113
	ds_bpermute_b32 v113, v155, v112
	s_and_saveexec_b64 s[14:15], s[8:9]
	s_cbranch_execz .LBB0_442
	v_lshlrev_b64 v[114:115], 6, v[162:163]
	v_lshl_add_u64 v[114:115], s[36:37], 0, v[114:115]
	v_lshl_add_u64 v[114:115], s[6:7], 2, v[114:115]
	s_lshl_b32 s18, s63, 2
	v_lshl_add_u64 v[114:115], v[114:115], 0, s[18:19]
	s_waitcnt lgkmcnt(0)
	v_add_f32_e32 v112, v112, v113
	global_store_dword v[114:115], v112, off

; __device__ __forceinline__ void st_nt(float* p, f32x4 v) { __builtin_nontemporal_store(v, (f32x4*)p); }
; __device__ __forceinline__ void st_nt(bf16_t* p, u32x4 v) { __builtin_nontemporal_store(v, (u32x4*)p); }
; __device__ __forceinline__ float sumsq4(const f32x4 v) { return (v[0] * v[0] + v[1] * v[1]) + (v[2] * v[2] + v[3] * v[3]); }
; __device__ __forceinline__ u32x4 pack8(const f32x4 a, const f32x4 b) { u32x4 w; w.x = cvt_pk_bf16(a[0], a[1]); w.y = cvt_pk_bf16(a[2], a[3]); w.z = cvt_pk_bf16(b[0], b[1]); w.w = cvt_pk_bf16(b[2], b[3]); return w; }
;     __device__ __forceinline__ void operator()(Acc& acc, const Unit& u, int wr, int wc, int fr, int fq, const float (&rsv)[8]) const {
;         const int row0 = u.pm * BM + wr * 64 + fr, cin = wc * 32 + 8 * fq;
;         const bool is_lat = u.pn >= 12;
; #pragma unroll
;         for (int ai = 0; ai < 2; ++ai)
; #pragma unroll
;             for (int m = 0; m < 4; ++m) {
;                 const int row = row0 + ai * HALF + m * 16; const float rs = rsv[ai * 4 + m]; float ss = 0.f;
; #pragma unroll
;                 for (int bj = 0; bj < 2; ++bj) { const f32x4 v0 = acc[ai][bj][m][0] * rs, v1 = acc[ai][bj][m][1] * rs; ss += sumsq4(v0) + sumsq4(v1);
;                     bf16_t* dst = is_lat ? lat + (size_t)row * 1024 + (u.pn - 12) * BM + cin + bj * HALF : qkv + (size_t)row * 3072 + u.pn * BM + cin + bj * HALF;
;                     st_nt(dst, pack8(v0, v1)); }
;                 if (is_lat) { ss += __shfl_xor(ss, 16); ss += __shfl_xor(ss, 32); if (fq == 0) latpart[(size_t)row * 16 + (u.pn - 12) * 4 + wc] = ss; }
;             }
.LBB0_443:
	v_or_b32_e32 v112, 16, v162
	s_waitcnt lgkmcnt(0)
	v_ashrrev_i32_e32 v113, 31, v112
	v_lshlrev_b64 v[114:115], 11, v[112:113]
	v_mov_b64_e32 v[116:117], s[30:31]
	v_lshl_add_u64 v[114:115], s[34:35], 0, v[114:115]
	v_mad_i64_i32 v[116:117], s[14:15], v112, s67, v[116:117]
	v_lshl_add_u64 v[114:115], s[46:47], 1, v[114:115]
	v_lshl_add_u64 v[116:117], s[44:45], 1, v[116:117]
	v_pk_mul_f32 v[108:109], v[148:149], v[108:109] op_sel:[1,0]
	v_pk_mul_f32 v[110:111], v[148:149], v[110:111] op_sel:[1,0]
	v_pk_mul_f32 v[104:105], v[148:149], v[104:105] op_sel:[1,0]
	v_pk_mul_f32 v[106:107], v[148:149], v[106:107] op_sel:[1,0]
	v_cndmask_b32_e64 v115, v117, v115, s[12:13]
	v_cndmask_b32_e64 v114, v116, v114, s[12:13]
	v_lshl_add_u64 v[118:119], v[114:115], 0, v[136:137]
	v_cvt_pk_bf16_f32 v114, v108, v109
	v_cvt_pk_bf16_f32 v115, v110, v111
	v_cvt_pk_bf16_f32 v116, v104, v105
	v_cvt_pk_bf16_f32 v117, v106, v107
	v_pk_mul_f32 v[100:101], v[148:149], v[100:101] op_sel:[1,0]
	v_pk_mul_f32 v[102:103], v[148:149], v[102:103] op_sel:[1,0]
	v_pk_mul_f32 v[96:97], v[148:149], v[96:97] op_sel:[1,0]
	v_pk_mul_f32 v[98:99], v[148:149], v[98:99] op_sel:[1,0]
	v_cndmask_b32_e64 v120, 0, 1, s[12:13]
	global_store_dwordx4 v[118:119], v[114:117], off
	v_cmp_ne_u32_e64 s[14:15], 1, v120
	s_andn2_b64 vcc, exec, s[12:13]
	v_cvt_pk_bf16_f32 v114, v100, v101
	v_cvt_pk_bf16_f32 v115, v102, v103
	v_cvt_pk_bf16_f32 v116, v96, v97
	v_cvt_pk_bf16_f32 v117, v98, v99
	global_store_dwordx4 v[118:119], v[114:117], off offset:256
	s_cbranch_vccnz .LBB0_447
	v_mul_f32_e32 v109, v109, v109
	v_mul_f32_e32 v105, v105, v105
	v_mul_f32_e32 v101, v101, v101
	v_mul_f32_e32 v97, v97, v97
	v_fmac_f32_e32 v109, v108, v108
	v_mul_f32_e32 v108, v111, v111
	v_fmac_f32_e32 v105, v104, v104
	v_mul_f32_e32 v104, v107, v107
	v_fmac_f32_e32 v101, v100, v100
	v_mul_f32_e32 v100, v103, v103
	v_fmac_f32_e32 v97, v96, v96
	v_mul_f32_e32 v96, v99, v99
	v_fmac_f32_e32 v108, v110, v110
	v_fmac_f32_e32 v104, v106, v106
	v_fmac_f32_e32 v100, v102, v102
	v_fmac_f32_e32 v96, v98, v98
	v_add_f32_e32 v108, v109, v108
	v_add_f32_e32 v104, v105, v104
	v_add_f32_e32 v100, v101, v100
	v_add_f32_e32 v96, v97, v96
	v_add_f32_e32 v104, v108, v104
	v_add_f32_e32 v96, v100, v96
	v_add_f32_e32 v96, v104, v96
	ds_bpermute_b32 v97, v153, v96
	s_waitcnt lgkmcnt(0)
	v_add_f32_e32 v96, v96, v97
	ds_bpermute_b32 v97, v155, v96
	s_and_saveexec_b64 s[48:49], s[8:9]
	s_cbranch_execz .LBB0_446
	v_lshlrev_b64 v[98:99], 6, v[112:113]
	v_lshl_add_u64 v[98:99], s[36:37], 0, v[98:99]
	v_lshl_add_u64 v[98:99], s[6:7], 2, v[98:99]
	s_lshl_b32 s18, s63, 2
	v_lshl_add_u64 v[98:99], v[98:99], 0, s[18:19]
	s_waitcnt lgkmcnt(0)
	v_add_f32_e32 v96, v96, v97
	global_store_dword v[98:99], v96, off

; __device__ __forceinline__ void st_nt(float* p, f32x4 v) { __builtin_nontemporal_store(v, (f32x4*)p); }
; __device__ __forceinline__ void st_nt(bf16_t* p, u32x4 v) { __builtin_nontemporal_store(v, (u32x4*)p); }
; __device__ __forceinline__ float sumsq4(const f32x4 v) { return (v[0] * v[0] + v[1] * v[1]) + (v[2] * v[2] + v[3] * v[3]); }
; __device__ __forceinline__ u32x4 pack8(const f32x4 a, const f32x4 b) { u32x4 w; w.x = cvt_pk_bf16(a[0], a[1]); w.y = cvt_pk_bf16(a[2], a[3]); w.z = cvt_pk_bf16(b[0], b[1]); w.w = cvt_pk_bf16(b[2], b[3]); return w; }
;     __device__ __forceinline__ void operator()(Acc& acc, const Unit& u, int wr, int wc, int fr, int fq, const float (&rsv)[8]) const {
;         const int row0 = u.pm * BM + wr * 64 + fr, cin = wc * 32 + 8 * fq;
;         const bool is_lat = u.pn >= 12;
; #pragma unroll
;         for (int ai = 0; ai < 2; ++ai)
; #pragma unroll
;             for (int m = 0; m < 4; ++m) {
;                 const int row = row0 + ai * HALF + m * 16; const float rs = rsv[ai * 4 + m]; float ss = 0.f;
; #pragma unroll
;                 for (int bj = 0; bj < 2; ++bj) { const f32x4 v0 = acc[ai][bj][m][0] * rs, v1 = acc[ai][bj][m][1] * rs; ss += sumsq4(v0) + sumsq4(v1);
;                     bf16_t* dst = is_lat ? lat + (size_t)row * 1024 + (u.pn - 12) * BM + cin + bj * HALF : qkv + (size_t)row * 3072 + u.pn * BM + cin + bj * HALF;
;                     st_nt(dst, pack8(v0, v1)); }
;                 if (is_lat) { ss += __shfl_xor(ss, 16); ss += __shfl_xor(ss, 32); if (fq == 0) latpart[(size_t)row * 16 + (u.pn - 12) * 4 + wc] = ss; }
;             }
.LBB0_447:
	v_or_b32_e32 v96, 32, v162
	s_waitcnt lgkmcnt(0)
	v_ashrrev_i32_e32 v97, 31, v96
	v_lshlrev_b64 v[98:99], 11, v[96:97]
	v_mov_b64_e32 v[100:101], s[30:31]
	v_lshl_add_u64 v[98:99], s[34:35], 0, v[98:99]
	v_mad_i64_i32 v[100:101], s[48:49], v96, s67, v[100:101]
	v_lshl_add_u64 v[98:99], s[46:47], 1, v[98:99]
	v_lshl_add_u64 v[100:101], s[44:45], 1, v[100:101]
	v_pk_mul_f32 v[94:95], v[150:151], v[94:95] op_sel_hi:[0,1]
	v_pk_mul_f32 v[92:93], v[150:151], v[92:93] op_sel_hi:[0,1]
	v_pk_mul_f32 v[90:91], v[150:151], v[90:91] op_sel_hi:[0,1]
	v_pk_mul_f32 v[88:89], v[150:151], v[88:89] op_sel_hi:[0,1]
	v_cndmask_b32_e64 v99, v101, v99, s[12:13]
	v_cndmask_b32_e64 v98, v100, v98, s[12:13]
	v_lshl_add_u64 v[102:103], v[98:99], 0, v[136:137]
	v_cvt_pk_bf16_f32 v98, v92, v93
	v_cvt_pk_bf16_f32 v99, v94, v95
	v_cvt_pk_bf16_f32 v100, v88, v89
	v_cvt_pk_bf16_f32 v101, v90, v91
	v_pk_mul_f32 v[86:87], v[150:151], v[86:87] op_sel_hi:[0,1]
	v_pk_mul_f32 v[84:85], v[150:151], v[84:85] op_sel_hi:[0,1]
	v_pk_mul_f32 v[82:83], v[150:151], v[82:83] op_sel_hi:[0,1]
	v_pk_mul_f32 v[80:81], v[150:151], v[80:81] op_sel_hi:[0,1]
	global_store_dwordx4 v[102:103], v[98:101], off
	s_and_b64 vcc, exec, s[14:15]
	s_nop 0
	v_cvt_pk_bf16_f32 v98, v84, v85
	v_cvt_pk_bf16_f32 v99, v86, v87
	v_cvt_pk_bf16_f32 v100, v80, v81
	v_cvt_pk_bf16_f32 v101, v82, v83
	global_store_dwordx4 v[102:103], v[98:101], off offset:256
	s_cbranch_vccnz .LBB0_451
	v_mul_f32_e32 v93, v93, v93
	v_mul_f32_e32 v89, v89, v89
	v_mul_f32_e32 v85, v85, v85
	v_mul_f32_e32 v81, v81, v81
	v_fmac_f32_e32 v93, v92, v92
	v_mul_f32_e32 v92, v95, v95
	v_fmac_f32_e32 v89, v88, v88
	v_mul_f32_e32 v88, v91, v91
	v_fmac_f32_e32 v85, v84, v84
	v_mul_f32_e32 v84, v87, v87
	v_fmac_f32_e32 v81, v80, v80
	v_mul_f32_e32 v80, v83, v83
	v_fmac_f32_e32 v92, v94, v94
	v_fmac_f32_e32 v88, v90, v90
	v_fmac_f32_e32 v84, v86, v86
	v_fmac_f32_e32 v80, v82, v82
	v_add_f32_e32 v92, v93, v92
	v_add_f32_e32 v88, v89, v88
	v_add_f32_e32 v84, v85, v84
	v_add_f32_e32 v80, v81, v80
	v_add_f32_e32 v88, v92, v88
	v_add_f32_e32 v80, v84, v80
	v_add_f32_e32 v80, v88, v80
	ds_bpermute_b32 v81, v153, v80
	s_waitcnt lgkmcnt(0)
	v_add_f32_e32 v80, v80, v81
	ds_bpermute_b32 v81, v155, v80
	s_and_saveexec_b64 s[48:49], s[8:9]
	s_cbranch_execz .LBB0_450
	v_lshlrev_b64 v[82:83], 6, v[96:97]
	v_lshl_add_u64 v[82:83], s[36:37], 0, v[82:83]
	v_lshl_add_u64 v[82:83], s[6:7], 2, v[82:83]
	s_lshl_b32 s18, s63, 2
	v_lshl_add_u64 v[82:83], v[82:83], 0, s[18:19]
	s_waitcnt lgkmcnt(0)
	v_add_f32_e32 v80, v80, v81
	global_store_dword v[82:83], v80, off

; __device__ __forceinline__ void st_nt(float* p, f32x4 v) { __builtin_nontemporal_store(v, (f32x4*)p); }
; __device__ __forceinline__ void st_nt(bf16_t* p, u32x4 v) { __builtin_nontemporal_store(v, (u32x4*)p); }
; __device__ __forceinline__ float sumsq4(const f32x4 v) { return (v[0] * v[0] + v[1] * v[1]) + (v[2] * v[2] + v[3] * v[3]); }
; __device__ __forceinline__ u32x4 pack8(const f32x4 a, const f32x4 b) { u32x4 w; w.x = cvt_pk_bf16(a[0], a[1]); w.y = cvt_pk_bf16(a[2], a[3]); w.z = cvt_pk_bf16(b[0], b[1]); w.w = cvt_pk_bf16(b[2], b[3]); return w; }
;     __device__ __forceinline__ void operator()(Acc& acc, const Unit& u, int wr, int wc, int fr, int fq, const float (&rsv)[8]) const {
;         const int row0 = u.pm * BM + wr * 64 + fr, cin = wc * 32 + 8 * fq;
;         const bool is_lat = u.pn >= 12;
; #pragma unroll
;         for (int ai = 0; ai < 2; ++ai)
; #pragma unroll
;             for (int m = 0; m < 4; ++m) {
;                 const int row = row0 + ai * HALF + m * 16; const float rs = rsv[ai * 4 + m]; float ss = 0.f;
; #pragma unroll
;                 for (int bj = 0; bj < 2; ++bj) { const f32x4 v0 = acc[ai][bj][m][0] * rs, v1 = acc[ai][bj][m][1] * rs; ss += sumsq4(v0) + sumsq4(v1);
;                     bf16_t* dst = is_lat ? lat + (size_t)row * 1024 + (u.pn - 12) * BM + cin + bj * HALF : qkv + (size_t)row * 3072 + u.pn * BM + cin + bj * HALF;
;                     st_nt(dst, pack8(v0, v1)); }
;                 if (is_lat) { ss += __shfl_xor(ss, 16); ss += __shfl_xor(ss, 32); if (fq == 0) latpart[(size_t)row * 16 + (u.pn - 12) * 4 + wc] = ss; }
;             }
.LBB0_451:
	v_or_b32_e32 v80, 48, v162
	s_waitcnt lgkmcnt(0)
	v_ashrrev_i32_e32 v81, 31, v80
	v_lshlrev_b64 v[82:83], 11, v[80:81]
	v_mov_b64_e32 v[84:85], s[30:31]
	v_lshl_add_u64 v[82:83], s[34:35], 0, v[82:83]
	v_mad_i64_i32 v[84:85], s[48:49], v80, s67, v[84:85]
	v_lshl_add_u64 v[82:83], s[46:47], 1, v[82:83]
	v_lshl_add_u64 v[84:85], s[44:45], 1, v[84:85]
	v_pk_mul_f32 v[78:79], v[152:153], v[78:79] op_sel_hi:[0,1]
	v_pk_mul_f32 v[76:77], v[152:153], v[76:77] op_sel_hi:[0,1]
	v_pk_mul_f32 v[74:75], v[152:153], v[74:75] op_sel_hi:[0,1]
	v_pk_mul_f32 v[72:73], v[152:153], v[72:73] op_sel_hi:[0,1]
	v_cndmask_b32_e64 v83, v85, v83, s[12:13]
	v_cndmask_b32_e64 v82, v84, v82, s[12:13]
	v_lshl_add_u64 v[86:87], v[82:83], 0, v[136:137]
	v_cvt_pk_bf16_f32 v82, v76, v77
	v_cvt_pk_bf16_f32 v83, v78, v79
	v_cvt_pk_bf16_f32 v84, v72, v73
	v_cvt_pk_bf16_f32 v85, v74, v75
	v_pk_mul_f32 v[70:71], v[152:153], v[70:71] op_sel_hi:[0,1]
	v_pk_mul_f32 v[68:69], v[152:153], v[68:69] op_sel_hi:[0,1]
	v_pk_mul_f32 v[66:67], v[152:153], v[66:67] op_sel_hi:[0,1]
	v_pk_mul_f32 v[64:65], v[152:153], v[64:65] op_sel_hi:[0,1]
	global_store_dwordx4 v[86:87], v[82:85], off
	s_and_b64 vcc, exec, s[14:15]
	s_nop 0
	v_cvt_pk_bf16_f32 v82, v68, v69
	v_cvt_pk_bf16_f32 v83, v70, v71
	v_cvt_pk_bf16_f32 v84, v64, v65
	v_cvt_pk_bf16_f32 v85, v66, v67
	global_store_dwordx4 v[86:87], v[82:85], off offset:256
	s_cbranch_vccnz .LBB0_455
	v_mul_f32_e32 v77, v77, v77
	v_mul_f32_e32 v73, v73, v73
	v_mul_f32_e32 v69, v69, v69
	v_mul_f32_e32 v65, v65, v65
	v_fmac_f32_e32 v77, v76, v76
	v_mul_f32_e32 v76, v79, v79
	v_fmac_f32_e32 v73, v72, v72
	v_mul_f32_e32 v72, v75, v75
	v_fmac_f32_e32 v69, v68, v68
	v_mul_f32_e32 v68, v71, v71
	v_fmac_f32_e32 v65, v64, v64
	v_mul_f32_e32 v64, v67, v67
	v_fmac_f32_e32 v76, v78, v78
	v_fmac_f32_e32 v72, v74, v74
	v_fmac_f32_e32 v68, v70, v70
	v_fmac_f32_e32 v64, v66, v66
	v_add_f32_e32 v76, v77, v76
	v_add_f32_e32 v72, v73, v72
	v_add_f32_e32 v68, v69, v68
	v_add_f32_e32 v64, v65, v64
	v_add_f32_e32 v72, v76, v72
	v_add_f32_e32 v64, v68, v64
	v_add_f32_e32 v64, v72, v64
	ds_bpermute_b32 v65, v153, v64
	s_waitcnt lgkmcnt(0)
	v_add_f32_e32 v64, v64, v65
	ds_bpermute_b32 v65, v155, v64
	s_and_saveexec_b64 s[48:49], s[8:9]
	s_cbranch_execz .LBB0_454
	v_lshlrev_b64 v[66:67], 6, v[80:81]
	v_lshl_add_u64 v[66:67], s[36:37], 0, v[66:67]
	v_lshl_add_u64 v[66:67], s[6:7], 2, v[66:67]
	s_lshl_b32 s18, s63, 2
	v_lshl_add_u64 v[66:67], v[66:67], 0, s[18:19]
	s_waitcnt lgkmcnt(0)
	v_add_f32_e32 v64, v64, v65
	global_store_dword v[66:67], v64, off

; __device__ __forceinline__ void st_nt(float* p, f32x4 v) { __builtin_nontemporal_store(v, (f32x4*)p); }
; __device__ __forceinline__ void st_nt(bf16_t* p, u32x4 v) { __builtin_nontemporal_store(v, (u32x4*)p); }
; __device__ __forceinline__ float sumsq4(const f32x4 v) { return (v[0] * v[0] + v[1] * v[1]) + (v[2] * v[2] + v[3] * v[3]); }
; __device__ __forceinline__ u32x4 pack8(const f32x4 a, const f32x4 b) { u32x4 w; w.x = cvt_pk_bf16(a[0], a[1]); w.y = cvt_pk_bf16(a[2], a[3]); w.z = cvt_pk_bf16(b[0], b[1]); w.w = cvt_pk_bf16(b[2], b[3]); return w; }
;     __device__ __forceinline__ void operator()(Acc& acc, const Unit& u, int wr, int wc, int fr, int fq, const float (&rsv)[8]) const {
;         const int row0 = u.pm * BM + wr * 64 + fr, cin = wc * 32 + 8 * fq;
;         const bool is_lat = u.pn >= 12;
; #pragma unroll
;         for (int ai = 0; ai < 2; ++ai)
; #pragma unroll
;             for (int m = 0; m < 4; ++m) {
;                 const int row = row0 + ai * HALF + m * 16; const float rs = rsv[ai * 4 + m]; float ss = 0.f;
; #pragma unroll
;                 for (int bj = 0; bj < 2; ++bj) { const f32x4 v0 = acc[ai][bj][m][0] * rs, v1 = acc[ai][bj][m][1] * rs; ss += sumsq4(v0) + sumsq4(v1);
;                     bf16_t* dst = is_lat ? lat + (size_t)row * 1024 + (u.pn - 12) * BM + cin + bj * HALF : qkv + (size_t)row * 3072 + u.pn * BM + cin + bj * HALF;
;                     st_nt(dst, pack8(v0, v1)); }
;                 if (is_lat) { ss += __shfl_xor(ss, 16); ss += __shfl_xor(ss, 32); if (fq == 0) latpart[(size_t)row * 16 + (u.pn - 12) * 4 + wc] = ss; }
;             }
.LBB0_455:
	v_add_u32_e32 v64, 0x80, v162
	s_waitcnt lgkmcnt(0)
	v_ashrrev_i32_e32 v65, 31, v64
	v_lshlrev_b64 v[66:67], 11, v[64:65]
	v_mov_b64_e32 v[68:69], s[30:31]
	v_lshl_add_u64 v[66:67], s[34:35], 0, v[66:67]
	v_mad_i64_i32 v[68:69], s[48:49], v64, s67, v[68:69]
	v_lshl_add_u64 v[66:67], s[46:47], 1, v[66:67]
	v_lshl_add_u64 v[68:69], s[44:45], 1, v[68:69]
	v_pk_mul_f32 v[62:63], v[154:155], v[62:63] op_sel_hi:[0,1]
	v_pk_mul_f32 v[60:61], v[154:155], v[60:61] op_sel_hi:[0,1]
	v_pk_mul_f32 v[58:59], v[154:155], v[58:59] op_sel_hi:[0,1]
	v_pk_mul_f32 v[56:57], v[154:155], v[56:57] op_sel_hi:[0,1]
	v_cndmask_b32_e64 v67, v69, v67, s[12:13]
	v_cndmask_b32_e64 v66, v68, v66, s[12:13]
	v_lshl_add_u64 v[70:71], v[66:67], 0, v[136:137]
	v_cvt_pk_bf16_f32 v66, v60, v61
	v_cvt_pk_bf16_f32 v67, v62, v63
	v_cvt_pk_bf16_f32 v68, v56, v57
	v_cvt_pk_bf16_f32 v69, v58, v59
	v_pk_mul_f32 v[54:55], v[154:155], v[54:55] op_sel_hi:[0,1]
	v_pk_mul_f32 v[52:53], v[154:155], v[52:53] op_sel_hi:[0,1]
	v_pk_mul_f32 v[50:51], v[154:155], v[50:51] op_sel_hi:[0,1]
	v_pk_mul_f32 v[48:49], v[154:155], v[48:49] op_sel_hi:[0,1]
	global_store_dwordx4 v[70:71], v[66:69], off
	s_and_b64 vcc, exec, s[14:15]
	s_nop 0
	v_cvt_pk_bf16_f32 v66, v52, v53
	v_cvt_pk_bf16_f32 v67, v54, v55
	v_cvt_pk_bf16_f32 v68, v48, v49
	v_cvt_pk_bf16_f32 v69, v50, v51
	global_store_dwordx4 v[70:71], v[66:69], off offset:256
	s_cbranch_vccnz .LBB0_459
	v_mul_f32_e32 v61, v61, v61
	v_mul_f32_e32 v57, v57, v57
	v_mul_f32_e32 v53, v53, v53
	v_mul_f32_e32 v49, v49, v49
	v_fmac_f32_e32 v61, v60, v60
	v_mul_f32_e32 v60, v63, v63
	v_fmac_f32_e32 v57, v56, v56
	v_mul_f32_e32 v56, v59, v59
	v_fmac_f32_e32 v53, v52, v52
	v_mul_f32_e32 v52, v55, v55
	v_fmac_f32_e32 v49, v48, v48
	v_mul_f32_e32 v48, v51, v51
	v_fmac_f32_e32 v60, v62, v62
	v_fmac_f32_e32 v56, v58, v58
	v_fmac_f32_e32 v52, v54, v54
	v_fmac_f32_e32 v48, v50, v50
	v_add_f32_e32 v60, v61, v60
	v_add_f32_e32 v56, v57, v56
	v_add_f32_e32 v52, v53, v52
	v_add_f32_e32 v48, v49, v48
	v_add_f32_e32 v56, v60, v56
	v_add_f32_e32 v48, v52, v48
	v_add_f32_e32 v48, v56, v48
	ds_bpermute_b32 v49, v153, v48
	s_waitcnt lgkmcnt(0)
	v_add_f32_e32 v48, v48, v49
	ds_bpermute_b32 v49, v155, v48
	s_and_saveexec_b64 s[48:49], s[8:9]
	s_cbranch_execz .LBB0_458
	v_lshlrev_b64 v[50:51], 6, v[64:65]
	v_lshl_add_u64 v[50:51], s[36:37], 0, v[50:51]
	v_lshl_add_u64 v[50:51], s[6:7], 2, v[50:51]
	s_lshl_b32 s18, s63, 2
	v_lshl_add_u64 v[50:51], v[50:51], 0, s[18:19]
	s_waitcnt lgkmcnt(0)
	v_add_f32_e32 v48, v48, v49
	global_store_dword v[50:51], v48, off

; __device__ __forceinline__ void st_nt(float* p, f32x4 v) { __builtin_nontemporal_store(v, (f32x4*)p); }
; __device__ __forceinline__ void st_nt(bf16_t* p, u32x4 v) { __builtin_nontemporal_store(v, (u32x4*)p); }
; __device__ __forceinline__ float sumsq4(const f32x4 v) { return (v[0] * v[0] + v[1] * v[1]) + (v[2] * v[2] + v[3] * v[3]); }
; __device__ __forceinline__ u32x4 pack8(const f32x4 a, const f32x4 b) { u32x4 w; w.x = cvt_pk_bf16(a[0], a[1]); w.y = cvt_pk_bf16(a[2], a[3]); w.z = cvt_pk_bf16(b[0], b[1]); w.w = cvt_pk_bf16(b[2], b[3]); return w; }
;     __device__ __forceinline__ void operator()(Acc& acc, const Unit& u, int wr, int wc, int fr, int fq, const float (&rsv)[8]) const {
;         const int row0 = u.pm * BM + wr * 64 + fr, cin = wc * 32 + 8 * fq;
;         const bool is_lat = u.pn >= 12;
; #pragma unroll
;         for (int ai = 0; ai < 2; ++ai)
; #pragma unroll
;             for (int m = 0; m < 4; ++m) {
;                 const int row = row0 + ai * HALF + m * 16; const float rs = rsv[ai * 4 + m]; float ss = 0.f;
; #pragma unroll
;                 for (int bj = 0; bj < 2; ++bj) { const f32x4 v0 = acc[ai][bj][m][0] * rs, v1 = acc[ai][bj][m][1] * rs; ss += sumsq4(v0) + sumsq4(v1);
;                     bf16_t* dst = is_lat ? lat + (size_t)row * 1024 + (u.pn - 12) * BM + cin + bj * HALF : qkv + (size_t)row * 3072 + u.pn * BM + cin + bj * HALF;
;                     st_nt(dst, pack8(v0, v1)); }
;                 if (is_lat) { ss += __shfl_xor(ss, 16); ss += __shfl_xor(ss, 32); if (fq == 0) latpart[(size_t)row * 16 + (u.pn - 12) * 4 + wc] = ss; }
;             }
.LBB0_459:
	v_add_u32_e32 v48, 0x90, v162
	s_waitcnt lgkmcnt(0)
	v_ashrrev_i32_e32 v49, 31, v48
	v_lshlrev_b64 v[50:51], 11, v[48:49]
	v_mov_b64_e32 v[52:53], s[30:31]
	v_lshl_add_u64 v[50:51], s[34:35], 0, v[50:51]
	v_mad_i64_i32 v[52:53], s[48:49], v48, s67, v[52:53]
	v_lshl_add_u64 v[50:51], s[46:47], 1, v[50:51]
	v_lshl_add_u64 v[52:53], s[44:45], 1, v[52:53]
	v_pk_mul_f32 v[46:47], v[156:157], v[46:47] op_sel_hi:[0,1]
	v_pk_mul_f32 v[44:45], v[156:157], v[44:45] op_sel_hi:[0,1]
	v_pk_mul_f32 v[42:43], v[156:157], v[42:43] op_sel_hi:[0,1]
	v_pk_mul_f32 v[40:41], v[156:157], v[40:41] op_sel_hi:[0,1]
	v_cndmask_b32_e64 v51, v53, v51, s[12:13]
	v_cndmask_b32_e64 v50, v52, v50, s[12:13]
	v_lshl_add_u64 v[54:55], v[50:51], 0, v[136:137]
	v_cvt_pk_bf16_f32 v50, v44, v45
	v_cvt_pk_bf16_f32 v51, v46, v47
	v_cvt_pk_bf16_f32 v52, v40, v41
	v_cvt_pk_bf16_f32 v53, v42, v43
	v_pk_mul_f32 v[38:39], v[156:157], v[38:39] op_sel_hi:[0,1]
	v_pk_mul_f32 v[36:37], v[156:157], v[36:37] op_sel_hi:[0,1]
	v_pk_mul_f32 v[34:35], v[156:157], v[34:35] op_sel_hi:[0,1]
	v_pk_mul_f32 v[32:33], v[156:157], v[32:33] op_sel_hi:[0,1]
	global_store_dwordx4 v[54:55], v[50:53], off
	s_and_b64 vcc, exec, s[14:15]
	s_nop 0
	v_cvt_pk_bf16_f32 v50, v36, v37
	v_cvt_pk_bf16_f32 v51, v38, v39
	v_cvt_pk_bf16_f32 v52, v32, v33
	v_cvt_pk_bf16_f32 v53, v34, v35
	global_store_dwordx4 v[54:55], v[50:53], off offset:256
	s_cbranch_vccnz .LBB0_463
	v_mul_f32_e32 v45, v45, v45
	v_mul_f32_e32 v41, v41, v41
	v_mul_f32_e32 v37, v37, v37
	v_mul_f32_e32 v33, v33, v33
	v_fmac_f32_e32 v45, v44, v44
	v_mul_f32_e32 v44, v47, v47
	v_fmac_f32_e32 v41, v40, v40
	v_mul_f32_e32 v40, v43, v43
	v_fmac_f32_e32 v37, v36, v36
	v_mul_f32_e32 v36, v39, v39
	v_fmac_f32_e32 v33, v32, v32
	v_mul_f32_e32 v32, v35, v35
	v_fmac_f32_e32 v44, v46, v46
	v_fmac_f32_e32 v40, v42, v42
	v_fmac_f32_e32 v36, v38, v38
	v_fmac_f32_e32 v32, v34, v34
	v_add_f32_e32 v44, v45, v44
	v_add_f32_e32 v40, v41, v40
	v_add_f32_e32 v36, v37, v36
	v_add_f32_e32 v32, v33, v32
	v_add_f32_e32 v40, v44, v40
	v_add_f32_e32 v32, v36, v32
	v_add_f32_e32 v32, v40, v32
	ds_bpermute_b32 v33, v153, v32
	s_waitcnt lgkmcnt(0)
	v_add_f32_e32 v32, v32, v33
	ds_bpermute_b32 v33, v155, v32
	s_and_saveexec_b64 s[48:49], s[8:9]
	s_cbranch_execz .LBB0_462
	v_lshlrev_b64 v[34:35], 6, v[48:49]
	v_lshl_add_u64 v[34:35], s[36:37], 0, v[34:35]
	v_lshl_add_u64 v[34:35], s[6:7], 2, v[34:35]
	s_lshl_b32 s18, s63, 2
	v_lshl_add_u64 v[34:35], v[34:35], 0, s[18:19]
	s_waitcnt lgkmcnt(0)
	v_add_f32_e32 v32, v32, v33
	global_store_dword v[34:35], v32, off

; __device__ __forceinline__ void st_nt(float* p, f32x4 v) { __builtin_nontemporal_store(v, (f32x4*)p); }
; __device__ __forceinline__ void st_nt(bf16_t* p, u32x4 v) { __builtin_nontemporal_store(v, (u32x4*)p); }
; __device__ __forceinline__ float sumsq4(const f32x4 v) { return (v[0] * v[0] + v[1] * v[1]) + (v[2] * v[2] + v[3] * v[3]); }
; __device__ __forceinline__ u32x4 pack8(const f32x4 a, const f32x4 b) { u32x4 w; w.x = cvt_pk_bf16(a[0], a[1]); w.y = cvt_pk_bf16(a[2], a[3]); w.z = cvt_pk_bf16(b[0], b[1]); w.w = cvt_pk_bf16(b[2], b[3]); return w; }
;     __device__ __forceinline__ void operator()(Acc& acc, const Unit& u, int wr, int wc, int fr, int fq, const float (&rsv)[8]) const {
;         const int row0 = u.pm * BM + wr * 64 + fr, cin = wc * 32 + 8 * fq;
;         const bool is_lat = u.pn >= 12;
; #pragma unroll
;         for (int ai = 0; ai < 2; ++ai)
; #pragma unroll
;             for (int m = 0; m < 4; ++m) {
;                 const int row = row0 + ai * HALF + m * 16; const float rs = rsv[ai * 4 + m]; float ss = 0.f;
; #pragma unroll
;                 for (int bj = 0; bj < 2; ++bj) { const f32x4 v0 = acc[ai][bj][m][0] * rs, v1 = acc[ai][bj][m][1] * rs; ss += sumsq4(v0) + sumsq4(v1);
;                     bf16_t* dst = is_lat ? lat + (size_t)row * 1024 + (u.pn - 12) * BM + cin + bj * HALF : qkv + (size_t)row * 3072 + u.pn * BM + cin + bj * HALF;
;                     st_nt(dst, pack8(v0, v1)); }
;                 if (is_lat) { ss += __shfl_xor(ss, 16); ss += __shfl_xor(ss, 32); if (fq == 0) latpart[(size_t)row * 16 + (u.pn - 12) * 4 + wc] = ss; }
;             }
.LBB0_463:
	v_add_u32_e32 v32, 0xa0, v162
	s_waitcnt lgkmcnt(0)
	v_ashrrev_i32_e32 v33, 31, v32
	v_lshlrev_b64 v[34:35], 11, v[32:33]
	v_mov_b64_e32 v[36:37], s[30:31]
	v_lshl_add_u64 v[34:35], s[34:35], 0, v[34:35]
	v_mad_i64_i32 v[36:37], s[48:49], v32, s67, v[36:37]
	v_lshl_add_u64 v[34:35], s[46:47], 1, v[34:35]
	v_lshl_add_u64 v[36:37], s[44:45], 1, v[36:37]
	v_pk_mul_f32 v[30:31], v[158:159], v[30:31] op_sel_hi:[0,1]
	v_pk_mul_f32 v[28:29], v[158:159], v[28:29] op_sel_hi:[0,1]
	v_pk_mul_f32 v[26:27], v[158:159], v[26:27] op_sel_hi:[0,1]
	v_pk_mul_f32 v[24:25], v[158:159], v[24:25] op_sel_hi:[0,1]
	v_cndmask_b32_e64 v35, v37, v35, s[12:13]
	v_cndmask_b32_e64 v34, v36, v34, s[12:13]
	v_lshl_add_u64 v[38:39], v[34:35], 0, v[136:137]
	v_cvt_pk_bf16_f32 v34, v28, v29
	v_cvt_pk_bf16_f32 v35, v30, v31
	v_cvt_pk_bf16_f32 v36, v24, v25
	v_cvt_pk_bf16_f32 v37, v26, v27
	v_pk_mul_f32 v[22:23], v[158:159], v[22:23] op_sel_hi:[0,1]
	v_pk_mul_f32 v[20:21], v[158:159], v[20:21] op_sel_hi:[0,1]
	v_pk_mul_f32 v[18:19], v[158:159], v[18:19] op_sel_hi:[0,1]
	v_pk_mul_f32 v[16:17], v[158:159], v[16:17] op_sel_hi:[0,1]
	global_store_dwordx4 v[38:39], v[34:37], off
	s_and_b64 vcc, exec, s[14:15]
	s_nop 0
	v_cvt_pk_bf16_f32 v34, v20, v21
	v_cvt_pk_bf16_f32 v35, v22, v23
	v_cvt_pk_bf16_f32 v36, v16, v17
	v_cvt_pk_bf16_f32 v37, v18, v19
	global_store_dwordx4 v[38:39], v[34:37], off offset:256
	s_cbranch_vccnz .LBB0_467
	v_mul_f32_e32 v29, v29, v29
	v_mul_f32_e32 v25, v25, v25
	v_mul_f32_e32 v21, v21, v21
	v_mul_f32_e32 v17, v17, v17
	v_fmac_f32_e32 v29, v28, v28
	v_mul_f32_e32 v28, v31, v31
	v_fmac_f32_e32 v25, v24, v24
	v_mul_f32_e32 v24, v27, v27
	v_fmac_f32_e32 v21, v20, v20
	v_mul_f32_e32 v20, v23, v23
	v_fmac_f32_e32 v17, v16, v16
	v_mul_f32_e32 v16, v19, v19
	v_fmac_f32_e32 v28, v30, v30
	v_fmac_f32_e32 v24, v26, v26
	v_fmac_f32_e32 v20, v22, v22
	v_fmac_f32_e32 v16, v18, v18
	v_add_f32_e32 v28, v29, v28
	v_add_f32_e32 v24, v25, v24
	v_add_f32_e32 v20, v21, v20
	v_add_f32_e32 v16, v17, v16
	v_add_f32_e32 v24, v28, v24
	v_add_f32_e32 v16, v20, v16
	v_add_f32_e32 v16, v24, v16
	ds_bpermute_b32 v17, v153, v16
	s_waitcnt lgkmcnt(0)
	v_add_f32_e32 v16, v16, v17
	ds_bpermute_b32 v17, v155, v16
	s_and_saveexec_b64 s[48:49], s[8:9]
	s_cbranch_execz .LBB0_466
	v_lshlrev_b64 v[18:19], 6, v[32:33]
	v_lshl_add_u64 v[18:19], s[36:37], 0, v[18:19]
	v_lshl_add_u64 v[18:19], s[6:7], 2, v[18:19]
	s_lshl_b32 s18, s63, 2
	v_lshl_add_u64 v[18:19], v[18:19], 0, s[18:19]
	s_waitcnt lgkmcnt(0)
	v_add_f32_e32 v16, v16, v17
	global_store_dword v[18:19], v16, off

; __device__ __forceinline__ void st_nt(float* p, f32x4 v) { __builtin_nontemporal_store(v, (f32x4*)p); }
; __device__ __forceinline__ void st_nt(bf16_t* p, u32x4 v) { __builtin_nontemporal_store(v, (u32x4*)p); }
; __device__ __forceinline__ float sumsq4(const f32x4 v) { return (v[0] * v[0] + v[1] * v[1]) + (v[2] * v[2] + v[3] * v[3]); }
; __device__ __forceinline__ u32x4 pack8(const f32x4 a, const f32x4 b) { u32x4 w; w.x = cvt_pk_bf16(a[0], a[1]); w.y = cvt_pk_bf16(a[2], a[3]); w.z = cvt_pk_bf16(b[0], b[1]); w.w = cvt_pk_bf16(b[2], b[3]); return w; }
;     __device__ __forceinline__ void operator()(Acc& acc, const Unit& u, int wr, int wc, int fr, int fq, const float (&rsv)[8]) const {
;         const int row0 = u.pm * BM + wr * 64 + fr, cin = wc * 32 + 8 * fq;
;         const bool is_lat = u.pn >= 12;
; #pragma unroll
;         for (int ai = 0; ai < 2; ++ai)
; #pragma unroll
;             for (int m = 0; m < 4; ++m) {
;                 const int row = row0 + ai * HALF + m * 16; const float rs = rsv[ai * 4 + m]; float ss = 0.f;
; #pragma unroll
;                 for (int bj = 0; bj < 2; ++bj) { const f32x4 v0 = acc[ai][bj][m][0] * rs, v1 = acc[ai][bj][m][1] * rs; ss += sumsq4(v0) + sumsq4(v1);
;                     bf16_t* dst = is_lat ? lat + (size_t)row * 1024 + (u.pn - 12) * BM + cin + bj * HALF : qkv + (size_t)row * 3072 + u.pn * BM + cin + bj * HALF;
;                     st_nt(dst, pack8(v0, v1)); }
;                 if (is_lat) { ss += __shfl_xor(ss, 16); ss += __shfl_xor(ss, 32); if (fq == 0) latpart[(size_t)row * 16 + (u.pn - 12) * 4 + wc] = ss; }
;             }
.LBB0_467:
	v_add_u32_e32 v16, 0xb0, v162
	s_waitcnt lgkmcnt(0)
	v_ashrrev_i32_e32 v17, 31, v16
	v_lshlrev_b64 v[18:19], 11, v[16:17]
	v_lshl_add_u64 v[18:19], s[34:35], 0, v[18:19]
	v_mov_b64_e32 v[20:21], s[30:31]
	v_lshl_add_u64 v[18:19], s[46:47], 1, v[18:19]
	v_mad_i64_i32 v[20:21], s[46:47], v16, s67, v[20:21]
	v_lshl_add_u64 v[20:21], s[44:45], 1, v[20:21]
	v_pk_mul_f32 v[14:15], v[160:161], v[14:15] op_sel_hi:[0,1]
	v_pk_mul_f32 v[12:13], v[160:161], v[12:13] op_sel_hi:[0,1]
	v_pk_mul_f32 v[10:11], v[160:161], v[10:11] op_sel_hi:[0,1]
	v_pk_mul_f32 v[8:9], v[160:161], v[8:9] op_sel_hi:[0,1]
	v_cndmask_b32_e64 v19, v21, v19, s[12:13]
	v_cndmask_b32_e64 v18, v20, v18, s[12:13]
	v_lshl_add_u64 v[22:23], v[18:19], 0, v[136:137]
	v_cvt_pk_bf16_f32 v18, v12, v13
	v_cvt_pk_bf16_f32 v19, v14, v15
	v_cvt_pk_bf16_f32 v20, v8, v9
	v_cvt_pk_bf16_f32 v21, v10, v11
	v_pk_mul_f32 v[6:7], v[160:161], v[6:7] op_sel_hi:[0,1]
	v_pk_mul_f32 v[4:5], v[160:161], v[4:5] op_sel_hi:[0,1]
	v_pk_mul_f32 v[2:3], v[160:161], v[2:3] op_sel_hi:[0,1]
	v_pk_mul_f32 v[0:1], v[160:161], v[0:1] op_sel_hi:[0,1]
	global_store_dwordx4 v[22:23], v[18:21], off
	s_and_b64 vcc, exec, s[14:15]
	s_nop 0
	v_cvt_pk_bf16_f32 v18, v4, v5
	v_cvt_pk_bf16_f32 v19, v6, v7
	v_cvt_pk_bf16_f32 v20, v0, v1
	v_cvt_pk_bf16_f32 v21, v2, v3
	global_store_dwordx4 v[22:23], v[18:21], off offset:256
	s_cbranch_vccnz .LBB0_471
	v_mul_f32_e32 v13, v13, v13
	v_mul_f32_e32 v9, v9, v9
	v_mul_f32_e32 v5, v5, v5
	v_mul_f32_e32 v1, v1, v1
	v_fmac_f32_e32 v13, v12, v12
	v_mul_f32_e32 v12, v15, v15
	v_fmac_f32_e32 v9, v8, v8
	v_mul_f32_e32 v8, v11, v11
	v_fmac_f32_e32 v5, v4, v4
	v_mul_f32_e32 v4, v7, v7
	v_fmac_f32_e32 v1, v0, v0
	v_mul_f32_e32 v0, v3, v3
	v_fmac_f32_e32 v12, v14, v14
	v_fmac_f32_e32 v8, v10, v10
	v_fmac_f32_e32 v4, v6, v6
	v_fmac_f32_e32 v0, v2, v2
	v_add_f32_e32 v12, v13, v12
	v_add_f32_e32 v8, v9, v8
	v_add_f32_e32 v4, v5, v4
	v_add_f32_e32 v0, v1, v0
	v_add_f32_e32 v8, v12, v8
	v_add_f32_e32 v0, v4, v0
	v_add_f32_e32 v0, v8, v0
	ds_bpermute_b32 v1, v153, v0
	s_waitcnt lgkmcnt(0)
	v_add_f32_e32 v0, v0, v1
	ds_bpermute_b32 v1, v155, v0
	s_and_saveexec_b64 s[12:13], s[8:9]
	s_cbranch_execz .LBB0_470
	v_lshlrev_b64 v[2:3], 6, v[16:17]
	v_lshl_add_u64 v[2:3], s[36:37], 0, v[2:3]
	v_lshl_add_u64 v[2:3], s[6:7], 2, v[2:3]
	s_lshl_b32 s18, s63, 2
	v_lshl_add_u64 v[2:3], v[2:3], 0, s[18:19]
	s_waitcnt lgkmcnt(0)
	v_add_f32_e32 v0, v0, v1
	global_store_dword v[2:3], v0, off

; __device__ __forceinline__ void st_nt(float* p, f32x4 v) { __builtin_nontemporal_store(v, (f32x4*)p); }
; __device__ __forceinline__ void st_nt(bf16_t* p, u32x4 v) { __builtin_nontemporal_store(v, (u32x4*)p); }
; __device__ __forceinline__ u32x4 pack8(const f32x4 a, const f32x4 b) { u32x4 w; w.x = cvt_pk_bf16(a[0], a[1]); w.y = cvt_pk_bf16(a[2], a[3]); w.z = cvt_pk_bf16(b[0], b[1]); w.w = cvt_pk_bf16(b[2], b[3]); return w; }
;     __device__ __forceinline__ void operator()(Acc& acc, const Unit& u, int wr, int wc, int fr, int fq, const float (&rsv)[8]) const {
;         const int row0 = u.pm * BM + wr * 64 + fr, col0 = u.pn * BM + wc * 32 + 8 * fq;
;         const int off0 = col0 % 192, off1 = (col0 + HALF) % 192;
;         const int ropebj = (u.z == 0) ? (off0 >= 128 ? 0 : (off1 >= 128 ? 1 : -1)) : -1;
;         const int kk = ((ropebj == 0 ? off0 : off1) - 128) >> 3;
;         f32x4 cs[8], sn[8];
;         if (ropebj >= 0) {
; #pragma unroll
;             for (int g = 0; g < 8; ++g) { const int pos = (row0 + (g >> 2) * HALF + (g & 3) * 16) & (SEQ - 1); cs[g] = *(const f32x4*)(rc + pos * 32 + 4 * kk); sn[g] = *(const f32x4*)(rsn + pos * 32 + 4 * kk); }
;         } else {
; #pragma unroll
;             for (int g = 0; g < 8; ++g) { cs[g] = (f32x4){1.f, 1.f, 1.f, 1.f}; sn[g] = (f32x4){0.f, 0.f, 0.f, 0.f}; }
;         }
; #pragma unroll
;         for (int ai = 0; ai < 2; ++ai)
; #pragma unroll
;             for (int m = 0; m < 4; ++m) {
;                 const int row = row0 + ai * HALF + m * 16;
;                 const float rs = rsv[ai * 4 + m];
; #pragma unroll
;                 for (int bj = 0; bj < 2; ++bj) { const int col = col0 + bj * HALF; f32x4 v0 = acc[ai][bj][m][0] * rs, v1 = acc[ai][bj][m][1] * rs;
;                     if (bj == ropebj) { const f32x4 c = cs[ai * 4 + m], s = sn[ai * 4 + m]; const f32x4 o1 = v0 * c - v1 * s, o2 = v1 * c + v0 * s; v0 = o1; v1 = o2; }
;                     if (u.z == 0) st_nt(q + (size_t)row * 1536 + col, pack8(v0, v1));
;                     else st_nt(kv + (size_t)row * 2048 + col, pack8(v0, v1)); }
;             }
.LBB0_546:
	s_or_b64 exec, exec, s[6:7]
	v_pk_mul_f32 v[120:121], v[210:211], v[120:121] op_sel_hi:[0,1]
	v_pk_mul_f32 v[124:125], v[210:211], v[124:125] op_sel_hi:[0,1]
	v_pk_mul_f32 v[122:123], v[210:211], v[122:123] op_sel_hi:[0,1]
	s_waitcnt vmcnt(0)
	v_pk_mul_f32 v[236:237], v[120:121], v[184:185]
	v_pk_mul_f32 v[240:241], v[120:121], v[188:189]
	v_ashrrev_i32_e32 v227, 31, v226
	v_pk_mul_f32 v[126:127], v[210:211], v[126:127] op_sel_hi:[0,1]
	v_pk_fma_f32 v[236:237], v[124:125], v[188:189], v[236:237] neg_lo:[0,0,1] neg_hi:[0,0,1]
	v_pk_mul_f32 v[242:243], v[122:123], v[190:191]
	v_pk_fma_f32 v[240:241], v[124:125], v[184:185], v[240:241]
	v_lshlrev_b64 v[234:235], 12, v[226:227]
	v_pk_mul_f32 v[238:239], v[122:123], v[186:187]
	v_pk_fma_f32 v[242:243], v[126:127], v[186:187], v[242:243]
	v_cndmask_b32_e64 v200, v125, v237, s[8:9]
	v_cndmask_b32_e64 v227, v124, v236, s[8:9]
	v_cndmask_b32_e64 v236, v121, v241, s[8:9]
	v_cndmask_b32_e64 v237, v120, v240, s[8:9]
	v_mov_b64_e32 v[120:121], s[30:31]
	v_pk_fma_f32 v[238:239], v[126:127], v[190:191], v[238:239] neg_lo:[0,0,1] neg_hi:[0,0,1]
	v_cndmask_b32_e64 v232, v123, v243, s[8:9]
	v_cndmask_b32_e64 v233, v122, v242, s[8:9]
	v_lshl_add_u64 v[122:123], s[34:35], 0, v[234:235]
	v_mad_i64_i32 v[124:125], s[0:1], v226, s75, v[120:121]
	v_ashrrev_i32_e32 v229, 31, v228
	v_cndmask_b32_e64 v127, v127, v239, s[8:9]
	v_cndmask_b32_e64 v126, v126, v238, s[8:9]
	v_cndmask_b32_e32 v125, v123, v125, vcc
	v_cndmask_b32_e32 v124, v122, v124, vcc
	v_lshlrev_b64 v[122:123], 1, v[228:229]
	v_lshl_add_u64 v[228:229], v[124:125], 0, v[122:123]
	v_cvt_pk_bf16_f32 v124, v227, v200
	v_cvt_pk_bf16_f32 v125, v126, v127
	v_cvt_pk_bf16_f32 v126, v237, v236
	v_cvt_pk_bf16_f32 v127, v233, v232
	v_pk_mul_f32 v[114:115], v[210:211], v[114:115] op_sel_hi:[0,1]
	v_pk_mul_f32 v[112:113], v[210:211], v[112:113] op_sel_hi:[0,1]
	global_store_dwordx4 v[228:229], v[124:127], off
	v_pk_mul_f32 v[118:119], v[210:211], v[118:119] op_sel_hi:[0,1]
	v_pk_mul_f32 v[116:117], v[210:211], v[116:117] op_sel_hi:[0,1]
	v_pk_mul_f32 v[124:125], v[112:113], v[184:185]
	v_pk_mul_f32 v[126:127], v[114:115], v[186:187]
	v_pk_fma_f32 v[124:125], v[116:117], v[188:189], v[124:125] neg_lo:[0,0,1] neg_hi:[0,0,1]
	v_pk_fma_f32 v[126:127], v[118:119], v[190:191], v[126:127] neg_lo:[0,0,1] neg_hi:[0,0,1]
	v_pk_mul_f32 v[188:189], v[112:113], v[188:189]
	v_pk_mul_f32 v[190:191], v[114:115], v[190:191]
	v_pk_fma_f32 v[184:185], v[116:117], v[184:185], v[188:189]
	v_pk_fma_f32 v[186:187], v[118:119], v[186:187], v[190:191]
	v_cmp_eq_u32_e64 s[10:11], 1, v231
	v_pk_mul_f32 v[106:107], v[212:213], v[106:107] op_sel_hi:[0,1]
	v_pk_mul_f32 v[104:105], v[212:213], v[104:105] op_sel_hi:[0,1]
	v_cndmask_b32_e64 v119, v119, v127, s[10:11]
	v_cndmask_b32_e64 v118, v118, v126, s[10:11]
	v_cndmask_b32_e64 v117, v117, v125, s[10:11]
	v_cndmask_b32_e64 v116, v116, v124, s[10:11]
	v_cndmask_b32_e64 v115, v115, v187, s[10:11]
	v_cndmask_b32_e64 v124, v114, v186, s[10:11]
	v_cndmask_b32_e64 v114, v113, v185, s[10:11]
	v_cndmask_b32_e64 v125, v112, v184, s[10:11]
	v_cvt_pk_bf16_f32 v112, v116, v117
	v_cvt_pk_bf16_f32 v113, v118, v119
	v_cvt_pk_bf16_f32 v114, v125, v114
	v_cvt_pk_bf16_f32 v115, v124, v115
	global_store_dwordx4 v[228:229], v[112:115], off offset:256
	v_pk_mul_f32 v[110:111], v[212:213], v[110:111] op_sel_hi:[0,1]
	v_pk_mul_f32 v[108:109], v[212:213], v[108:109] op_sel_hi:[0,1]
	v_or_b32_e32 v112, 16, v226
	v_ashrrev_i32_e32 v113, 31, v112
	v_pk_mul_f32 v[116:117], v[104:105], v[176:177]
	v_pk_mul_f32 v[118:119], v[106:107], v[178:179]
	v_pk_mul_f32 v[124:125], v[104:105], v[180:181]
	v_pk_mul_f32 v[126:127], v[106:107], v[182:183]
	v_lshlrev_b64 v[114:115], 12, v[112:113]
	v_pk_fma_f32 v[118:119], v[110:111], v[182:183], v[118:119] neg_lo:[0,0,1] neg_hi:[0,0,1]
	v_pk_fma_f32 v[116:117], v[108:109], v[180:181], v[116:117] neg_lo:[0,0,1] neg_hi:[0,0,1]
	v_pk_fma_f32 v[126:127], v[110:111], v[178:179], v[126:127]
	v_pk_fma_f32 v[124:125], v[108:109], v[176:177], v[124:125]
	v_cndmask_b32_e64 v111, v111, v119, s[8:9]
	v_cndmask_b32_e64 v110, v110, v118, s[8:9]
	v_cndmask_b32_e64 v113, v109, v117, s[8:9]
	v_cndmask_b32_e64 v117, v107, v127, s[8:9]
	v_cndmask_b32_e64 v118, v106, v126, s[8:9]
	v_cndmask_b32_e64 v119, v105, v125, s[8:9]
	v_cndmask_b32_e64 v124, v104, v124, s[8:9]
	v_mad_i64_i32 v[104:105], s[0:1], v112, s75, v[120:121]
	v_lshl_add_u64 v[106:107], s[34:35], 0, v[114:115]
	v_cndmask_b32_e64 v116, v108, v116, s[8:9]
	v_cndmask_b32_e32 v105, v107, v105, vcc
	v_cndmask_b32_e32 v104, v106, v104, vcc
	v_lshl_add_u64 v[108:109], v[104:105], 0, v[122:123]
	v_cvt_pk_bf16_f32 v104, v116, v113
	v_cvt_pk_bf16_f32 v105, v110, v111
	v_cvt_pk_bf16_f32 v106, v124, v119
	v_cvt_pk_bf16_f32 v107, v118, v117
	v_pk_mul_f32 v[98:99], v[212:213], v[98:99] op_sel_hi:[0,1]
	v_pk_mul_f32 v[96:97], v[212:213], v[96:97] op_sel_hi:[0,1]
	global_store_dwordx4 v[108:109], v[104:107], off
	v_pk_mul_f32 v[102:103], v[212:213], v[102:103] op_sel_hi:[0,1]
	v_pk_mul_f32 v[100:101], v[212:213], v[100:101] op_sel_hi:[0,1]
	v_pk_mul_f32 v[104:105], v[96:97], v[176:177]
	v_pk_mul_f32 v[106:107], v[98:99], v[178:179]
	v_pk_mul_f32 v[110:111], v[96:97], v[180:181]
	v_pk_mul_f32 v[112:113], v[98:99], v[182:183]
	v_pk_fma_f32 v[106:107], v[102:103], v[182:183], v[106:107] neg_lo:[0,0,1] neg_hi:[0,0,1]
	v_pk_fma_f32 v[104:105], v[100:101], v[180:181], v[104:105] neg_lo:[0,0,1] neg_hi:[0,0,1]
	v_pk_fma_f32 v[112:113], v[102:103], v[178:179], v[112:113]
	v_pk_fma_f32 v[110:111], v[100:101], v[176:177], v[110:111]
	v_cndmask_b32_e64 v103, v103, v107, s[10:11]
	v_cndmask_b32_e64 v102, v102, v106, s[10:11]
; __device__ __forceinline__ void st_nt(float* p, f32x4 v) { __builtin_nontemporal_store(v, (f32x4*)p); }
; __device__ __forceinline__ void st_nt(bf16_t* p, u32x4 v) { __builtin_nontemporal_store(v, (u32x4*)p); }
; __device__ __forceinline__ u32x4 pack8(const f32x4 a, const f32x4 b) { u32x4 w; w.x = cvt_pk_bf16(a[0], a[1]); w.y = cvt_pk_bf16(a[2], a[3]); w.z = cvt_pk_bf16(b[0], b[1]); w.w = cvt_pk_bf16(b[2], b[3]); return w; }
;     __device__ __forceinline__ void operator()(Acc& acc, const Unit& u, int wr, int wc, int fr, int fq, const float (&rsv)[8]) const {
;     ...
; #pragma unroll
;         for (int ai = 0; ai < 2; ++ai)
; #pragma unroll
;             for (int m = 0; m < 4; ++m) {
;                 const int row = row0 + ai * HALF + m * 16;
;                 const float rs = rsv[ai * 4 + m];
; #pragma unroll
;                 for (int bj = 0; bj < 2; ++bj) { const int col = col0 + bj * HALF; f32x4 v0 = acc[ai][bj][m][0] * rs, v1 = acc[ai][bj][m][1] * rs;
;                     if (bj == ropebj) { const f32x4 c = cs[ai * 4 + m], s = sn[ai * 4 + m]; const f32x4 o1 = v0 * c - v1 * s, o2 = v1 * c + v0 * s; v0 = o1; v1 = o2; }
;                     if (u.z == 0) st_nt(q + (size_t)row * 1536 + col, pack8(v0, v1));
;                     else st_nt(kv + (size_t)row * 2048 + col, pack8(v0, v1)); }
;             }
	v_cndmask_b32_e64 v101, v101, v105, s[10:11]
	v_cndmask_b32_e64 v100, v100, v104, s[10:11]
	v_cndmask_b32_e64 v99, v99, v113, s[10:11]
	v_cndmask_b32_e64 v104, v98, v112, s[10:11]
	v_cndmask_b32_e64 v98, v97, v111, s[10:11]
	v_cndmask_b32_e64 v105, v96, v110, s[10:11]
	v_cvt_pk_bf16_f32 v96, v100, v101
	v_cvt_pk_bf16_f32 v97, v102, v103
	v_cvt_pk_bf16_f32 v98, v105, v98
	v_cvt_pk_bf16_f32 v99, v104, v99
	global_store_dwordx4 v[108:109], v[96:99], off offset:256
	v_pk_mul_f32 v[90:91], v[214:215], v[90:91] op_sel_hi:[0,1]
	v_pk_mul_f32 v[88:89], v[214:215], v[88:89] op_sel_hi:[0,1]
	v_or_b32_e32 v96, 32, v226
	v_ashrrev_i32_e32 v97, 31, v96
	v_pk_mul_f32 v[94:95], v[214:215], v[94:95] op_sel_hi:[0,1]
	v_pk_mul_f32 v[92:93], v[214:215], v[92:93] op_sel_hi:[0,1]
	v_pk_mul_f32 v[100:101], v[88:89], v[168:169]
	v_pk_mul_f32 v[102:103], v[90:91], v[170:171]
	v_pk_mul_f32 v[104:105], v[88:89], v[172:173]
	v_pk_mul_f32 v[106:107], v[90:91], v[174:175]
	v_lshlrev_b64 v[98:99], 12, v[96:97]
	v_pk_fma_f32 v[102:103], v[94:95], v[174:175], v[102:103] neg_lo:[0,0,1] neg_hi:[0,0,1]
	v_pk_fma_f32 v[100:101], v[92:93], v[172:173], v[100:101] neg_lo:[0,0,1] neg_hi:[0,0,1]
	v_pk_fma_f32 v[106:107], v[94:95], v[170:171], v[106:107]
	v_pk_fma_f32 v[104:105], v[92:93], v[168:169], v[104:105]
	v_cndmask_b32_e64 v95, v95, v103, s[8:9]
	v_cndmask_b32_e64 v94, v94, v102, s[8:9]
	v_cndmask_b32_e64 v97, v93, v101, s[8:9]
	v_cndmask_b32_e64 v101, v91, v107, s[8:9]
	v_cndmask_b32_e64 v102, v90, v106, s[8:9]
	v_cndmask_b32_e64 v103, v89, v105, s[8:9]
	v_cndmask_b32_e64 v104, v88, v104, s[8:9]
	v_mad_i64_i32 v[88:89], s[0:1], v96, s75, v[120:121]
	v_lshl_add_u64 v[90:91], s[34:35], 0, v[98:99]
	v_cndmask_b32_e64 v100, v92, v100, s[8:9]
	v_cndmask_b32_e32 v89, v91, v89, vcc
	v_cndmask_b32_e32 v88, v90, v88, vcc
	v_lshl_add_u64 v[92:93], v[88:89], 0, v[122:123]
	v_cvt_pk_bf16_f32 v88, v100, v97
	v_cvt_pk_bf16_f32 v89, v94, v95
	v_cvt_pk_bf16_f32 v90, v104, v103
	v_cvt_pk_bf16_f32 v91, v102, v101
	v_pk_mul_f32 v[82:83], v[214:215], v[82:83] op_sel_hi:[0,1]
	v_pk_mul_f32 v[80:81], v[214:215], v[80:81] op_sel_hi:[0,1]
	global_store_dwordx4 v[92:93], v[88:91], off
	v_pk_mul_f32 v[86:87], v[214:215], v[86:87] op_sel_hi:[0,1]
	v_pk_mul_f32 v[84:85], v[214:215], v[84:85] op_sel_hi:[0,1]
	v_pk_mul_f32 v[88:89], v[80:81], v[168:169]
	v_pk_mul_f32 v[90:91], v[82:83], v[170:171]
	v_pk_mul_f32 v[94:95], v[80:81], v[172:173]
	v_pk_mul_f32 v[96:97], v[82:83], v[174:175]
	v_pk_fma_f32 v[90:91], v[86:87], v[174:175], v[90:91] neg_lo:[0,0,1] neg_hi:[0,0,1]
	v_pk_fma_f32 v[88:89], v[84:85], v[172:173], v[88:89] neg_lo:[0,0,1] neg_hi:[0,0,1]
	v_pk_fma_f32 v[96:97], v[86:87], v[170:171], v[96:97]
	v_pk_fma_f32 v[94:95], v[84:85], v[168:169], v[94:95]
	v_cndmask_b32_e64 v87, v87, v91, s[10:11]
	v_cndmask_b32_e64 v86, v86, v90, s[10:11]
	v_cndmask_b32_e64 v85, v85, v89, s[10:11]
	v_cndmask_b32_e64 v84, v84, v88, s[10:11]
	v_cndmask_b32_e64 v83, v83, v97, s[10:11]
	v_cndmask_b32_e64 v88, v82, v96, s[10:11]
	v_cndmask_b32_e64 v82, v81, v95, s[10:11]
	v_cndmask_b32_e64 v89, v80, v94, s[10:11]
	v_cvt_pk_bf16_f32 v80, v84, v85
	v_cvt_pk_bf16_f32 v81, v86, v87
	v_cvt_pk_bf16_f32 v82, v89, v82
	v_cvt_pk_bf16_f32 v83, v88, v83
	global_store_dwordx4 v[92:93], v[80:83], off offset:256
	v_pk_mul_f32 v[74:75], v[216:217], v[74:75] op_sel_hi:[0,1]
	v_pk_mul_f32 v[72:73], v[216:217], v[72:73] op_sel_hi:[0,1]
	v_or_b32_e32 v80, 48, v226
	v_ashrrev_i32_e32 v81, 31, v80
	v_pk_mul_f32 v[78:79], v[216:217], v[78:79] op_sel_hi:[0,1]
	v_pk_mul_f32 v[76:77], v[216:217], v[76:77] op_sel_hi:[0,1]
	v_pk_mul_f32 v[84:85], v[72:73], v[160:161]
	v_pk_mul_f32 v[86:87], v[74:75], v[162:163]
	v_pk_mul_f32 v[88:89], v[72:73], v[164:165]
	v_pk_mul_f32 v[90:91], v[74:75], v[166:167]
	v_lshlrev_b64 v[82:83], 12, v[80:81]
	v_pk_fma_f32 v[86:87], v[78:79], v[166:167], v[86:87] neg_lo:[0,0,1] neg_hi:[0,0,1]
	v_pk_fma_f32 v[84:85], v[76:77], v[164:165], v[84:85] neg_lo:[0,0,1] neg_hi:[0,0,1]
	v_pk_fma_f32 v[90:91], v[78:79], v[162:163], v[90:91]
	v_pk_fma_f32 v[88:89], v[76:77], v[160:161], v[88:89]
	v_cndmask_b32_e64 v79, v79, v87, s[8:9]
	v_cndmask_b32_e64 v78, v78, v86, s[8:9]
	v_cndmask_b32_e64 v81, v77, v85, s[8:9]
	v_cndmask_b32_e64 v85, v75, v91, s[8:9]
	v_cndmask_b32_e64 v86, v74, v90, s[8:9]
	v_cndmask_b32_e64 v87, v73, v89, s[8:9]
	v_cndmask_b32_e64 v88, v72, v88, s[8:9]
	v_mad_i64_i32 v[72:73], s[0:1], v80, s75, v[120:121]
	v_lshl_add_u64 v[74:75], s[34:35], 0, v[82:83]
	v_cndmask_b32_e64 v84, v76, v84, s[8:9]
	v_cndmask_b32_e32 v73, v75, v73, vcc
	v_cndmask_b32_e32 v72, v74, v72, vcc
	v_lshl_add_u64 v[76:77], v[72:73], 0, v[122:123]
	v_cvt_pk_bf16_f32 v72, v84, v81
	v_cvt_pk_bf16_f32 v73, v78, v79
	v_cvt_pk_bf16_f32 v74, v88, v87
	v_cvt_pk_bf16_f32 v75, v86, v85
	v_pk_mul_f32 v[66:67], v[216:217], v[66:67] op_sel_hi:[0,1]
	v_pk_mul_f32 v[64:65], v[216:217], v[64:65] op_sel_hi:[0,1]
	global_store_dwordx4 v[76:77], v[72:75], off
	v_pk_mul_f32 v[70:71], v[216:217], v[70:71] op_sel_hi:[0,1]
	v_pk_mul_f32 v[68:69], v[216:217], v[68:69] op_sel_hi:[0,1]
	v_pk_mul_f32 v[72:73], v[64:65], v[160:161]
	v_pk_mul_f32 v[74:75], v[66:67], v[162:163]
	v_pk_mul_f32 v[78:79], v[64:65], v[164:165]
	v_pk_mul_f32 v[80:81], v[66:67], v[166:167]
	v_pk_fma_f32 v[74:75], v[70:71], v[166:167], v[74:75] neg_lo:[0,0,1] neg_hi:[0,0,1]
	v_pk_fma_f32 v[72:73], v[68:69], v[164:165], v[72:73] neg_lo:[0,0,1] neg_hi:[0,0,1]
	v_pk_fma_f32 v[80:81], v[70:71], v[162:163], v[80:81]
	v_pk_fma_f32 v[78:79], v[68:69], v[160:161], v[78:79]
	v_cndmask_b32_e64 v71, v71, v75, s[10:11]
	v_cndmask_b32_e64 v70, v70, v74, s[10:11]
	v_cndmask_b32_e64 v69, v69, v73, s[10:11]
; __device__ __forceinline__ void st_nt(float* p, f32x4 v) { __builtin_nontemporal_store(v, (f32x4*)p); }
; __device__ __forceinline__ void st_nt(bf16_t* p, u32x4 v) { __builtin_nontemporal_store(v, (u32x4*)p); }
; __device__ __forceinline__ u32x4 pack8(const f32x4 a, const f32x4 b) { u32x4 w; w.x = cvt_pk_bf16(a[0], a[1]); w.y = cvt_pk_bf16(a[2], a[3]); w.z = cvt_pk_bf16(b[0], b[1]); w.w = cvt_pk_bf16(b[2], b[3]); return w; }
;     __device__ __forceinline__ void operator()(Acc& acc, const Unit& u, int wr, int wc, int fr, int fq, const float (&rsv)[8]) const {
;     ...
; #pragma unroll
;         for (int ai = 0; ai < 2; ++ai)
; #pragma unroll
;             for (int m = 0; m < 4; ++m) {
;                 const int row = row0 + ai * HALF + m * 16;
;                 const float rs = rsv[ai * 4 + m];
; #pragma unroll
;                 for (int bj = 0; bj < 2; ++bj) { const int col = col0 + bj * HALF; f32x4 v0 = acc[ai][bj][m][0] * rs, v1 = acc[ai][bj][m][1] * rs;
;                     if (bj == ropebj) { const f32x4 c = cs[ai * 4 + m], s = sn[ai * 4 + m]; const f32x4 o1 = v0 * c - v1 * s, o2 = v1 * c + v0 * s; v0 = o1; v1 = o2; }
;                     if (u.z == 0) st_nt(q + (size_t)row * 1536 + col, pack8(v0, v1));
;                     else st_nt(kv + (size_t)row * 2048 + col, pack8(v0, v1)); }
;             }
	v_cndmask_b32_e64 v68, v68, v72, s[10:11]
	v_cndmask_b32_e64 v67, v67, v81, s[10:11]
	v_cndmask_b32_e64 v72, v66, v80, s[10:11]
	v_cndmask_b32_e64 v66, v65, v79, s[10:11]
	v_cndmask_b32_e64 v73, v64, v78, s[10:11]
	v_cvt_pk_bf16_f32 v64, v68, v69
	v_cvt_pk_bf16_f32 v65, v70, v71
	v_cvt_pk_bf16_f32 v66, v73, v66
	v_cvt_pk_bf16_f32 v67, v72, v67
	global_store_dwordx4 v[76:77], v[64:67], off offset:256
	v_pk_mul_f32 v[58:59], v[218:219], v[58:59] op_sel_hi:[0,1]
	v_pk_mul_f32 v[56:57], v[218:219], v[56:57] op_sel_hi:[0,1]
	v_add_u32_e32 v64, 0x80, v226
	v_ashrrev_i32_e32 v65, 31, v64
	v_pk_mul_f32 v[62:63], v[218:219], v[62:63] op_sel_hi:[0,1]
	v_pk_mul_f32 v[60:61], v[218:219], v[60:61] op_sel_hi:[0,1]
	v_pk_mul_f32 v[68:69], v[56:57], v[152:153]
	v_pk_mul_f32 v[70:71], v[58:59], v[154:155]
	v_pk_mul_f32 v[72:73], v[56:57], v[156:157]
	v_pk_mul_f32 v[74:75], v[58:59], v[158:159]
	v_lshlrev_b64 v[66:67], 12, v[64:65]
	v_pk_fma_f32 v[70:71], v[62:63], v[158:159], v[70:71] neg_lo:[0,0,1] neg_hi:[0,0,1]
	v_pk_fma_f32 v[68:69], v[60:61], v[156:157], v[68:69] neg_lo:[0,0,1] neg_hi:[0,0,1]
	v_pk_fma_f32 v[74:75], v[62:63], v[154:155], v[74:75]
	v_pk_fma_f32 v[72:73], v[60:61], v[152:153], v[72:73]
	v_cndmask_b32_e64 v63, v63, v71, s[8:9]
	v_cndmask_b32_e64 v62, v62, v70, s[8:9]
	v_cndmask_b32_e64 v65, v61, v69, s[8:9]
	v_cndmask_b32_e64 v69, v59, v75, s[8:9]
	v_cndmask_b32_e64 v70, v58, v74, s[8:9]
	v_cndmask_b32_e64 v71, v57, v73, s[8:9]
	v_cndmask_b32_e64 v72, v56, v72, s[8:9]
	v_mad_i64_i32 v[56:57], s[0:1], v64, s75, v[120:121]
	v_lshl_add_u64 v[58:59], s[34:35], 0, v[66:67]
	v_cndmask_b32_e64 v68, v60, v68, s[8:9]
	v_cndmask_b32_e32 v57, v59, v57, vcc
	v_cndmask_b32_e32 v56, v58, v56, vcc
	v_lshl_add_u64 v[60:61], v[56:57], 0, v[122:123]
	v_cvt_pk_bf16_f32 v56, v68, v65
	v_cvt_pk_bf16_f32 v57, v62, v63
	v_cvt_pk_bf16_f32 v58, v72, v71
	v_cvt_pk_bf16_f32 v59, v70, v69
	v_pk_mul_f32 v[50:51], v[218:219], v[50:51] op_sel_hi:[0,1]
	v_pk_mul_f32 v[48:49], v[218:219], v[48:49] op_sel_hi:[0,1]
	global_store_dwordx4 v[60:61], v[56:59], off
	v_pk_mul_f32 v[54:55], v[218:219], v[54:55] op_sel_hi:[0,1]
	v_pk_mul_f32 v[52:53], v[218:219], v[52:53] op_sel_hi:[0,1]
	v_pk_mul_f32 v[56:57], v[48:49], v[152:153]
	v_pk_mul_f32 v[58:59], v[50:51], v[154:155]
	v_pk_mul_f32 v[62:63], v[48:49], v[156:157]
	v_pk_mul_f32 v[64:65], v[50:51], v[158:159]
	v_pk_fma_f32 v[58:59], v[54:55], v[158:159], v[58:59] neg_lo:[0,0,1] neg_hi:[0,0,1]
	v_pk_fma_f32 v[56:57], v[52:53], v[156:157], v[56:57] neg_lo:[0,0,1] neg_hi:[0,0,1]
	v_pk_fma_f32 v[64:65], v[54:55], v[154:155], v[64:65]
	v_pk_fma_f32 v[62:63], v[52:53], v[152:153], v[62:63]
	v_cndmask_b32_e64 v55, v55, v59, s[10:11]
	v_cndmask_b32_e64 v54, v54, v58, s[10:11]
	v_cndmask_b32_e64 v53, v53, v57, s[10:11]
	v_cndmask_b32_e64 v52, v52, v56, s[10:11]
	v_cndmask_b32_e64 v51, v51, v65, s[10:11]
	v_cndmask_b32_e64 v56, v50, v64, s[10:11]
	v_cndmask_b32_e64 v50, v49, v63, s[10:11]
	v_cndmask_b32_e64 v57, v48, v62, s[10:11]
	v_cvt_pk_bf16_f32 v48, v52, v53
	v_cvt_pk_bf16_f32 v49, v54, v55
	v_cvt_pk_bf16_f32 v50, v57, v50
	v_cvt_pk_bf16_f32 v51, v56, v51
	global_store_dwordx4 v[60:61], v[48:51], off offset:256
	v_pk_mul_f32 v[42:43], v[220:221], v[42:43] op_sel_hi:[0,1]
	v_pk_mul_f32 v[40:41], v[220:221], v[40:41] op_sel_hi:[0,1]
	v_add_u32_e32 v48, 0x90, v226
	v_ashrrev_i32_e32 v49, 31, v48
	v_pk_mul_f32 v[46:47], v[220:221], v[46:47] op_sel_hi:[0,1]
	v_pk_mul_f32 v[44:45], v[220:221], v[44:45] op_sel_hi:[0,1]
	v_pk_mul_f32 v[52:53], v[40:41], v[144:145]
	v_pk_mul_f32 v[54:55], v[42:43], v[146:147]
	v_pk_mul_f32 v[56:57], v[40:41], v[148:149]
	v_pk_mul_f32 v[58:59], v[42:43], v[150:151]
	v_lshlrev_b64 v[50:51], 12, v[48:49]
	v_pk_fma_f32 v[54:55], v[46:47], v[150:151], v[54:55] neg_lo:[0,0,1] neg_hi:[0,0,1]
	v_pk_fma_f32 v[52:53], v[44:45], v[148:149], v[52:53] neg_lo:[0,0,1] neg_hi:[0,0,1]
	v_pk_fma_f32 v[58:59], v[46:47], v[146:147], v[58:59]
	v_pk_fma_f32 v[56:57], v[44:45], v[144:145], v[56:57]
	v_cndmask_b32_e64 v47, v47, v55, s[8:9]
	v_cndmask_b32_e64 v46, v46, v54, s[8:9]
	v_cndmask_b32_e64 v49, v45, v53, s[8:9]
	v_cndmask_b32_e64 v53, v43, v59, s[8:9]
	v_cndmask_b32_e64 v54, v42, v58, s[8:9]
	v_cndmask_b32_e64 v55, v41, v57, s[8:9]
	v_cndmask_b32_e64 v56, v40, v56, s[8:9]
	v_mad_i64_i32 v[40:41], s[0:1], v48, s75, v[120:121]
	v_lshl_add_u64 v[42:43], s[34:35], 0, v[50:51]
	v_cndmask_b32_e64 v52, v44, v52, s[8:9]
	v_cndmask_b32_e32 v41, v43, v41, vcc
	v_cndmask_b32_e32 v40, v42, v40, vcc
	v_lshl_add_u64 v[44:45], v[40:41], 0, v[122:123]
	v_cvt_pk_bf16_f32 v40, v52, v49
	v_cvt_pk_bf16_f32 v41, v46, v47
	v_cvt_pk_bf16_f32 v42, v56, v55
	v_cvt_pk_bf16_f32 v43, v54, v53
	v_pk_mul_f32 v[34:35], v[220:221], v[34:35] op_sel_hi:[0,1]
	v_pk_mul_f32 v[32:33], v[220:221], v[32:33] op_sel_hi:[0,1]
	global_store_dwordx4 v[44:45], v[40:43], off
	v_pk_mul_f32 v[38:39], v[220:221], v[38:39] op_sel_hi:[0,1]
	v_pk_mul_f32 v[36:37], v[220:221], v[36:37] op_sel_hi:[0,1]
	v_pk_mul_f32 v[40:41], v[32:33], v[144:145]
	v_pk_mul_f32 v[42:43], v[34:35], v[146:147]
	v_pk_mul_f32 v[46:47], v[32:33], v[148:149]
	v_pk_mul_f32 v[48:49], v[34:35], v[150:151]
	v_pk_fma_f32 v[42:43], v[38:39], v[150:151], v[42:43] neg_lo:[0,0,1] neg_hi:[0,0,1]
	v_pk_fma_f32 v[40:41], v[36:37], v[148:149], v[40:41] neg_lo:[0,0,1] neg_hi:[0,0,1]
	v_pk_fma_f32 v[48:49], v[38:39], v[146:147], v[48:49]
	v_pk_fma_f32 v[46:47], v[36:37], v[144:145], v[46:47]
	v_cndmask_b32_e64 v39, v39, v43, s[10:11]
	v_cndmask_b32_e64 v38, v38, v42, s[10:11]
	v_cndmask_b32_e64 v37, v37, v41, s[10:11]
	v_cndmask_b32_e64 v36, v36, v40, s[10:11]
	v_cndmask_b32_e64 v35, v35, v49, s[10:11]
; __device__ __forceinline__ void st_nt(float* p, f32x4 v) { __builtin_nontemporal_store(v, (f32x4*)p); }
; __device__ __forceinline__ void st_nt(bf16_t* p, u32x4 v) { __builtin_nontemporal_store(v, (u32x4*)p); }
; __device__ __forceinline__ u32x4 pack8(const f32x4 a, const f32x4 b) { u32x4 w; w.x = cvt_pk_bf16(a[0], a[1]); w.y = cvt_pk_bf16(a[2], a[3]); w.z = cvt_pk_bf16(b[0], b[1]); w.w = cvt_pk_bf16(b[2], b[3]); return w; }
;     __device__ __forceinline__ void rstd_fill(float (&rsv)[8], const Unit& u, int wr, int fr, int fq) const { rstd_regs32(rsv, part, u.pm * BM + wr * 64 + fr, fq); }
;     __device__ __forceinline__ void rstd_fill(float (&rsv)[8], const Unit& u, int wr, int fr, int fq) const { rstd_regs32(rsv, part, u.pm * BM + wr * 64 + fr, fq); }
;     __device__ __forceinline__ void rstd_fill(float (&rsv)[8], const Unit& u, int wr, int fr, int fq) const { rstd_regs32(rsv, part, u.pm * BM + wr * 64 + fr, fq); }
;     __device__ __forceinline__ void rstd_fill(float (&rsv)[8], const Unit& u, int wr, int fr, int fq) const { rstd_regs32(rsv, part, u.pm * BM + wr * 64 + fr, fq); }
; #define PG8_SCHED __builtin_amdgcn_sched_barrier(0)
;     __device__ __forceinline__ void operator()(Acc& acc, const Unit& u, int wr, int wc, int fr, int fq, const float (&rsv)[8]) const {
;     ...
; #pragma unroll
;         for (int ai = 0; ai < 2; ++ai)
; #pragma unroll
;             for (int m = 0; m < 4; ++m) {
;                 const int row = row0 + ai * HALF + m * 16;
;                 const float rs = rsv[ai * 4 + m];
; #pragma unroll
;                 for (int bj = 0; bj < 2; ++bj) { const int col = col0 + bj * HALF; f32x4 v0 = acc[ai][bj][m][0] * rs, v1 = acc[ai][bj][m][1] * rs;
;                     if (bj == ropebj) { const f32x4 c = cs[ai * 4 + m], s = sn[ai * 4 + m]; const f32x4 o1 = v0 * c - v1 * s, o2 = v1 * c + v0 * s; v0 = o1; v1 = o2; }
;                     if (u.z == 0) st_nt(q + (size_t)row * 1536 + col, pack8(v0, v1));
;                     else st_nt(kv + (size_t)row * 2048 + col, pack8(v0, v1)); }
;             }
; template <class Epi>
; __device__ __forceinline__ void gemm_phase(LAS unsigned char* lds, const GSched& S, const int K, const int lda, const int ldb, const Epi& E) {
;     ...
;         if (!has_next) break;
;         if constexpr (Epi::RSTD) { if (nxt.pm != cur.pm || nxt.z != cur.z) { PG8_SCHED; E.rstd_fill(rsv, nxt, wr, fr, fq); PG8_SCHED; } }
	v_cndmask_b32_e64 v40, v34, v48, s[10:11]
	v_cndmask_b32_e64 v34, v33, v47, s[10:11]
	v_cndmask_b32_e64 v41, v32, v46, s[10:11]
	v_cvt_pk_bf16_f32 v32, v36, v37
	v_cvt_pk_bf16_f32 v33, v38, v39
	v_cvt_pk_bf16_f32 v34, v41, v34
	v_cvt_pk_bf16_f32 v35, v40, v35
	global_store_dwordx4 v[44:45], v[32:35], off offset:256
	v_pk_mul_f32 v[26:27], v[222:223], v[26:27] op_sel_hi:[0,1]
	v_pk_mul_f32 v[24:25], v[222:223], v[24:25] op_sel_hi:[0,1]
	v_add_u32_e32 v32, 0xa0, v226
	v_ashrrev_i32_e32 v33, 31, v32
	v_pk_mul_f32 v[30:31], v[222:223], v[30:31] op_sel_hi:[0,1]
	v_pk_mul_f32 v[28:29], v[222:223], v[28:29] op_sel_hi:[0,1]
	v_pk_mul_f32 v[36:37], v[24:25], v[136:137]
	v_pk_mul_f32 v[38:39], v[26:27], v[138:139]
	v_pk_mul_f32 v[40:41], v[24:25], v[140:141]
	v_pk_mul_f32 v[42:43], v[26:27], v[142:143]
	v_lshlrev_b64 v[34:35], 12, v[32:33]
	v_pk_fma_f32 v[38:39], v[30:31], v[142:143], v[38:39] neg_lo:[0,0,1] neg_hi:[0,0,1]
	v_pk_fma_f32 v[36:37], v[28:29], v[140:141], v[36:37] neg_lo:[0,0,1] neg_hi:[0,0,1]
	v_pk_fma_f32 v[42:43], v[30:31], v[138:139], v[42:43]
	v_pk_fma_f32 v[40:41], v[28:29], v[136:137], v[40:41]
	v_cndmask_b32_e64 v31, v31, v39, s[8:9]
	v_cndmask_b32_e64 v30, v30, v38, s[8:9]
	v_cndmask_b32_e64 v33, v29, v37, s[8:9]
	v_cndmask_b32_e64 v37, v27, v43, s[8:9]
	v_cndmask_b32_e64 v38, v26, v42, s[8:9]
	v_cndmask_b32_e64 v39, v25, v41, s[8:9]
	v_cndmask_b32_e64 v40, v24, v40, s[8:9]
	v_mad_i64_i32 v[24:25], s[0:1], v32, s75, v[120:121]
	v_lshl_add_u64 v[26:27], s[34:35], 0, v[34:35]
	v_cndmask_b32_e64 v36, v28, v36, s[8:9]
	v_cndmask_b32_e32 v25, v27, v25, vcc
	v_cndmask_b32_e32 v24, v26, v24, vcc
	v_lshl_add_u64 v[28:29], v[24:25], 0, v[122:123]
	v_cvt_pk_bf16_f32 v24, v36, v33
	v_cvt_pk_bf16_f32 v25, v30, v31
	v_cvt_pk_bf16_f32 v26, v40, v39
	v_cvt_pk_bf16_f32 v27, v38, v37
	v_pk_mul_f32 v[18:19], v[222:223], v[18:19] op_sel_hi:[0,1]
	v_pk_mul_f32 v[16:17], v[222:223], v[16:17] op_sel_hi:[0,1]
	global_store_dwordx4 v[28:29], v[24:27], off
	v_pk_mul_f32 v[22:23], v[222:223], v[22:23] op_sel_hi:[0,1]
	v_pk_mul_f32 v[20:21], v[222:223], v[20:21] op_sel_hi:[0,1]
	v_pk_mul_f32 v[24:25], v[16:17], v[136:137]
	v_pk_mul_f32 v[26:27], v[18:19], v[138:139]
	v_pk_mul_f32 v[30:31], v[16:17], v[140:141]
	v_pk_mul_f32 v[32:33], v[18:19], v[142:143]
	v_pk_fma_f32 v[26:27], v[22:23], v[142:143], v[26:27] neg_lo:[0,0,1] neg_hi:[0,0,1]
	v_pk_fma_f32 v[24:25], v[20:21], v[140:141], v[24:25] neg_lo:[0,0,1] neg_hi:[0,0,1]
	v_pk_fma_f32 v[32:33], v[22:23], v[138:139], v[32:33]
	v_pk_fma_f32 v[30:31], v[20:21], v[136:137], v[30:31]
	v_cndmask_b32_e64 v23, v23, v27, s[10:11]
	v_cndmask_b32_e64 v22, v22, v26, s[10:11]
	v_cndmask_b32_e64 v21, v21, v25, s[10:11]
	v_cndmask_b32_e64 v20, v20, v24, s[10:11]
	v_cndmask_b32_e64 v19, v19, v33, s[10:11]
	v_cndmask_b32_e64 v24, v18, v32, s[10:11]
	v_cndmask_b32_e64 v18, v17, v31, s[10:11]
	v_cndmask_b32_e64 v25, v16, v30, s[10:11]
	v_cvt_pk_bf16_f32 v16, v20, v21
	v_cvt_pk_bf16_f32 v17, v22, v23
	v_cvt_pk_bf16_f32 v18, v25, v18
	v_cvt_pk_bf16_f32 v19, v24, v19
	global_store_dwordx4 v[28:29], v[16:19], off offset:256
	v_pk_mul_f32 v[10:11], v[224:225], v[10:11] op_sel_hi:[0,1]
	v_pk_mul_f32 v[8:9], v[224:225], v[8:9] op_sel_hi:[0,1]
	v_add_u32_e32 v16, 0xb0, v226
	v_ashrrev_i32_e32 v17, 31, v16
	v_pk_mul_f32 v[14:15], v[224:225], v[14:15] op_sel_hi:[0,1]
	v_pk_mul_f32 v[12:13], v[224:225], v[12:13] op_sel_hi:[0,1]
	v_pk_mul_f32 v[20:21], v[8:9], v[132:133]
	v_pk_mul_f32 v[22:23], v[10:11], v[134:135]
	v_pk_mul_f32 v[24:25], v[8:9], v[128:129]
	v_pk_mul_f32 v[26:27], v[10:11], v[130:131]
	v_lshlrev_b64 v[18:19], 12, v[16:17]
	v_pk_fma_f32 v[22:23], v[14:15], v[130:131], v[22:23] neg_lo:[0,0,1] neg_hi:[0,0,1]
	v_pk_fma_f32 v[20:21], v[12:13], v[128:129], v[20:21] neg_lo:[0,0,1] neg_hi:[0,0,1]
	v_pk_fma_f32 v[26:27], v[14:15], v[134:135], v[26:27]
	v_pk_fma_f32 v[24:25], v[12:13], v[132:133], v[24:25]
	v_cndmask_b32_e64 v15, v15, v23, s[8:9]
	v_cndmask_b32_e64 v14, v14, v22, s[8:9]
	v_cndmask_b32_e64 v17, v13, v21, s[8:9]
	v_cndmask_b32_e64 v21, v11, v27, s[8:9]
	v_cndmask_b32_e64 v22, v10, v26, s[8:9]
	v_cndmask_b32_e64 v23, v9, v25, s[8:9]
	v_cndmask_b32_e64 v24, v8, v24, s[8:9]
	v_mad_i64_i32 v[8:9], s[0:1], v16, s75, v[120:121]
	v_lshl_add_u64 v[10:11], s[34:35], 0, v[18:19]
	v_cndmask_b32_e64 v20, v12, v20, s[8:9]
	v_cndmask_b32_e32 v9, v11, v9, vcc
	v_cndmask_b32_e32 v8, v10, v8, vcc
	v_lshl_add_u64 v[12:13], v[8:9], 0, v[122:123]
	v_cvt_pk_bf16_f32 v8, v20, v17
	v_cvt_pk_bf16_f32 v9, v14, v15
	v_cvt_pk_bf16_f32 v10, v24, v23
	v_cvt_pk_bf16_f32 v11, v22, v21
	v_pk_mul_f32 v[2:3], v[224:225], v[2:3] op_sel_hi:[0,1]
	v_pk_mul_f32 v[0:1], v[224:225], v[0:1] op_sel_hi:[0,1]
	global_store_dwordx4 v[12:13], v[8:11], off
	v_pk_mul_f32 v[6:7], v[224:225], v[6:7] op_sel_hi:[0,1]
	v_pk_mul_f32 v[4:5], v[224:225], v[4:5] op_sel_hi:[0,1]
	v_pk_mul_f32 v[8:9], v[0:1], v[132:133]
	v_pk_mul_f32 v[10:11], v[2:3], v[134:135]
	v_pk_mul_f32 v[14:15], v[0:1], v[128:129]
	v_pk_mul_f32 v[16:17], v[2:3], v[130:131]
	v_pk_fma_f32 v[10:11], v[6:7], v[130:131], v[10:11] neg_lo:[0,0,1] neg_hi:[0,0,1]
	v_pk_fma_f32 v[8:9], v[4:5], v[128:129], v[8:9] neg_lo:[0,0,1] neg_hi:[0,0,1]
	v_pk_fma_f32 v[16:17], v[6:7], v[134:135], v[16:17]
	v_pk_fma_f32 v[14:15], v[4:5], v[132:133], v[14:15]
	v_cndmask_b32_e64 v7, v7, v11, s[10:11]
	v_cndmask_b32_e64 v6, v6, v10, s[10:11]
	v_cndmask_b32_e64 v5, v5, v9, s[10:11]
	v_cndmask_b32_e64 v4, v4, v8, s[10:11]
	v_cndmask_b32_e64 v3, v3, v17, s[10:11]
	v_cndmask_b32_e64 v8, v2, v16, s[10:11]
	v_cndmask_b32_e64 v2, v1, v15, s[10:11]
	v_cndmask_b32_e64 v9, v0, v14, s[10:11]
	v_cvt_pk_bf16_f32 v0, v4, v5
	v_cvt_pk_bf16_f32 v1, v6, v7
	v_cvt_pk_bf16_f32 v2, v9, v2
	v_cvt_pk_bf16_f32 v3, v8, v3
	s_mov_b64 s[6:7], -1
	s_and_b64 vcc, exec, s[50:51]
	global_store_dwordx4 v[12:13], v[0:3], off offset:256
	s_cbranch_vccz .LBB0_534
;     __device__ __forceinline__ void rstd_fill(float (&rsv)[8], const Unit& u, int wr, int fr, int fq) const { rstd_regs32(rsv, part, u.pm * BM + wr * 64 + fr, fq); }
;     __device__ __forceinline__ void rstd_fill(float (&rsv)[8], const Unit& u, int wr, int fr, int fq) const { rstd_regs32(rsv, part, u.pm * BM + wr * 64 + fr, fq); }
;     __device__ __forceinline__ void rstd_fill(float (&rsv)[8], const Unit& u, int wr, int fr, int fq) const { rstd_regs32(rsv, part, u.pm * BM + wr * 64 + fr, fq); }
;     __device__ __forceinline__ void rstd_fill(float (&rsv)[8], const Unit& u, int wr, int fr, int fq) const { rstd_regs32(rsv, part, u.pm * BM + wr * 64 + fr, fq); }
;     __device__ __forceinline__ void rstd_fill(float (&rsv)[8], const Unit& u, int wr, int fr, int fq) const { rstd_regs_lat(rsv, latpart, u.pm * BM + wr * 64 + fr, u.z); }
;     __device__ __forceinline__ void rstd_fill(float (&rsv)[8], const Unit& u, int wr, int fr, int fq) const { rstd_regs32(rsv, part_in, u.pm * BM + wr * 64 + fr, fq); }
; #define PG8_SCHED __builtin_amdgcn_sched_barrier(0)
; __device__ __forceinline__ void rstd_regs_lat(float (&rsv)[8], const float* latpart, int row0, int z) {
;     int r0 = row0; asm volatile("" : "+v"(r0));
;     const float* q = latpart + (size_t)r0 * 16 + z * 8;
;     f32x4 a[8], b[8];
; #pragma unroll
;     for (int g = 0; g < 8; ++g) { const float* p = q + (size_t)((g >> 2) * HALF + (g & 3) * 16) * 16; a[g] = *(const f32x4*)p; b[g] = *(const f32x4*)(p + 4); }
; #pragma unroll
;     for (int g = 0; g < 8; ++g) { const float s = ((a[g][0] + a[g][1]) + (a[g][2] + a[g][3])) + ((b[g][0] + b[g][1]) + (b[g][2] + b[g][3]));
;         rsv[g] = __builtin_amdgcn_rsqf(s * (1.0f / 512.0f) + EPS); }
; }
; template <class Epi>
; __device__ __forceinline__ void gemm_phase(LAS unsigned char* lds, const GSched& S, const int K, const int lda, const int ldb, const Epi& E) {
;     ...
;         if constexpr (Epi::RSTD) { if (nxt.pm != cur.pm || nxt.z != cur.z) { PG8_SCHED; E.rstd_fill(rsv, nxt, wr, fr, fq); PG8_SCHED; } }
	s_cmp_eq_u32 s44, s28
	s_cselect_b64 s[0:1], -1, 0
	v_cmp_eq_u32_e32 vcc, s78, v230
	s_and_b64 s[0:1], s[0:1], vcc
	s_and_b64 vcc, exec, s[0:1]
	s_cbranch_vccnz .LBB0_533
	v_lshl_add_u32 v0, s44, 8, v213
	s_lshl_b32 s0, s78, 3
	v_ashrrev_i32_e32 v1, 31, v0
	v_lshlrev_b64 v[0:1], 6, v[0:1]
	v_lshl_add_u64 v[0:1], s[18:19], 0, v[0:1]
	s_ashr_i32 s1, s0, 31
	v_lshl_add_u64 v[56:57], s[0:1], 2, v[0:1]
	global_load_dwordx4 v[0:3], v[56:57], off
	global_load_dwordx4 v[4:7], v[56:57], off offset:16
	global_load_dwordx4 v[8:11], v[56:57], off offset:1024
	global_load_dwordx4 v[12:15], v[56:57], off offset:1040
	global_load_dwordx4 v[16:19], v[56:57], off offset:2048
	global_load_dwordx4 v[20:23], v[56:57], off offset:2064
	global_load_dwordx4 v[24:27], v[56:57], off offset:3072
	global_load_dwordx4 v[28:31], v[56:57], off offset:3088
	v_add_co_u32_e32 v58, vcc, s63, v56
	v_lshl_add_u64 v[36:37], v[56:57], 0, s[20:21]
	s_nop 0
	v_addc_co_u32_e32 v59, vcc, 0, v57, vcc
	global_load_dwordx4 v[32:35], v[58:59], off
	s_nop 0
	global_load_dwordx4 v[36:39], v[36:37], off offset:16
	s_nop 0
	global_load_dwordx4 v[40:43], v[58:59], off offset:1024
	v_lshl_add_u64 v[44:45], v[56:57], 0, s[22:23]
	global_load_dwordx4 v[44:47], v[44:45], off offset:16
	v_lshl_add_u64 v[52:53], v[56:57], 0, s[24:25]
	global_load_dwordx4 v[48:51], v[58:59], off offset:2048
	s_nop 0
	global_load_dwordx4 v[52:55], v[52:53], off offset:16
	v_lshl_add_u64 v[60:61], v[56:57], 0, s[26:27]
	global_load_dwordx4 v[56:59], v[58:59], off offset:3072
	s_nop 0
	global_load_dwordx4 v[60:63], v[60:61], off offset:16
	s_waitcnt vmcnt(0)
	v_mov_b32_e32 v64, v0
	v_mov_b32_e32 v65, v4
	v_mov_b32_e32 v4, v1
	v_mov_b32_e32 v0, v2
	v_mov_b32_e32 v1, v6
	v_mov_b32_e32 v6, v3
	v_mov_b32_e32 v2, v8
	v_mov_b32_e32 v3, v12
	v_mov_b32_e32 v12, v9
	v_mov_b32_e32 v8, v10
	v_mov_b32_e32 v9, v14
	v_mov_b32_e32 v14, v11
	v_mov_b32_e32 v10, v16
	v_mov_b32_e32 v11, v20
	v_mov_b32_e32 v20, v17
	v_mov_b32_e32 v16, v18
	v_mov_b32_e32 v17, v22
	v_mov_b32_e32 v22, v19
	v_mov_b32_e32 v18, v24
	v_mov_b32_e32 v19, v28
	v_mov_b32_e32 v28, v25
	v_mov_b32_e32 v24, v26
	v_mov_b32_e32 v25, v30
	v_mov_b32_e32 v30, v27
	v_pk_add_f32 v[4:5], v[64:65], v[4:5]
	v_pk_add_f32 v[0:1], v[0:1], v[6:7]
	v_pk_add_f32 v[2:3], v[2:3], v[12:13]
	v_pk_add_f32 v[6:7], v[8:9], v[14:15]
	v_pk_add_f32 v[8:9], v[10:11], v[20:21]
	v_pk_add_f32 v[10:11], v[16:17], v[22:23]
	v_pk_add_f32 v[12:13], v[18:19], v[28:29]
	v_mov_b32_e32 v16, v32
	v_mov_b32_e32 v17, v36
	v_mov_b32_e32 v36, v33
	v_mov_b32_e32 v18, v34
	v_mov_b32_e32 v19, v38
	v_mov_b32_e32 v38, v35
	v_pk_add_f32 v[14:15], v[24:25], v[30:31]
	v_pk_add_f32 v[0:1], v[4:5], v[0:1]
	v_pk_add_f32 v[2:3], v[2:3], v[6:7]
	v_pk_add_f32 v[4:5], v[8:9], v[10:11]
	v_pk_add_f32 v[8:9], v[16:17], v[36:37]
	v_pk_add_f32 v[10:11], v[18:19], v[38:39]
	v_pk_add_f32 v[6:7], v[12:13], v[14:15]
	v_add_f32_e32 v12, v0, v1
	v_add_f32_e32 v2, v2, v3
	v_add_f32_e32 v3, v4, v5
	v_pk_add_f32 v[0:1], v[8:9], v[10:11]
	v_fmamk_f32 v2, v2, 0x3b000000, v211
	v_fmamk_f32 v3, v3, 0x3b000000, v211
	v_add_f32_e32 v0, v0, v1
	v_mov_b32_e32 v20, v40
	v_rsq_f32_e32 v212, v2
	v_rsq_f32_e32 v214, v3
	v_fmamk_f32 v0, v0, 0x3b000000, v211
	v_mov_b32_e32 v21, v44
	v_mov_b32_e32 v44, v41
	v_mov_b32_e32 v2, v42
	v_mov_b32_e32 v3, v46
	v_mov_b32_e32 v46, v43
	v_rsq_f32_e32 v218, v0
	v_pk_add_f32 v[0:1], v[20:21], v[44:45]
	v_pk_add_f32 v[2:3], v[2:3], v[46:47]
	v_add_f32_e32 v4, v6, v7
	v_pk_add_f32 v[0:1], v[0:1], v[2:3]
	v_mov_b32_e32 v2, v50
	v_add_f32_e32 v0, v0, v1
	v_fmamk_f32 v0, v0, 0x3b000000, v211
	v_rsq_f32_e32 v220, v0
	v_mov_b32_e32 v0, v48
	v_mov_b32_e32 v1, v52
	v_mov_b32_e32 v52, v49
	v_mov_b32_e32 v3, v54
	v_mov_b32_e32 v54, v51
	v_pk_add_f32 v[0:1], v[0:1], v[52:53]
	v_pk_add_f32 v[2:3], v[2:3], v[54:55]
	v_fmamk_f32 v5, v12, 0x3b000000, v211
	v_pk_add_f32 v[0:1], v[0:1], v[2:3]
	v_mov_b32_e32 v2, v58
	v_add_f32_e32 v0, v0, v1
	v_fmamk_f32 v0, v0, 0x3b000000, v211
	v_rsq_f32_e32 v222, v0
	v_mov_b32_e32 v0, v56
	v_mov_b32_e32 v1, v60
	v_mov_b32_e32 v60, v57
	v_mov_b32_e32 v3, v62
	v_mov_b32_e32 v62, v59
	v_pk_add_f32 v[0:1], v[0:1], v[60:61]
	v_pk_add_f32 v[2:3], v[2:3], v[62:63]
	v_fmamk_f32 v4, v4, 0x3b000000, v211
	v_pk_add_f32 v[0:1], v[0:1], v[2:3]
	v_rsq_f32_e32 v210, v5
	v_add_f32_e32 v0, v0, v1
	v_fmamk_f32 v0, v0, 0x3b000000, v211
	v_rsq_f32_e32 v216, v4
	v_rsq_f32_e32 v224, v0
	s_branch .LBB0_533

; #define PG8_STAGE(bufoff, gbase, voff) do { _Pragma("unroll") for (int _i = 0; _i < 2; ++_i) \
;         __builtin_amdgcn_global_load_lds((const unsigned*)((const char*)(gbase) + (voff)[_i]), (LAS unsigned*)(lds + (bufoff) + ldsw + _i * 8192), 16, 0, 0); } while (0)
; #define PG8_LDA(dst, b, h) do { _Pragma("unroll") for (int m = 0; m < 4; ++m) _Pragma("unroll") for (int k = 0; k < 2; ++k) dst[m][k] = *(const LAS bf16x8*)(lds + PG8_SA(b, h) + aoff + m * 2048 + k * 1024); } while (0)
; #define PG8_LDB(dst, b, h) do { _Pragma("unroll") for (int n = 0; n < 2; ++n) _Pragma("unroll") for (int k = 0; k < 2; ++k) dst[n][k] = *(const LAS bf16x8*)(lds + PG8_SB(b, h) + boff + n * 2048 + k * 1024); } while (0)
; #define PG8_WAIT_V(n) asm volatile("s_waitcnt vmcnt(" #n ")" ::: "memory")
; #define PG8_WAIT_L(n) asm volatile("s_waitcnt lgkmcnt(" #n ")" ::: "memory")
; #define PG8_BAR __builtin_amdgcn_s_barrier()
; template <class Epi>
; __device__ __forceinline__ void gemm_phase(LAS unsigned char* lds, const GSched& S, const int K, const int lda, const int ldb, const Epi& E) {
;     ...
;         for (int t = 0; t < nt; t += 2) {
;             const bool last = (t == nt - 2);
;             const char* a1 = cA + (size_t)(t + 1) * kstep;
;             const char* a2 = last ? nA : cA + (size_t)(t + 2) * kstep; const char* b2 = last ? nB : cB + (size_t)(t + 2) * kstep;
;             const char* a3 = a2 + kstep; const char* b3 = b2 + kstep;
;             PG8_LDB(B0, 0, 0); PG8_SCHED; PG8_LDA(At, 0, 0); PG8_STAGE(PG8_SA(1, 1), a1 + hstepA, voffA);
;             PG8_WAIT_L(8); PG8_BAR; PG8_WAIT_L(0); PG8_MMA(0, 0, At, B0); PG8_BAR; PG8_SCHED;
;             if constexpr (!Epi::NARROW) PG8_LDB(B1, 0, 1); PG8_STAGE(PG8_SB(0, 0), b2, voffB);
;             PG8_BAR; PG8_WAIT_L(0); if constexpr (!Epi::NARROW) PG8_MMA(0, 1, At, B1); PG8_BAR;
;             PG8_LDA(At, 0, 1); PG8_STAGE(PG8_SA(0, 0), a2, voffA);
;             PG8_BAR; PG8_WAIT_L(0); PG8_MMA(1, 0, At, B0); PG8_BAR; PG8_SCHED;
;             PG8_STAGE(PG8_SB(0, 1), b2 + hstepB, voffB);
;             PG8_WAIT_V(6); PG8_BAR; if constexpr (!Epi::NARROW) PG8_MMA(1, 1, At, B1); PG8_BAR;
;             PG8_LDB(B0, 1, 0); PG8_SCHED; PG8_LDA(At, 1, 0); PG8_STAGE(PG8_SA(0, 1), a2 + hstepA, voffA);
;             PG8_WAIT_L(8); PG8_BAR; PG8_WAIT_L(0); PG8_MMA(0, 0, At, B0); PG8_BAR; PG8_SCHED;
.LBB0_769:
	ds_read_b128 v[166:169], v154
	ds_read_b128 v[170:173], v154 offset:1024
	ds_read_b128 v[174:177], v154 offset:2048
	ds_read_b128 v[178:181], v154 offset:3072
	s_add_u32 s34, s30, 0x100
	s_addc_u32 s35, s31, 0
	s_cmp_eq_u32 s64, 28
	s_cselect_b32 s39, s29, s35
	s_cselect_b32 s38, s28, s34
	s_cselect_b32 s37, s9, s5
	s_cselect_b32 s36, s8, s4
	v_lshl_add_u64 v[146:147], s[30:31], 0, v[140:141]
	s_add_i32 m0, s45, 0xc000
	ds_read_b128 v[182:185], v155
	ds_read_b128 v[186:189], v155 offset:1024
	ds_read_b128 v[190:193], v155 offset:2048
	ds_read_b128 v[194:197], v155 offset:3072
	ds_read_b128 v[198:201], v155 offset:4096
	ds_read_b128 v[202:205], v155 offset:5120
	ds_read_b128 v[206:209], v155 offset:6144
	ds_read_b128 v[210:213], v155 offset:7168
	global_load_lds_dwordx4 v[146:147], off
	v_lshl_add_u64 v[146:147], s[30:31], 0, v[138:139]
	s_add_i32 m0, s45, 0xe000
	s_nop 0
	global_load_lds_dwordx4 v[146:147], off
	s_waitcnt lgkmcnt(8)
	s_barrier
	s_waitcnt lgkmcnt(0)
	s_setprio 1
	s_waitcnt lgkmcnt(0)
	v_mfma_f32_16x16x32_bf16 v[124:127], v[166:169], v[182:185], v[124:127]
	v_mfma_f32_16x16x32_bf16 v[120:123], v[174:177], v[182:185], v[120:123]
	v_mfma_f32_16x16x32_bf16 v[108:111], v[166:169], v[190:193], v[108:111]
	v_mfma_f32_16x16x32_bf16 v[104:107], v[174:177], v[190:193], v[104:107]
	v_mfma_f32_16x16x32_bf16 v[92:95], v[166:169], v[198:201], v[92:95]
	v_mfma_f32_16x16x32_bf16 v[88:91], v[174:177], v[198:201], v[88:91]
	v_mfma_f32_16x16x32_bf16 v[76:79], v[166:169], v[206:209], v[76:79]
	v_mfma_f32_16x16x32_bf16 v[72:75], v[174:177], v[206:209], v[72:75]
	v_mfma_f32_16x16x32_bf16 v[124:127], v[170:173], v[186:189], v[124:127]
	v_mfma_f32_16x16x32_bf16 v[120:123], v[178:181], v[186:189], v[120:123]
	v_mfma_f32_16x16x32_bf16 v[108:111], v[170:173], v[194:197], v[108:111]
	v_mfma_f32_16x16x32_bf16 v[104:107], v[178:181], v[194:197], v[104:107]
	v_mfma_f32_16x16x32_bf16 v[92:95], v[170:173], v[202:205], v[92:95]
	v_mfma_f32_16x16x32_bf16 v[88:91], v[178:181], v[202:205], v[88:91]
	v_mfma_f32_16x16x32_bf16 v[76:79], v[170:173], v[210:213], v[76:79]
	v_mfma_f32_16x16x32_bf16 v[72:75], v[178:181], v[210:213], v[72:75]
	s_setprio 0
	s_barrier
	s_add_i32 s30, s58, s44
	v_lshl_add_u64 v[146:147], s[36:37], 0, v[130:131]
	s_mov_b32 m0, s30
	ds_read_b128 v[214:217], v156
	ds_read_b128 v[218:221], v156 offset:1024
	ds_read_b128 v[222:225], v156 offset:2048
	ds_read_b128 v[226:229], v156 offset:3072
	global_load_lds_dwordx4 v[146:147], off
	v_lshl_add_u64 v[230:231], s[36:37], 0, v[134:135]
	s_add_i32 m0, s30, 0x2000
	s_nop 0
	global_load_lds_dwordx4 v[230:231], off
	s_barrier
	s_waitcnt lgkmcnt(0)
	s_setprio 1
	v_mfma_f32_16x16x32_bf16 v[116:119], v[214:217], v[182:185], v[116:119]
	v_mfma_f32_16x16x32_bf16 v[112:115], v[222:225], v[182:185], v[112:115]
	v_mfma_f32_16x16x32_bf16 v[100:103], v[214:217], v[190:193], v[100:103]
	v_mfma_f32_16x16x32_bf16 v[96:99], v[222:225], v[190:193], v[96:99]
	v_mfma_f32_16x16x32_bf16 v[84:87], v[214:217], v[198:201], v[84:87]
	v_mfma_f32_16x16x32_bf16 v[80:83], v[222:225], v[198:201], v[80:83]
	v_mfma_f32_16x16x32_bf16 v[68:71], v[214:217], v[206:209], v[68:71]
	v_mfma_f32_16x16x32_bf16 v[64:67], v[222:225], v[206:209], v[64:67]
	v_mfma_f32_16x16x32_bf16 v[116:119], v[218:221], v[186:189], v[116:119]
	v_mfma_f32_16x16x32_bf16 v[112:115], v[226:229], v[186:189], v[112:115]
	v_mfma_f32_16x16x32_bf16 v[100:103], v[218:221], v[194:197], v[100:103]
	v_mfma_f32_16x16x32_bf16 v[96:99], v[226:229], v[194:197], v[96:99]
	v_mfma_f32_16x16x32_bf16 v[84:87], v[218:221], v[202:205], v[84:87]
	v_mfma_f32_16x16x32_bf16 v[80:83], v[226:229], v[202:205], v[80:83]
	v_mfma_f32_16x16x32_bf16 v[68:71], v[218:221], v[210:213], v[68:71]
	v_mfma_f32_16x16x32_bf16 v[64:67], v[226:229], v[210:213], v[64:67]
	s_setprio 0
	s_mov_b32 m0, s45
	v_lshl_add_u64 v[234:235], s[38:39], 0, v[128:129]
	s_barrier
	ds_read_b128 v[182:185], v155 offset:16384
	ds_read_b128 v[186:189], v155 offset:17408
	ds_read_b128 v[190:193], v155 offset:18432
	ds_read_b128 v[194:197], v155 offset:19456
	ds_read_b128 v[198:201], v155 offset:20480
	ds_read_b128 v[202:205], v155 offset:21504
	ds_read_b128 v[206:209], v155 offset:22528
	ds_read_b128 v[210:213], v155 offset:23552
	global_load_lds_dwordx4 v[234:235], off
	v_lshl_add_u64 v[236:237], s[38:39], 0, v[132:133]
	s_mov_b32 m0, s46
	s_nop 0
	global_load_lds_dwordx4 v[236:237], off
	s_barrier
	s_waitcnt lgkmcnt(0)
	s_setprio 1
	v_mfma_f32_16x16x32_bf16 v[60:63], v[166:169], v[182:185], v[60:63]
	v_mfma_f32_16x16x32_bf16 v[56:59], v[174:177], v[182:185], v[56:59]
	v_mfma_f32_16x16x32_bf16 v[44:47], v[166:169], v[190:193], v[44:47]
	v_mfma_f32_16x16x32_bf16 v[40:43], v[174:177], v[190:193], v[40:43]
	v_mfma_f32_16x16x32_bf16 v[28:31], v[166:169], v[198:201], v[28:31]
	v_mfma_f32_16x16x32_bf16 v[24:27], v[174:177], v[198:201], v[24:27]
	v_mfma_f32_16x16x32_bf16 v[12:15], v[166:169], v[206:209], v[12:15]
	v_mfma_f32_16x16x32_bf16 v[8:11], v[174:177], v[206:209], v[8:11]
	v_mfma_f32_16x16x32_bf16 v[60:63], v[170:173], v[186:189], v[60:63]
	v_mfma_f32_16x16x32_bf16 v[56:59], v[178:181], v[186:189], v[56:59]
	v_mfma_f32_16x16x32_bf16 v[44:47], v[170:173], v[194:197], v[44:47]
	v_mfma_f32_16x16x32_bf16 v[40:43], v[178:181], v[194:197], v[40:43]
	v_mfma_f32_16x16x32_bf16 v[28:31], v[170:173], v[202:205], v[28:31]
	v_mfma_f32_16x16x32_bf16 v[24:27], v[178:181], v[202:205], v[24:27]
	v_mfma_f32_16x16x32_bf16 v[12:15], v[170:173], v[210:213], v[12:15]
	v_mfma_f32_16x16x32_bf16 v[8:11], v[178:181], v[210:213], v[8:11]
	s_setprio 0
	s_barrier
; #define PG8_STAGE(bufoff, gbase, voff) do { _Pragma("unroll") for (int _i = 0; _i < 2; ++_i) \
;         __builtin_amdgcn_global_load_lds((const unsigned*)((const char*)(gbase) + (voff)[_i]), (LAS unsigned*)(lds + (bufoff) + ldsw + _i * 8192), 16, 0, 0); } while (0)
; #define PG8_LDA(dst, b, h) do { _Pragma("unroll") for (int m = 0; m < 4; ++m) _Pragma("unroll") for (int k = 0; k < 2; ++k) dst[m][k] = *(const LAS bf16x8*)(lds + PG8_SA(b, h) + aoff + m * 2048 + k * 1024); } while (0)
; #define PG8_LDB(dst, b, h) do { _Pragma("unroll") for (int n = 0; n < 2; ++n) _Pragma("unroll") for (int k = 0; k < 2; ++k) dst[n][k] = *(const LAS bf16x8*)(lds + PG8_SB(b, h) + boff + n * 2048 + k * 1024); } while (0)
; #define PG8_MMA(ai, bj, At, Bt) do { __builtin_amdgcn_s_setprio(1); _Pragma("unroll") for (int m = 0; m < 4; ++m) _Pragma("unroll") for (int n = 0; n < 2; ++n) _Pragma("unroll") for (int k = 0; k < 2; ++k) \
;         acc[ai][bj][m][n] = __builtin_amdgcn_mfma_f32_16x16x32_bf16(Bt[n][k], At[m][k], acc[ai][bj][m][n], 0, 0, 0); __builtin_amdgcn_s_setprio(0); } while (0)
; #define PG8_WAIT_V(n) asm volatile("s_waitcnt vmcnt(" #n ")" ::: "memory")
; #define PG8_WAIT_L(n) asm volatile("s_waitcnt lgkmcnt(" #n ")" ::: "memory")
; #define PG8_BAR __builtin_amdgcn_s_barrier()
; #define PG8_SCHED __builtin_amdgcn_sched_barrier(0)
; template <class Epi>
; __device__ __forceinline__ void gemm_phase(LAS unsigned char* lds, const GSched& S, const int K, const int lda, const int ldb, const Epi& E) {
;     ...
;             PG8_STAGE(PG8_SB(0, 1), b2 + hstepB, voffB);
;             PG8_WAIT_V(6); PG8_BAR; if constexpr (!Epi::NARROW) PG8_MMA(1, 1, At, B1); PG8_BAR;
;             PG8_LDB(B0, 1, 0); PG8_SCHED; PG8_LDA(At, 1, 0); PG8_STAGE(PG8_SA(0, 1), a2 + hstepA, voffA);
;             PG8_WAIT_L(8); PG8_BAR; PG8_WAIT_L(0); PG8_MMA(0, 0, At, B0); PG8_BAR; PG8_SCHED;
;             if constexpr (!Epi::NARROW) PG8_LDB(B1, 1, 1); PG8_STAGE(PG8_SB(1, 0), b3, voffB);
;             PG8_BAR; PG8_WAIT_L(0); if constexpr (!Epi::NARROW) PG8_MMA(0, 1, At, B1); PG8_BAR;
;             PG8_LDA(At, 1, 1); PG8_STAGE(PG8_SA(1, 0), a3, voffA);
;             PG8_BAR; PG8_WAIT_L(0); PG8_MMA(1, 0, At, B0); PG8_BAR; PG8_SCHED;
;             PG8_STAGE(PG8_SB(1, 1), b3 + hstepB, voffB);
	s_add_u32 s30, s36, 0x84000
	s_addc_u32 s31, s37, 0
	s_add_i32 s65, s59, s44
	v_lshl_add_u64 v[166:167], s[30:31], 0, v[130:131]
	s_mov_b32 m0, s65
	s_nop 0
	global_load_lds_dwordx4 v[166:167], off
	v_lshl_add_u64 v[166:167], s[30:31], 0, v[134:135]
	s_add_i32 m0, s65, 0x2000
	s_nop 0
	global_load_lds_dwordx4 v[166:167], off
	s_waitcnt vmcnt(6)
	s_barrier
	s_setprio 1
	v_mfma_f32_16x16x32_bf16 v[52:55], v[214:217], v[182:185], v[52:55]
	v_mfma_f32_16x16x32_bf16 v[48:51], v[222:225], v[182:185], v[48:51]
	v_mfma_f32_16x16x32_bf16 v[36:39], v[214:217], v[190:193], v[36:39]
	v_mfma_f32_16x16x32_bf16 v[32:35], v[222:225], v[190:193], v[32:35]
	v_mfma_f32_16x16x32_bf16 v[20:23], v[214:217], v[198:201], v[20:23]
	v_mfma_f32_16x16x32_bf16 v[16:19], v[222:225], v[198:201], v[16:19]
	v_mfma_f32_16x16x32_bf16 v[4:7], v[214:217], v[206:209], v[4:7]
	v_mfma_f32_16x16x32_bf16 v[0:3], v[222:225], v[206:209], v[0:3]
	v_mfma_f32_16x16x32_bf16 v[52:55], v[218:221], v[186:189], v[52:55]
	v_mfma_f32_16x16x32_bf16 v[48:51], v[226:229], v[186:189], v[48:51]
	v_mfma_f32_16x16x32_bf16 v[36:39], v[218:221], v[194:197], v[36:39]
	v_mfma_f32_16x16x32_bf16 v[32:35], v[226:229], v[194:197], v[32:35]
	v_mfma_f32_16x16x32_bf16 v[20:23], v[218:221], v[202:205], v[20:23]
	v_mfma_f32_16x16x32_bf16 v[16:19], v[226:229], v[202:205], v[16:19]
	v_mfma_f32_16x16x32_bf16 v[4:7], v[218:221], v[210:213], v[4:7]
	v_mfma_f32_16x16x32_bf16 v[0:3], v[226:229], v[210:213], v[0:3]
	s_setprio 0
	s_add_i32 s65, 0, 0x18000
	v_add_u32_e32 v165, s65, v152
	s_barrier
	ds_read_b128 v[166:169], v165
	ds_read_b128 v[170:173], v165 offset:1024
	ds_read_b128 v[174:177], v165 offset:2048
	ds_read_b128 v[178:181], v165 offset:3072
	s_add_u32 s30, s38, 0x94000
	s_addc_u32 s31, s39, 0
	s_mov_b32 m0, s47
	v_lshl_add_u64 v[214:215], s[30:31], 0, v[128:129]
	ds_read_b128 v[182:185], v155 offset:32768
	ds_read_b128 v[186:189], v155 offset:33792
	ds_read_b128 v[190:193], v155 offset:34816
	ds_read_b128 v[194:197], v155 offset:35840
	ds_read_b128 v[198:201], v155 offset:36864
	ds_read_b128 v[202:205], v155 offset:37888
	ds_read_b128 v[206:209], v155 offset:38912
	ds_read_b128 v[210:213], v155 offset:39936
	global_load_lds_dwordx4 v[214:215], off
	v_lshl_add_u64 v[214:215], s[30:31], 0, v[132:133]
	s_mov_b32 m0, s48
	s_nop 0
	global_load_lds_dwordx4 v[214:215], off
	s_waitcnt lgkmcnt(8)
	s_barrier
	s_waitcnt lgkmcnt(0)
	s_setprio 1
	s_waitcnt lgkmcnt(0)
	v_mfma_f32_16x16x32_bf16 v[124:127], v[166:169], v[182:185], v[124:127]
	v_mfma_f32_16x16x32_bf16 v[120:123], v[174:177], v[182:185], v[120:123]
	v_mfma_f32_16x16x32_bf16 v[108:111], v[166:169], v[190:193], v[108:111]
	v_mfma_f32_16x16x32_bf16 v[104:107], v[174:177], v[190:193], v[104:107]
	v_mfma_f32_16x16x32_bf16 v[92:95], v[166:169], v[198:201], v[92:95]
	v_mfma_f32_16x16x32_bf16 v[88:91], v[174:177], v[198:201], v[88:91]
	v_mfma_f32_16x16x32_bf16 v[76:79], v[166:169], v[206:209], v[76:79]
	v_mfma_f32_16x16x32_bf16 v[72:75], v[174:177], v[206:209], v[72:75]
	v_mfma_f32_16x16x32_bf16 v[124:127], v[170:173], v[186:189], v[124:127]
	v_mfma_f32_16x16x32_bf16 v[120:123], v[178:181], v[186:189], v[120:123]
	v_mfma_f32_16x16x32_bf16 v[108:111], v[170:173], v[194:197], v[108:111]
	v_mfma_f32_16x16x32_bf16 v[104:107], v[178:181], v[194:197], v[104:107]
	v_mfma_f32_16x16x32_bf16 v[92:95], v[170:173], v[202:205], v[92:95]
	v_mfma_f32_16x16x32_bf16 v[88:91], v[178:181], v[202:205], v[88:91]
	v_mfma_f32_16x16x32_bf16 v[76:79], v[170:173], v[210:213], v[76:79]
	v_mfma_f32_16x16x32_bf16 v[72:75], v[178:181], v[210:213], v[72:75]
	s_setprio 0
	s_barrier
	s_add_i32 s38, 0, 0x1c000
	s_add_i32 s30, s65, s44
	v_add_u32_e32 v165, s38, v152
	v_lshl_add_u64 v[146:147], v[146:147], 0, s[26:27]
	s_mov_b32 m0, s30
	ds_read_b128 v[214:217], v165
	ds_read_b128 v[218:221], v165 offset:1024
	ds_read_b128 v[222:225], v165 offset:2048
	ds_read_b128 v[226:229], v165 offset:3072
	global_load_lds_dwordx4 v[146:147], off
	v_lshl_add_u64 v[146:147], v[230:231], 0, s[26:27]
	s_add_i32 m0, s30, 0x2000
	s_nop 0
	global_load_lds_dwordx4 v[146:147], off
	s_barrier
	s_waitcnt lgkmcnt(0)
	s_setprio 1
	s_waitcnt lgkmcnt(0)
	v_mfma_f32_16x16x32_bf16 v[116:119], v[214:217], v[182:185], v[116:119]
	v_mfma_f32_16x16x32_bf16 v[112:115], v[222:225], v[182:185], v[112:115]
	v_mfma_f32_16x16x32_bf16 v[100:103], v[214:217], v[190:193], v[100:103]
	v_mfma_f32_16x16x32_bf16 v[96:99], v[222:225], v[190:193], v[96:99]
	v_mfma_f32_16x16x32_bf16 v[84:87], v[214:217], v[198:201], v[84:87]
	v_mfma_f32_16x16x32_bf16 v[80:83], v[222:225], v[198:201], v[80:83]
	v_mfma_f32_16x16x32_bf16 v[68:71], v[214:217], v[206:209], v[68:71]
	v_mfma_f32_16x16x32_bf16 v[64:67], v[222:225], v[206:209], v[64:67]
	v_mfma_f32_16x16x32_bf16 v[116:119], v[218:221], v[186:189], v[116:119]
	v_mfma_f32_16x16x32_bf16 v[112:115], v[226:229], v[186:189], v[112:115]
	v_mfma_f32_16x16x32_bf16 v[100:103], v[218:221], v[194:197], v[100:103]
	v_mfma_f32_16x16x32_bf16 v[96:99], v[226:229], v[194:197], v[96:99]
	v_mfma_f32_16x16x32_bf16 v[84:87], v[218:221], v[202:205], v[84:87]
	v_mfma_f32_16x16x32_bf16 v[80:83], v[226:229], v[202:205], v[80:83]
	v_mfma_f32_16x16x32_bf16 v[68:71], v[218:221], v[210:213], v[68:71]
	v_mfma_f32_16x16x32_bf16 v[64:67], v[226:229], v[210:213], v[64:67]
	s_setprio 0
	s_mov_b32 m0, s53
	v_lshl_add_u64 v[146:147], v[234:235], 0, s[26:27]
	s_barrier
	ds_read_b128 v[182:185], v155 offset:49152
	ds_read_b128 v[186:189], v155 offset:50176
	ds_read_b128 v[190:193], v155 offset:51200
	ds_read_b128 v[194:197], v155 offset:52224
	ds_read_b128 v[198:201], v155 offset:53248
	ds_read_b128 v[202:205], v155 offset:54272
	ds_read_b128 v[206:209], v155 offset:55296
	ds_read_b128 v[210:213], v155 offset:56320
	global_load_lds_dwordx4 v[146:147], off
	v_lshl_add_u64 v[146:147], v[236:237], 0, s[26:27]
	s_mov_b32 m0, s54
	s_nop 0
	global_load_lds_dwordx4 v[146:147], off
	s_barrier
; __device__ __forceinline__ void st_nt(float* p, f32x4 v) { __builtin_nontemporal_store(v, (f32x4*)p); }
; __device__ __forceinline__ void st_nt(bf16_t* p, u32x4 v) { __builtin_nontemporal_store(v, (u32x4*)p); }
; __device__ __forceinline__ u32x4 pack8(const f32x4 a, const f32x4 b) { u32x4 w; w.x = cvt_pk_bf16(a[0], a[1]); w.y = cvt_pk_bf16(a[2], a[3]); w.z = cvt_pk_bf16(b[0], b[1]); w.w = cvt_pk_bf16(b[2], b[3]); return w; }
; #define PG8_WAIT_V(n) asm volatile("s_waitcnt vmcnt(" #n ")" ::: "memory")
; #define PG8_WAIT_L(n) asm volatile("s_waitcnt lgkmcnt(" #n ")" ::: "memory")
; #define PG8_BAR __builtin_amdgcn_s_barrier()
; #define PG8_SCHED __builtin_amdgcn_sched_barrier(0)
;     __device__ __forceinline__ void operator()(Acc& acc, const Unit& u, int wr, int wc, int fr, int fq, const float (&rsv)[8]) const {
;         const int row0 = u.pm * BM + wr * 64 + fr, col = u.pn * HALF + wc * 32 + 8 * fq;
; #pragma unroll
;         for (int ai = 0; ai < 2; ++ai)
; #pragma unroll
;             for (int m = 0; m < 4; ++m) {
;                 const int row = row0 + ai * HALF + m * 16; const float rs = rsv[ai * 4 + m];
;                 f32x4 r0, r1, b0, b1;
; #pragma unroll
;                 for (int jj = 0; jj < 4; ++jj) {
;                     const float rsn = rs * -1.4426950408889634f;
;                     const float da0 = 1.0f + __builtin_amdgcn_exp2f(acc[ai][0][m][0][jj] * rsn), da1 = 1.0f + __builtin_amdgcn_exp2f(acc[ai][0][m][1][jj] * rsn);
;                     const float db0 = 1.0f + __builtin_amdgcn_exp2f(acc[ai][1][m][0][jj] * rsn), db1 = 1.0f + __builtin_amdgcn_exp2f(acc[ai][1][m][1][jj] * rsn);
;                     b0[jj] = __builtin_amdgcn_rcpf(db0); b1[jj] = __builtin_amdgcn_rcpf(db1);
;                     r0[jj] = db0 * __builtin_amdgcn_rcpf(da0); r1[jj] = db1 * __builtin_amdgcn_rcpf(da1); }
;                 st_nt(gates + (size_t)row * 4096 + col, pack8(r0, r1));
;                 st_nt(gates + (size_t)row * 4096 + 2048 + col, pack8(b0, b1));
; template <class Epi>
; __device__ __forceinline__ void gemm_phase(LAS unsigned char* lds, const GSched& S, const int K, const int lda, const int ldb, const Epi& E) {
;     ...
;             PG8_BAR; PG8_WAIT_L(0); PG8_MMA(1, 0, At, B0); PG8_BAR; PG8_SCHED;
;             PG8_STAGE(PG8_SB(1, 1), b3 + hstepB, voffB);
;             PG8_WAIT_V(6); PG8_BAR; if constexpr (!Epi::NARROW) PG8_MMA(1, 1, At, B1); PG8_BAR;
	s_waitcnt lgkmcnt(0)
	s_setprio 1
	v_mfma_f32_16x16x32_bf16 v[60:63], v[166:169], v[182:185], v[60:63]
	v_mfma_f32_16x16x32_bf16 v[56:59], v[174:177], v[182:185], v[56:59]
	v_mfma_f32_16x16x32_bf16 v[44:47], v[166:169], v[190:193], v[44:47]
	v_mfma_f32_16x16x32_bf16 v[40:43], v[174:177], v[190:193], v[40:43]
	v_mfma_f32_16x16x32_bf16 v[28:31], v[166:169], v[198:201], v[28:31]
	v_mfma_f32_16x16x32_bf16 v[24:27], v[174:177], v[198:201], v[24:27]
	v_mfma_f32_16x16x32_bf16 v[12:15], v[166:169], v[206:209], v[12:15]
	v_mfma_f32_16x16x32_bf16 v[8:11], v[174:177], v[206:209], v[8:11]
	v_mfma_f32_16x16x32_bf16 v[60:63], v[170:173], v[186:189], v[60:63]
	v_mfma_f32_16x16x32_bf16 v[56:59], v[178:181], v[186:189], v[56:59]
	v_mfma_f32_16x16x32_bf16 v[44:47], v[170:173], v[194:197], v[44:47]
	v_mfma_f32_16x16x32_bf16 v[40:43], v[178:181], v[194:197], v[40:43]
	v_mfma_f32_16x16x32_bf16 v[28:31], v[170:173], v[202:205], v[28:31]
	v_mfma_f32_16x16x32_bf16 v[24:27], v[178:181], v[202:205], v[24:27]
	v_mfma_f32_16x16x32_bf16 v[12:15], v[170:173], v[210:213], v[12:15]
	v_mfma_f32_16x16x32_bf16 v[8:11], v[178:181], v[210:213], v[8:11]
	s_setprio 0
	s_barrier
	s_add_u32 s30, s36, 0x84080
	s_addc_u32 s31, s37, 0
	s_add_i32 s36, s38, s44
	v_lshl_add_u64 v[146:147], s[30:31], 0, v[130:131]
	s_mov_b32 m0, s36
	s_nop 0
	global_load_lds_dwordx4 v[146:147], off
	v_lshl_add_u64 v[146:147], s[30:31], 0, v[134:135]
	s_add_i32 m0, s36, 0x2000
	s_nop 0
	global_load_lds_dwordx4 v[146:147], off
	s_waitcnt vmcnt(6)
	s_barrier
	s_setprio 1
	v_mfma_f32_16x16x32_bf16 v[52:55], v[214:217], v[182:185], v[52:55]
	v_mfma_f32_16x16x32_bf16 v[48:51], v[222:225], v[182:185], v[48:51]
	v_mfma_f32_16x16x32_bf16 v[36:39], v[214:217], v[190:193], v[36:39]
	v_mfma_f32_16x16x32_bf16 v[32:35], v[222:225], v[190:193], v[32:35]
	v_mfma_f32_16x16x32_bf16 v[20:23], v[214:217], v[198:201], v[20:23]
	v_mfma_f32_16x16x32_bf16 v[16:19], v[222:225], v[198:201], v[16:19]
	v_mfma_f32_16x16x32_bf16 v[4:7], v[214:217], v[206:209], v[4:7]
	v_mfma_f32_16x16x32_bf16 v[0:3], v[222:225], v[206:209], v[0:3]
	v_mfma_f32_16x16x32_bf16 v[52:55], v[218:221], v[186:189], v[52:55]
	v_mfma_f32_16x16x32_bf16 v[48:51], v[226:229], v[186:189], v[48:51]
	v_mfma_f32_16x16x32_bf16 v[36:39], v[218:221], v[194:197], v[36:39]
	v_mfma_f32_16x16x32_bf16 v[32:35], v[226:229], v[194:197], v[32:35]
	v_mfma_f32_16x16x32_bf16 v[20:23], v[218:221], v[202:205], v[20:23]
	v_mfma_f32_16x16x32_bf16 v[16:19], v[226:229], v[202:205], v[16:19]
	v_mfma_f32_16x16x32_bf16 v[4:7], v[218:221], v[210:213], v[4:7]
	v_mfma_f32_16x16x32_bf16 v[0:3], v[226:229], v[210:213], v[0:3]
	s_setprio 0
	s_add_i32 s64, s64, 2
	s_add_u32 s4, s4, 0x100
	s_addc_u32 s5, s5, 0
	s_cmp_gt_u32 s64, 29
	s_mov_b64 s[30:31], s[34:35]
	s_barrier
	s_cbranch_scc0 .LBB0_769
	v_mul_f32_e32 v147, 0xbfb8aa3b, v157
	v_mul_f32_e32 v120, v147, v120
	v_exp_f32_e32 v120, v120
	v_mul_f32_e32 v124, v147, v124
	v_exp_f32_e32 v124, v124
	v_mul_f32_e32 v116, v147, v116
	v_add_f32_e32 v165, 1.0, v120
	v_mul_f32_e32 v120, v147, v125
	v_exp_f32_e32 v125, v120
	v_mul_f32_e32 v120, v147, v121
	v_exp_f32_e32 v121, v120
	v_mul_f32_e32 v117, v147, v117
	v_add_f32_e32 v124, 1.0, v124
	v_exp_f32_e32 v116, v116
	v_add_f32_e32 v125, 1.0, v125
	v_exp_f32_e32 v117, v117
	v_rcp_f32_e32 v120, v124
	v_rcp_f32_e32 v124, v165
	v_add_f32_e32 v165, 1.0, v121
	v_rcp_f32_e32 v121, v125
	v_mul_f32_e32 v112, v147, v112
	v_mul_f32_e32 v113, v147, v113
	v_pk_add_f32 v[116:117], v[116:117], 1.0 op_sel_hi:[1,0]
	v_exp_f32_e32 v112, v112
	v_exp_f32_e32 v113, v113
	v_rcp_f32_e32 v168, v116
	v_pk_mul_f32 v[120:121], v[120:121], v[116:117]
	v_mul_f32_e32 v116, v147, v126
	v_rcp_f32_e32 v125, v165
	v_exp_f32_e32 v116, v116
	v_rcp_f32_e32 v169, v117
	v_pk_add_f32 v[112:113], v[112:113], 1.0 op_sel_hi:[1,0]
	v_mul_f32_e32 v117, v147, v122
	v_exp_f32_e32 v117, v117
	v_pk_mul_f32 v[124:125], v[124:125], v[112:113]
	v_rcp_f32_e32 v170, v113
	v_add_f32_e32 v113, 1.0, v116
	v_mul_f32_e32 v116, v147, v127
	v_exp_f32_e32 v122, v116
	v_mul_f32_e32 v116, v147, v123
	v_exp_f32_e32 v123, v116
	v_rcp_f32_e32 v165, v112
	v_add_f32_e32 v117, 1.0, v117
	v_mul_f32_e32 v112, v147, v118
	v_rcp_f32_e32 v116, v113
	v_mul_f32_e32 v113, v147, v119
	v_exp_f32_e32 v112, v112
	v_rcp_f32_e32 v118, v117
	v_add_f32_e32 v117, 1.0, v122
	v_exp_f32_e32 v113, v113
	v_mul_f32_e32 v114, v147, v114
	v_mul_f32_e32 v115, v147, v115
	v_rcp_f32_e32 v117, v117
	v_exp_f32_e32 v114, v114
	v_add_f32_e32 v126, 1.0, v123
	v_exp_f32_e32 v115, v115
	v_rcp_f32_e32 v119, v126
	v_pk_add_f32 v[112:113], v[112:113], 1.0 op_sel_hi:[1,0]
	v_lshl_add_u32 v146, s55, 8, v151
	v_pk_mul_f32 v[122:123], v[116:117], v[112:113]
	v_lshl_or_b32 v166, s2, 7, v153
	v_rcp_f32_e32 v171, v112
	v_rcp_f32_e32 v172, v113
	v_pk_add_f32 v[112:113], v[114:115], 1.0 op_sel_hi:[1,0]
	v_ashrrev_i32_e32 v147, 31, v146
	v_cvt_pk_bf16_f32 v117, v122, v123
	v_mul_f32_e32 v122, 0xbfb8aa3b, v158
	v_ashrrev_i32_e32 v167, 31, v166
	v_rcp_f32_e32 v173, v112
	v_pk_mul_f32 v[126:127], v[118:119], v[112:113]
	v_rcp_f32_e32 v174, v113
	v_lshlrev_b64 v[112:113], 13, v[146:147]
	v_mul_f32_e32 v104, v122, v104
	v_lshl_add_u64 v[112:113], s[24:25], 0, v[112:113]
	v_lshlrev_b64 v[114:115], 1, v[166:167]
	v_exp_f32_e32 v104, v104
	v_lshl_add_u64 v[112:113], v[112:113], 0, v[114:115]
	v_cvt_pk_bf16_f32 v116, v120, v121
	v_cvt_pk_bf16_f32 v118, v124, v125
	v_cvt_pk_bf16_f32 v119, v126, v127
	v_add_co_u32_e32 v120, vcc, s50, v112
	global_store_dwordx4 v[112:113], v[116:119], off
	s_nop 0
	v_addc_co_u32_e32 v121, vcc, 0, v113, vcc
	v_cvt_pk_bf16_f32 v116, v168, v169
	v_cvt_pk_bf16_f32 v117, v171, v172
; __device__ __forceinline__ void st_nt(float* p, f32x4 v) { __builtin_nontemporal_store(v, (f32x4*)p); }
; __device__ __forceinline__ void st_nt(bf16_t* p, u32x4 v) { __builtin_nontemporal_store(v, (u32x4*)p); }
; __device__ __forceinline__ u32x4 pack8(const f32x4 a, const f32x4 b) { u32x4 w; w.x = cvt_pk_bf16(a[0], a[1]); w.y = cvt_pk_bf16(a[2], a[3]); w.z = cvt_pk_bf16(b[0], b[1]); w.w = cvt_pk_bf16(b[2], b[3]); return w; }
;     __device__ __forceinline__ void operator()(Acc& acc, const Unit& u, int wr, int wc, int fr, int fq, const float (&rsv)[8]) const {
;         const int row0 = u.pm * BM + wr * 64 + fr, col = u.pn * HALF + wc * 32 + 8 * fq;
; #pragma unroll
;         for (int ai = 0; ai < 2; ++ai)
; #pragma unroll
;             for (int m = 0; m < 4; ++m) {
;                 const int row = row0 + ai * HALF + m * 16; const float rs = rsv[ai * 4 + m];
;                 f32x4 r0, r1, b0, b1;
; #pragma unroll
;                 for (int jj = 0; jj < 4; ++jj) {
;                     const float rsn = rs * -1.4426950408889634f;
;                     const float da0 = 1.0f + __builtin_amdgcn_exp2f(acc[ai][0][m][0][jj] * rsn), da1 = 1.0f + __builtin_amdgcn_exp2f(acc[ai][0][m][1][jj] * rsn);
;                     const float db0 = 1.0f + __builtin_amdgcn_exp2f(acc[ai][1][m][0][jj] * rsn), db1 = 1.0f + __builtin_amdgcn_exp2f(acc[ai][1][m][1][jj] * rsn);
;                     b0[jj] = __builtin_amdgcn_rcpf(db0); b1[jj] = __builtin_amdgcn_rcpf(db1);
;                     r0[jj] = db0 * __builtin_amdgcn_rcpf(da0); r1[jj] = db1 * __builtin_amdgcn_rcpf(da1); }
;                 st_nt(gates + (size_t)row * 4096 + col, pack8(r0, r1));
;                 st_nt(gates + (size_t)row * 4096 + 2048 + col, pack8(b0, b1));
	v_cvt_pk_bf16_f32 v118, v165, v170
	v_cvt_pk_bf16_f32 v119, v173, v174
	v_mul_f32_e32 v108, v122, v108
	global_store_dwordx4 v[120:121], v[116:119], off
	v_exp_f32_e32 v108, v108
	v_mul_f32_e32 v100, v122, v100
	v_add_f32_e32 v116, 1.0, v104
	v_mul_f32_e32 v104, v122, v109
	v_exp_f32_e32 v109, v104
	v_mul_f32_e32 v104, v122, v105
	v_exp_f32_e32 v105, v104
	v_mul_f32_e32 v101, v122, v101
	v_add_f32_e32 v108, 1.0, v108
	v_exp_f32_e32 v100, v100
	v_add_f32_e32 v109, 1.0, v109
	v_exp_f32_e32 v101, v101
	v_mul_f32_e32 v96, v122, v96
	v_rcp_f32_e32 v104, v108
	v_rcp_f32_e32 v108, v116
	v_add_f32_e32 v116, 1.0, v105
	v_mul_f32_e32 v97, v122, v97
	v_rcp_f32_e32 v105, v109
	v_exp_f32_e32 v96, v96
	v_exp_f32_e32 v97, v97
	v_rcp_f32_e32 v109, v116
	v_pk_add_f32 v[100:101], v[100:101], 1.0 op_sel_hi:[1,0]
	v_mul_f32_e32 v98, v122, v98
	v_rcp_f32_e32 v117, v100
	v_pk_mul_f32 v[104:105], v[104:105], v[100:101]
	v_mul_f32_e32 v100, v122, v110
	v_pk_add_f32 v[96:97], v[96:97], 1.0 op_sel_hi:[1,0]
	v_exp_f32_e32 v110, v100
	v_mul_f32_e32 v100, v122, v106
	v_rcp_f32_e32 v118, v101
	v_rcp_f32_e32 v116, v96
	v_exp_f32_e32 v106, v100
	v_pk_mul_f32 v[100:101], v[108:109], v[96:97]
	v_mul_f32_e32 v96, v122, v102
	v_mul_f32_e32 v102, v122, v111
	v_exp_f32_e32 v108, v102
	v_mul_f32_e32 v102, v122, v107
	v_exp_f32_e32 v107, v102
	v_rcp_f32_e32 v119, v97
	v_add_f32_e32 v97, 1.0, v110
	v_rcp_f32_e32 v102, v97
	v_mul_f32_e32 v97, v122, v103
	v_exp_f32_e32 v96, v96
	v_add_f32_e32 v108, 1.0, v108
	v_exp_f32_e32 v97, v97
	v_mul_f32_e32 v99, v122, v99
	v_add_f32_e32 v106, 1.0, v106
	v_exp_f32_e32 v98, v98
	v_add_f32_e32 v107, 1.0, v107
	v_rcp_f32_e32 v103, v108
	v_exp_f32_e32 v99, v99
	v_rcp_f32_e32 v106, v106
	v_rcp_f32_e32 v107, v107
	v_pk_add_f32 v[96:97], v[96:97], 1.0 op_sel_hi:[1,0]
	s_mov_b64 s[30:31], -1
	v_rcp_f32_e32 v110, v96
	v_pk_mul_f32 v[102:103], v[102:103], v[96:97]
	v_rcp_f32_e32 v111, v97
	v_pk_add_f32 v[96:97], v[98:99], 1.0 op_sel_hi:[1,0]
	v_cvt_pk_bf16_f32 v98, v100, v101
	v_rcp_f32_e32 v120, v96
	v_pk_mul_f32 v[106:107], v[106:107], v[96:97]
	v_or_b32_e32 v96, 16, v146
	v_rcp_f32_e32 v121, v97
	v_ashrrev_i32_e32 v97, 31, v96
	v_lshlrev_b64 v[96:97], 13, v[96:97]
	v_lshl_add_u64 v[96:97], s[24:25], 0, v[96:97]
	v_lshl_add_u64 v[108:109], v[96:97], 0, v[114:115]
	v_cvt_pk_bf16_f32 v97, v102, v103
	v_mul_f32_e32 v102, 0xbfb8aa3b, v159
	v_mul_f32_e32 v88, v102, v88
	v_exp_f32_e32 v88, v88
	v_cvt_pk_bf16_f32 v96, v104, v105
	v_cvt_pk_bf16_f32 v99, v106, v107
	v_add_co_u32_e32 v100, vcc, s50, v108
	global_store_dwordx4 v[108:109], v[96:99], off
	s_nop 0
	v_addc_co_u32_e32 v101, vcc, 0, v109, vcc
	v_cvt_pk_bf16_f32 v96, v117, v118
	v_cvt_pk_bf16_f32 v97, v110, v111
	v_cvt_pk_bf16_f32 v98, v116, v119
	v_cvt_pk_bf16_f32 v99, v120, v121
	v_mul_f32_e32 v92, v102, v92
	global_store_dwordx4 v[100:101], v[96:99], off
	v_exp_f32_e32 v92, v92
	v_mul_f32_e32 v84, v102, v84
	v_add_f32_e32 v96, 1.0, v88
	v_mul_f32_e32 v88, v102, v93
	v_exp_f32_e32 v93, v88
	v_mul_f32_e32 v88, v102, v89
	v_exp_f32_e32 v89, v88
	v_mul_f32_e32 v85, v102, v85
	v_add_f32_e32 v92, 1.0, v92
	v_exp_f32_e32 v84, v84
	v_add_f32_e32 v93, 1.0, v93
	v_exp_f32_e32 v85, v85
	v_mul_f32_e32 v80, v102, v80
	v_rcp_f32_e32 v88, v92
	v_rcp_f32_e32 v92, v96
	v_add_f32_e32 v96, 1.0, v89
	v_mul_f32_e32 v81, v102, v81
	v_rcp_f32_e32 v89, v93
	v_exp_f32_e32 v80, v80
	v_exp_f32_e32 v81, v81
	v_rcp_f32_e32 v93, v96
	v_pk_add_f32 v[84:85], v[84:85], 1.0 op_sel_hi:[1,0]
	v_mul_f32_e32 v82, v102, v82
	v_rcp_f32_e32 v97, v84
	v_pk_mul_f32 v[88:89], v[88:89], v[84:85]
	v_mul_f32_e32 v84, v102, v94
	v_pk_add_f32 v[80:81], v[80:81], 1.0 op_sel_hi:[1,0]
	v_exp_f32_e32 v94, v84
	v_mul_f32_e32 v84, v102, v90
	v_rcp_f32_e32 v98, v85
	v_rcp_f32_e32 v96, v80
	v_exp_f32_e32 v90, v84
	v_pk_mul_f32 v[84:85], v[92:93], v[80:81]
	v_mul_f32_e32 v80, v102, v86
	v_mul_f32_e32 v86, v102, v95
	v_exp_f32_e32 v92, v86
	v_mul_f32_e32 v86, v102, v91
	v_exp_f32_e32 v91, v86
	v_rcp_f32_e32 v99, v81
	v_add_f32_e32 v81, 1.0, v94
	v_rcp_f32_e32 v86, v81
	v_mul_f32_e32 v81, v102, v87
	v_exp_f32_e32 v80, v80
	v_add_f32_e32 v92, 1.0, v92
	v_exp_f32_e32 v81, v81
	v_mul_f32_e32 v83, v102, v83
	v_add_f32_e32 v90, 1.0, v90
	v_exp_f32_e32 v82, v82
	v_add_f32_e32 v91, 1.0, v91
	v_rcp_f32_e32 v87, v92
	v_exp_f32_e32 v83, v83
	v_rcp_f32_e32 v90, v90
	v_rcp_f32_e32 v91, v91
	v_pk_add_f32 v[80:81], v[80:81], 1.0 op_sel_hi:[1,0]
	s_nop 0
	v_rcp_f32_e32 v94, v80
	v_pk_mul_f32 v[86:87], v[86:87], v[80:81]
	v_rcp_f32_e32 v95, v81
	v_pk_add_f32 v[80:81], v[82:83], 1.0 op_sel_hi:[1,0]
	v_cvt_pk_bf16_f32 v82, v84, v85
	v_rcp_f32_e32 v100, v80
	v_pk_mul_f32 v[90:91], v[90:91], v[80:81]
	v_or_b32_e32 v80, 32, v146
	v_rcp_f32_e32 v101, v81
	v_ashrrev_i32_e32 v81, 31, v80
	v_lshlrev_b64 v[80:81], 13, v[80:81]
	v_lshl_add_u64 v[80:81], s[24:25], 0, v[80:81]
	v_lshl_add_u64 v[92:93], v[80:81], 0, v[114:115]
	v_cvt_pk_bf16_f32 v81, v86, v87
	v_mul_f32_e32 v86, 0xbfb8aa3b, v160
	v_mul_f32_e32 v72, v86, v72
	v_exp_f32_e32 v72, v72
	v_cvt_pk_bf16_f32 v80, v88, v89
	v_cvt_pk_bf16_f32 v83, v90, v91
	v_add_co_u32_e32 v84, vcc, s50, v92
	global_store_dwordx4 v[92:93], v[80:83], off
	s_nop 0
	v_addc_co_u32_e32 v85, vcc, 0, v93, vcc
	v_cvt_pk_bf16_f32 v80, v97, v98
	v_cvt_pk_bf16_f32 v81, v94, v95
	v_cvt_pk_bf16_f32 v82, v96, v99
	v_cvt_pk_bf16_f32 v83, v100, v101
	v_mul_f32_e32 v76, v86, v76
	global_store_dwordx4 v[84:85], v[80:83], off
	v_exp_f32_e32 v76, v76
	v_mul_f32_e32 v68, v86, v68
	v_add_f32_e32 v80, 1.0, v72
	v_mul_f32_e32 v72, v86, v77
	v_exp_f32_e32 v77, v72
	v_mul_f32_e32 v72, v86, v73
	v_exp_f32_e32 v73, v72
	v_mul_f32_e32 v69, v86, v69
	v_add_f32_e32 v76, 1.0, v76
; __device__ __forceinline__ void st_nt(float* p, f32x4 v) { __builtin_nontemporal_store(v, (f32x4*)p); }
; __device__ __forceinline__ void st_nt(bf16_t* p, u32x4 v) { __builtin_nontemporal_store(v, (u32x4*)p); }
; __device__ __forceinline__ u32x4 pack8(const f32x4 a, const f32x4 b) { u32x4 w; w.x = cvt_pk_bf16(a[0], a[1]); w.y = cvt_pk_bf16(a[2], a[3]); w.z = cvt_pk_bf16(b[0], b[1]); w.w = cvt_pk_bf16(b[2], b[3]); return w; }
;     __device__ __forceinline__ void operator()(Acc& acc, const Unit& u, int wr, int wc, int fr, int fq, const float (&rsv)[8]) const {
;         const int row0 = u.pm * BM + wr * 64 + fr, col = u.pn * HALF + wc * 32 + 8 * fq;
; #pragma unroll
;         for (int ai = 0; ai < 2; ++ai)
; #pragma unroll
;             for (int m = 0; m < 4; ++m) {
;                 const int row = row0 + ai * HALF + m * 16; const float rs = rsv[ai * 4 + m];
;                 f32x4 r0, r1, b0, b1;
; #pragma unroll
;                 for (int jj = 0; jj < 4; ++jj) {
;                     const float rsn = rs * -1.4426950408889634f;
;                     const float da0 = 1.0f + __builtin_amdgcn_exp2f(acc[ai][0][m][0][jj] * rsn), da1 = 1.0f + __builtin_amdgcn_exp2f(acc[ai][0][m][1][jj] * rsn);
;                     const float db0 = 1.0f + __builtin_amdgcn_exp2f(acc[ai][1][m][0][jj] * rsn), db1 = 1.0f + __builtin_amdgcn_exp2f(acc[ai][1][m][1][jj] * rsn);
;                     b0[jj] = __builtin_amdgcn_rcpf(db0); b1[jj] = __builtin_amdgcn_rcpf(db1);
;                     r0[jj] = db0 * __builtin_amdgcn_rcpf(da0); r1[jj] = db1 * __builtin_amdgcn_rcpf(da1); }
;                 st_nt(gates + (size_t)row * 4096 + col, pack8(r0, r1));
;                 st_nt(gates + (size_t)row * 4096 + 2048 + col, pack8(b0, b1));
	v_exp_f32_e32 v68, v68
	v_add_f32_e32 v77, 1.0, v77
	v_exp_f32_e32 v69, v69
	v_mul_f32_e32 v64, v86, v64
	v_rcp_f32_e32 v72, v76
	v_rcp_f32_e32 v76, v80
	v_add_f32_e32 v80, 1.0, v73
	v_mul_f32_e32 v65, v86, v65
	v_rcp_f32_e32 v73, v77
	v_exp_f32_e32 v64, v64
	v_exp_f32_e32 v65, v65
	v_rcp_f32_e32 v77, v80
	v_pk_add_f32 v[68:69], v[68:69], 1.0 op_sel_hi:[1,0]
	v_mul_f32_e32 v66, v86, v66
	v_rcp_f32_e32 v81, v68
	v_pk_mul_f32 v[72:73], v[72:73], v[68:69]
	v_mul_f32_e32 v68, v86, v78
	v_pk_add_f32 v[64:65], v[64:65], 1.0 op_sel_hi:[1,0]
	v_exp_f32_e32 v78, v68
	v_mul_f32_e32 v68, v86, v74
	v_rcp_f32_e32 v82, v69
	v_rcp_f32_e32 v80, v64
	v_exp_f32_e32 v74, v68
	v_pk_mul_f32 v[68:69], v[76:77], v[64:65]
	v_mul_f32_e32 v64, v86, v70
	v_mul_f32_e32 v70, v86, v79
	v_exp_f32_e32 v76, v70
	v_mul_f32_e32 v70, v86, v75
	v_exp_f32_e32 v75, v70
	v_rcp_f32_e32 v83, v65
	v_add_f32_e32 v65, 1.0, v78
	v_rcp_f32_e32 v70, v65
	v_mul_f32_e32 v65, v86, v71
	v_exp_f32_e32 v64, v64
	v_add_f32_e32 v76, 1.0, v76
	v_exp_f32_e32 v65, v65
	v_mul_f32_e32 v67, v86, v67
	v_add_f32_e32 v74, 1.0, v74
	v_exp_f32_e32 v66, v66
	v_add_f32_e32 v75, 1.0, v75
	v_rcp_f32_e32 v71, v76
	v_exp_f32_e32 v67, v67
	v_rcp_f32_e32 v74, v74
	v_rcp_f32_e32 v75, v75
	v_pk_add_f32 v[64:65], v[64:65], 1.0 op_sel_hi:[1,0]
	s_nop 0
	v_rcp_f32_e32 v78, v64
	v_pk_mul_f32 v[70:71], v[70:71], v[64:65]
	v_rcp_f32_e32 v79, v65
	v_pk_add_f32 v[64:65], v[66:67], 1.0 op_sel_hi:[1,0]
	v_cvt_pk_bf16_f32 v66, v68, v69
	v_rcp_f32_e32 v84, v64
	v_pk_mul_f32 v[74:75], v[74:75], v[64:65]
	v_or_b32_e32 v64, 48, v146
	v_rcp_f32_e32 v85, v65
	v_ashrrev_i32_e32 v65, 31, v64
	v_lshlrev_b64 v[64:65], 13, v[64:65]
	v_lshl_add_u64 v[64:65], s[24:25], 0, v[64:65]
	v_lshl_add_u64 v[76:77], v[64:65], 0, v[114:115]
	v_cvt_pk_bf16_f32 v65, v70, v71
	v_mul_f32_e32 v70, 0xbfb8aa3b, v161
	v_mul_f32_e32 v56, v70, v56
	v_exp_f32_e32 v56, v56
	v_cvt_pk_bf16_f32 v64, v72, v73
	v_cvt_pk_bf16_f32 v67, v74, v75
	v_add_co_u32_e32 v68, vcc, s50, v76
	global_store_dwordx4 v[76:77], v[64:67], off
	s_nop 0
	v_addc_co_u32_e32 v69, vcc, 0, v77, vcc
	v_cvt_pk_bf16_f32 v64, v81, v82
	v_cvt_pk_bf16_f32 v65, v78, v79
	v_cvt_pk_bf16_f32 v66, v80, v83
	v_cvt_pk_bf16_f32 v67, v84, v85
	v_mul_f32_e32 v60, v70, v60
	global_store_dwordx4 v[68:69], v[64:67], off
	v_exp_f32_e32 v60, v60
	v_mul_f32_e32 v52, v70, v52
	v_add_f32_e32 v64, 1.0, v56
	v_mul_f32_e32 v56, v70, v61
	v_exp_f32_e32 v61, v56
	v_mul_f32_e32 v56, v70, v57
	v_exp_f32_e32 v57, v56
	v_mul_f32_e32 v53, v70, v53
	v_add_f32_e32 v60, 1.0, v60
	v_exp_f32_e32 v52, v52
	v_add_f32_e32 v61, 1.0, v61
	v_exp_f32_e32 v53, v53
	v_mul_f32_e32 v48, v70, v48
	v_rcp_f32_e32 v56, v60
	v_rcp_f32_e32 v60, v64
	v_add_f32_e32 v64, 1.0, v57
	v_mul_f32_e32 v49, v70, v49
	v_rcp_f32_e32 v57, v61
	v_exp_f32_e32 v48, v48
	v_exp_f32_e32 v49, v49
	v_rcp_f32_e32 v61, v64
	v_pk_add_f32 v[52:53], v[52:53], 1.0 op_sel_hi:[1,0]
	v_mul_f32_e32 v50, v70, v50
	v_rcp_f32_e32 v65, v52
	v_pk_mul_f32 v[56:57], v[56:57], v[52:53]
	v_mul_f32_e32 v52, v70, v62
	v_pk_add_f32 v[48:49], v[48:49], 1.0 op_sel_hi:[1,0]
	v_exp_f32_e32 v62, v52
	v_mul_f32_e32 v52, v70, v58
	v_rcp_f32_e32 v66, v53
	v_rcp_f32_e32 v64, v48
	v_exp_f32_e32 v58, v52
	v_pk_mul_f32 v[52:53], v[60:61], v[48:49]
	v_mul_f32_e32 v48, v70, v54
	v_mul_f32_e32 v54, v70, v63
	v_exp_f32_e32 v61, v54
	v_mul_f32_e32 v54, v70, v59
	v_exp_f32_e32 v59, v54
	v_rcp_f32_e32 v60, v49
	v_add_f32_e32 v49, 1.0, v62
	v_rcp_f32_e32 v54, v49
	v_mul_f32_e32 v49, v70, v55
	v_exp_f32_e32 v48, v48
	v_add_f32_e32 v61, 1.0, v61
	v_exp_f32_e32 v49, v49
	v_mul_f32_e32 v51, v70, v51
	v_add_f32_e32 v58, 1.0, v58
	v_exp_f32_e32 v50, v50
	v_add_f32_e32 v59, 1.0, v59
	v_rcp_f32_e32 v55, v61
	v_exp_f32_e32 v51, v51
	v_rcp_f32_e32 v58, v58
	v_rcp_f32_e32 v59, v59
	v_pk_add_f32 v[48:49], v[48:49], 1.0 op_sel_hi:[1,0]
	s_nop 0
	v_rcp_f32_e32 v61, v48
	v_pk_mul_f32 v[54:55], v[54:55], v[48:49]
	v_rcp_f32_e32 v62, v49
	v_pk_add_f32 v[48:49], v[50:51], 1.0 op_sel_hi:[1,0]
	v_cvt_pk_bf16_f32 v50, v52, v53
	v_pk_mul_f32 v[58:59], v[58:59], v[48:49]
	v_rcp_f32_e32 v67, v49
	v_cvt_pk_bf16_f32 v49, v54, v55
	v_mul_f32_e32 v54, 0xbfb8aa3b, v162
	v_rcp_f32_e32 v63, v48
	v_mul_f32_e32 v40, v54, v40
	v_exp_f32_e32 v40, v40
	v_add_co_u32_e32 v52, vcc, s60, v112
	v_cvt_pk_bf16_f32 v48, v56, v57
	v_cvt_pk_bf16_f32 v51, v58, v59
	v_addc_co_u32_e32 v53, vcc, 0, v113, vcc
	global_store_dwordx4 v[52:53], v[48:51], off offset:-4096
	v_mul_f32_e32 v44, v54, v44
	v_exp_f32_e32 v44, v44
	v_cvt_pk_bf16_f32 v48, v65, v66
	v_cvt_pk_bf16_f32 v49, v61, v62
	v_cvt_pk_bf16_f32 v50, v64, v60
	v_cvt_pk_bf16_f32 v51, v63, v67
	global_store_dwordx4 v[52:53], v[48:51], off
	v_mul_f32_e32 v36, v54, v36
	v_mul_f32_e32 v37, v54, v37
	v_add_f32_e32 v48, 1.0, v40
	v_mul_f32_e32 v40, v54, v45
	v_exp_f32_e32 v45, v40
	v_mul_f32_e32 v40, v54, v41
	v_exp_f32_e32 v41, v40
	v_add_f32_e32 v44, 1.0, v44
	v_exp_f32_e32 v36, v36
	v_add_f32_e32 v45, 1.0, v45
	v_exp_f32_e32 v37, v37
	v_mul_f32_e32 v32, v54, v32
	v_rcp_f32_e32 v40, v44
	v_rcp_f32_e32 v44, v48
	v_add_f32_e32 v48, 1.0, v41
	v_mul_f32_e32 v33, v54, v33
	v_rcp_f32_e32 v41, v45
	v_exp_f32_e32 v32, v32
	v_exp_f32_e32 v33, v33
	v_rcp_f32_e32 v45, v48
	v_pk_add_f32 v[36:37], v[36:37], 1.0 op_sel_hi:[1,0]
	v_mul_f32_e32 v34, v54, v34
	v_rcp_f32_e32 v49, v36
	v_pk_mul_f32 v[40:41], v[40:41], v[36:37]
	v_mul_f32_e32 v36, v54, v46
	v_pk_add_f32 v[32:33], v[32:33], 1.0 op_sel_hi:[1,0]
	v_exp_f32_e32 v46, v36
	v_mul_f32_e32 v36, v54, v42
	v_rcp_f32_e32 v50, v37
	v_rcp_f32_e32 v48, v32
	v_exp_f32_e32 v42, v36
	v_pk_mul_f32 v[36:37], v[44:45], v[32:33]
	v_mul_f32_e32 v32, v54, v38
	v_mul_f32_e32 v38, v54, v47
; __device__ __forceinline__ void st_nt(float* p, f32x4 v) { __builtin_nontemporal_store(v, (f32x4*)p); }
; __device__ __forceinline__ void st_nt(bf16_t* p, u32x4 v) { __builtin_nontemporal_store(v, (u32x4*)p); }
; __device__ __forceinline__ u32x4 pack8(const f32x4 a, const f32x4 b) { u32x4 w; w.x = cvt_pk_bf16(a[0], a[1]); w.y = cvt_pk_bf16(a[2], a[3]); w.z = cvt_pk_bf16(b[0], b[1]); w.w = cvt_pk_bf16(b[2], b[3]); return w; }
;     __device__ __forceinline__ void operator()(Acc& acc, const Unit& u, int wr, int wc, int fr, int fq, const float (&rsv)[8]) const {
;         const int row0 = u.pm * BM + wr * 64 + fr, col = u.pn * HALF + wc * 32 + 8 * fq;
; #pragma unroll
;         for (int ai = 0; ai < 2; ++ai)
; #pragma unroll
;             for (int m = 0; m < 4; ++m) {
;                 const int row = row0 + ai * HALF + m * 16; const float rs = rsv[ai * 4 + m];
;                 f32x4 r0, r1, b0, b1;
; #pragma unroll
;                 for (int jj = 0; jj < 4; ++jj) {
;                     const float rsn = rs * -1.4426950408889634f;
;                     const float da0 = 1.0f + __builtin_amdgcn_exp2f(acc[ai][0][m][0][jj] * rsn), da1 = 1.0f + __builtin_amdgcn_exp2f(acc[ai][0][m][1][jj] * rsn);
;                     const float db0 = 1.0f + __builtin_amdgcn_exp2f(acc[ai][1][m][0][jj] * rsn), db1 = 1.0f + __builtin_amdgcn_exp2f(acc[ai][1][m][1][jj] * rsn);
;                     b0[jj] = __builtin_amdgcn_rcpf(db0); b1[jj] = __builtin_amdgcn_rcpf(db1);
;                     r0[jj] = db0 * __builtin_amdgcn_rcpf(da0); r1[jj] = db1 * __builtin_amdgcn_rcpf(da1); }
;                 st_nt(gates + (size_t)row * 4096 + col, pack8(r0, r1));
;                 st_nt(gates + (size_t)row * 4096 + 2048 + col, pack8(b0, b1));
;             }
;     }
	v_exp_f32_e32 v45, v38
	v_mul_f32_e32 v38, v54, v43
	v_exp_f32_e32 v43, v38
	v_rcp_f32_e32 v44, v33
	v_add_f32_e32 v33, 1.0, v46
	v_rcp_f32_e32 v38, v33
	v_mul_f32_e32 v33, v54, v39
	v_exp_f32_e32 v32, v32
	v_add_f32_e32 v45, 1.0, v45
	v_exp_f32_e32 v33, v33
	v_mul_f32_e32 v35, v54, v35
	v_add_f32_e32 v42, 1.0, v42
	v_exp_f32_e32 v34, v34
	v_add_f32_e32 v43, 1.0, v43
	v_rcp_f32_e32 v39, v45
	v_exp_f32_e32 v35, v35
	v_rcp_f32_e32 v42, v42
	v_rcp_f32_e32 v43, v43
	v_pk_add_f32 v[32:33], v[32:33], 1.0 op_sel_hi:[1,0]
	s_nop 0
	v_rcp_f32_e32 v45, v32
	v_pk_mul_f32 v[38:39], v[38:39], v[32:33]
	v_rcp_f32_e32 v46, v33
	v_pk_add_f32 v[32:33], v[34:35], 1.0 op_sel_hi:[1,0]
	v_cvt_pk_bf16_f32 v34, v36, v37
	v_pk_mul_f32 v[42:43], v[42:43], v[32:33]
	v_rcp_f32_e32 v51, v33
	v_cvt_pk_bf16_f32 v33, v38, v39
	v_mul_f32_e32 v38, 0xbfb8aa3b, v163
	v_rcp_f32_e32 v47, v32
	v_mul_f32_e32 v24, v38, v24
	v_exp_f32_e32 v24, v24
	v_add_co_u32_e32 v36, vcc, s61, v112
	v_cvt_pk_bf16_f32 v32, v40, v41
	v_cvt_pk_bf16_f32 v35, v42, v43
	v_addc_co_u32_e32 v37, vcc, 0, v113, vcc
	global_store_dwordx4 v[36:37], v[32:35], off offset:-4096
	v_mul_f32_e32 v28, v38, v28
	v_exp_f32_e32 v28, v28
	v_cvt_pk_bf16_f32 v32, v49, v50
	v_cvt_pk_bf16_f32 v33, v45, v46
	v_cvt_pk_bf16_f32 v34, v48, v44
	v_cvt_pk_bf16_f32 v35, v47, v51
	global_store_dwordx4 v[36:37], v[32:35], off
	v_mul_f32_e32 v20, v38, v20
	v_mul_f32_e32 v21, v38, v21
	v_add_f32_e32 v32, 1.0, v24
	v_mul_f32_e32 v24, v38, v29
	v_exp_f32_e32 v29, v24
	v_mul_f32_e32 v24, v38, v25
	v_exp_f32_e32 v25, v24
	v_add_f32_e32 v28, 1.0, v28
	v_exp_f32_e32 v20, v20
	v_add_f32_e32 v29, 1.0, v29
	v_exp_f32_e32 v21, v21
	v_mul_f32_e32 v16, v38, v16
	v_rcp_f32_e32 v24, v28
	v_rcp_f32_e32 v28, v32
	v_add_f32_e32 v32, 1.0, v25
	v_mul_f32_e32 v17, v38, v17
	v_rcp_f32_e32 v25, v29
	v_exp_f32_e32 v16, v16
	v_exp_f32_e32 v17, v17
	v_rcp_f32_e32 v29, v32
	v_pk_add_f32 v[20:21], v[20:21], 1.0 op_sel_hi:[1,0]
	v_mul_f32_e32 v18, v38, v18
	v_rcp_f32_e32 v33, v20
	v_pk_mul_f32 v[24:25], v[24:25], v[20:21]
	v_mul_f32_e32 v20, v38, v30
	v_pk_add_f32 v[16:17], v[16:17], 1.0 op_sel_hi:[1,0]
	v_exp_f32_e32 v30, v20
	v_mul_f32_e32 v20, v38, v26
	v_rcp_f32_e32 v34, v21
	v_rcp_f32_e32 v32, v16
	v_exp_f32_e32 v26, v20
	v_pk_mul_f32 v[20:21], v[28:29], v[16:17]
	v_mul_f32_e32 v16, v38, v22
	v_mul_f32_e32 v22, v38, v31
	v_exp_f32_e32 v29, v22
	v_mul_f32_e32 v22, v38, v27
	v_exp_f32_e32 v27, v22
	v_rcp_f32_e32 v28, v17
	v_add_f32_e32 v17, 1.0, v30
	v_rcp_f32_e32 v22, v17
	v_mul_f32_e32 v17, v38, v23
	v_exp_f32_e32 v16, v16
	v_add_f32_e32 v29, 1.0, v29
	v_exp_f32_e32 v17, v17
	v_mul_f32_e32 v19, v38, v19
	v_add_f32_e32 v26, 1.0, v26
	v_exp_f32_e32 v18, v18
	v_add_f32_e32 v27, 1.0, v27
	v_rcp_f32_e32 v23, v29
	v_exp_f32_e32 v19, v19
	v_rcp_f32_e32 v26, v26
	v_rcp_f32_e32 v27, v27
	v_pk_add_f32 v[16:17], v[16:17], 1.0 op_sel_hi:[1,0]
	s_nop 0
	v_rcp_f32_e32 v29, v16
	v_pk_mul_f32 v[22:23], v[22:23], v[16:17]
	v_rcp_f32_e32 v30, v17
	v_pk_add_f32 v[16:17], v[18:19], 1.0 op_sel_hi:[1,0]
	v_cvt_pk_bf16_f32 v18, v20, v21
	v_pk_mul_f32 v[26:27], v[26:27], v[16:17]
	v_rcp_f32_e32 v35, v17
	v_cvt_pk_bf16_f32 v17, v22, v23
	v_mul_f32_e32 v22, 0xbfb8aa3b, v164
	v_rcp_f32_e32 v31, v16
	v_mul_f32_e32 v8, v22, v8
	v_exp_f32_e32 v8, v8
	v_add_co_u32_e32 v20, vcc, s62, v112
	v_cvt_pk_bf16_f32 v16, v24, v25
	v_cvt_pk_bf16_f32 v19, v26, v27
	v_addc_co_u32_e32 v21, vcc, 0, v113, vcc
	global_store_dwordx4 v[20:21], v[16:19], off offset:-4096
	v_mul_f32_e32 v12, v22, v12
	v_exp_f32_e32 v12, v12
	v_cvt_pk_bf16_f32 v16, v33, v34
	v_cvt_pk_bf16_f32 v17, v29, v30
	v_cvt_pk_bf16_f32 v18, v32, v28
	v_cvt_pk_bf16_f32 v19, v31, v35
	global_store_dwordx4 v[20:21], v[16:19], off
	v_mul_f32_e32 v4, v22, v4
	v_mul_f32_e32 v5, v22, v5
	v_add_f32_e32 v16, 1.0, v8
	v_mul_f32_e32 v8, v22, v13
	v_exp_f32_e32 v13, v8
	v_mul_f32_e32 v8, v22, v9
	v_exp_f32_e32 v9, v8
	v_add_f32_e32 v12, 1.0, v12
	v_exp_f32_e32 v4, v4
	v_add_f32_e32 v13, 1.0, v13
	v_exp_f32_e32 v5, v5
	v_mul_f32_e32 v0, v22, v0
	v_rcp_f32_e32 v8, v12
	v_rcp_f32_e32 v12, v16
	v_add_f32_e32 v16, 1.0, v9
	v_mul_f32_e32 v1, v22, v1
	v_rcp_f32_e32 v9, v13
	v_exp_f32_e32 v0, v0
	v_exp_f32_e32 v1, v1
	v_rcp_f32_e32 v13, v16
	v_pk_add_f32 v[4:5], v[4:5], 1.0 op_sel_hi:[1,0]
	v_mul_f32_e32 v2, v22, v2
	v_rcp_f32_e32 v17, v4
	v_pk_mul_f32 v[8:9], v[8:9], v[4:5]
	v_mul_f32_e32 v4, v22, v14
	v_pk_add_f32 v[0:1], v[0:1], 1.0 op_sel_hi:[1,0]
	v_exp_f32_e32 v14, v4
	v_mul_f32_e32 v4, v22, v10
	v_rcp_f32_e32 v18, v5
	v_rcp_f32_e32 v16, v0
	v_exp_f32_e32 v10, v4
	v_pk_mul_f32 v[4:5], v[12:13], v[0:1]
	v_mul_f32_e32 v0, v22, v6
	v_mul_f32_e32 v6, v22, v15
	v_exp_f32_e32 v13, v6
	v_mul_f32_e32 v6, v22, v11
	v_exp_f32_e32 v11, v6
	v_rcp_f32_e32 v12, v1
	v_add_f32_e32 v1, 1.0, v14
	v_rcp_f32_e32 v6, v1
	v_mul_f32_e32 v1, v22, v7
	v_exp_f32_e32 v0, v0
	v_add_f32_e32 v13, 1.0, v13
	v_exp_f32_e32 v1, v1
	v_mul_f32_e32 v3, v22, v3
	v_add_f32_e32 v10, 1.0, v10
	v_exp_f32_e32 v2, v2
	v_add_f32_e32 v11, 1.0, v11
	v_rcp_f32_e32 v7, v13
	v_exp_f32_e32 v3, v3
	v_rcp_f32_e32 v10, v10
	v_rcp_f32_e32 v11, v11
	v_pk_add_f32 v[0:1], v[0:1], 1.0 op_sel_hi:[1,0]
	s_nop 0
	v_rcp_f32_e32 v13, v0
	v_pk_mul_f32 v[6:7], v[6:7], v[0:1]
	v_rcp_f32_e32 v14, v1
	v_pk_add_f32 v[0:1], v[2:3], 1.0 op_sel_hi:[1,0]
	v_cvt_pk_bf16_f32 v2, v4, v5
	v_rcp_f32_e32 v15, v0
	v_pk_mul_f32 v[10:11], v[10:11], v[0:1]
	v_rcp_f32_e32 v19, v1
	v_add_co_u32_e32 v4, vcc, s63, v112
	v_cvt_pk_bf16_f32 v0, v8, v9
	v_cvt_pk_bf16_f32 v1, v6, v7
	v_cvt_pk_bf16_f32 v3, v10, v11
	v_addc_co_u32_e32 v5, vcc, 0, v113, vcc
	global_store_dwordx4 v[4:5], v[0:3], off
	v_add_co_u32_e32 v4, vcc, 0x161000, v112
	s_nop 0
	v_cvt_pk_bf16_f32 v0, v17, v18
	v_addc_co_u32_e32 v5, vcc, 0, v113, vcc
	v_cvt_pk_bf16_f32 v1, v13, v14
	v_cvt_pk_bf16_f32 v2, v16, v12
	v_cvt_pk_bf16_f32 v3, v15, v19
	s_and_b64 vcc, exec, s[6:7]
	global_store_dwordx4 v[4:5], v[0:3], off
	s_cbranch_vccz .LBB0_757
;     __device__ __forceinline__ void rstd_fill(float (&rsv)[8], const Unit& u, int wr, int fr, int fq) const { rstd_regs32(rsv, part, u.pm * BM + wr * 64 + fr, fq); }
;     __device__ __forceinline__ void rstd_fill(float (&rsv)[8], const Unit& u, int wr, int fr, int fq) const { rstd_regs32(rsv, part, u.pm * BM + wr * 64 + fr, fq); }
;     __device__ __forceinline__ void rstd_fill(float (&rsv)[8], const Unit& u, int wr, int fr, int fq) const { rstd_regs32(rsv, part, u.pm * BM + wr * 64 + fr, fq); }
;     __device__ __forceinline__ void rstd_fill(float (&rsv)[8], const Unit& u, int wr, int fr, int fq) const { rstd_regs32(rsv, part, u.pm * BM + wr * 64 + fr, fq); }
;     __device__ __forceinline__ void rstd_fill(float (&rsv)[8], const Unit& u, int wr, int fr, int fq) const { rstd_regs_lat(rsv, latpart, u.pm * BM + wr * 64 + fr, u.z); }
;     __device__ __forceinline__ void rstd_fill(float (&rsv)[8], const Unit& u, int wr, int fr, int fq) const { rstd_regs32(rsv, part_in, u.pm * BM + wr * 64 + fr, fq); }
; #define PG8_SCHED __builtin_amdgcn_sched_barrier(0)
; __device__ __forceinline__ void rstd_regs32(float (&rsv)[8], const float* part, int row0, int fq) {
;     int r0 = row0; asm volatile("" : "+v"(r0));
;     const float* q = part + (size_t)r0 * 32 + fq * 8;
;     f32x4 a[8], b[8];
; #pragma unroll
;     for (int g = 0; g < 8; ++g) { const float* p = q + (size_t)((g >> 2) * HALF + (g & 3) * 16) * 32; a[g] = *(const f32x4*)p; b[g] = *(const f32x4*)(p + 4); }
; #pragma unroll
;     for (int g = 0; g < 8; ++g) { float s = ((a[g][0] + a[g][1]) + (a[g][2] + a[g][3])) + ((b[g][0] + b[g][1]) + (b[g][2] + b[g][3]));
;         s += __shfl_xor(s, 16); s += __shfl_xor(s, 32); rsv[g] = __builtin_amdgcn_rsqf(s * (1.0f / 2048.0f) + EPS); }
; }
; template <class Epi>
; __device__ __forceinline__ void gemm_phase(LAS unsigned char* lds, const GSched& S, const int K, const int lda, const int ldb, const Epi& E) {
;     ...
;         if constexpr (Epi::RSTD) { if (nxt.pm != cur.pm || nxt.z != cur.z) { PG8_SCHED; E.rstd_fill(rsv, nxt, wr, fr, fq); PG8_SCHED; } }
	s_cmp_eq_u32 s1, s55
	s_cbranch_scc1 .LBB0_756
	v_lshl_add_u32 v0, s1, 8, v151
	s_nop 0
	v_ashrrev_i32_e32 v1, 31, v0
	v_lshlrev_b64 v[0:1], 7, v[0:1]
	v_lshl_add_u64 v[48:49], v[136:137], 0, v[0:1]
	global_load_dwordx4 v[0:3], v[48:49], off
	global_load_dwordx4 v[4:7], v[48:49], off offset:16
	global_load_dwordx4 v[8:11], v[48:49], off offset:2048
	global_load_dwordx4 v[12:15], v[48:49], off offset:2064
	v_add_co_u32_e32 v28, vcc, 0x1000, v48
	v_lshl_add_u64 v[24:25], v[48:49], 0, s[12:13]
	v_lshl_add_u64 v[16:17], v[48:49], 0, s[16:17]
	v_addc_co_u32_e32 v29, vcc, 0, v49, vcc
	v_lshl_add_u64 v[32:33], v[48:49], 0, s[14:15]
	global_load_dwordx4 v[16:19], v[16:17], off offset:16
	s_nop 0
	global_load_dwordx4 v[20:23], v[28:29], off
	s_nop 0
	global_load_dwordx4 v[24:27], v[24:25], off offset:16
	s_nop 0
	global_load_dwordx4 v[28:31], v[28:29], off offset:2048
	s_nop 0
	global_load_dwordx4 v[32:35], v[32:33], off offset:16
	v_add_co_u32_e32 v50, vcc, s49, v48
	s_mov_b64 s[6:7], vcc
	v_add_co_u32_e32 v56, vcc, s51, v48
	v_lshl_add_u64 v[40:41], v[48:49], 0, s[18:19]
	s_nop 0
	v_addc_co_u32_e32 v57, vcc, 0, v49, vcc
	global_load_dwordx4 v[36:39], v[56:57], off offset:-4096
	v_lshl_add_u64 v[44:45], v[48:49], 0, s[20:21]
	global_load_dwordx4 v[40:43], v[40:41], off offset:16
	s_nop 0
	global_load_dwordx4 v[44:47], v[44:45], off offset:16
	v_lshl_add_u64 v[60:61], v[48:49], 0, s[22:23]
	v_addc_co_u32_e64 v51, vcc, 0, v49, s[6:7]
	global_load_dwordx4 v[48:51], v[50:51], off offset:2048
	s_nop 0
	global_load_dwordx4 v[52:55], v[56:57], off
	s_nop 0
	global_load_dwordx4 v[56:59], v[56:57], off offset:2048
	s_nop 0
	global_load_dwordx4 v[60:63], v[60:61], off offset:16
	s_waitcnt vmcnt(0)
	v_mov_b32_e32 v64, v0
	v_mov_b32_e32 v65, v4
	v_mov_b32_e32 v4, v1
	v_mov_b32_e32 v0, v2
	v_mov_b32_e32 v1, v6
	v_mov_b32_e32 v6, v3
	v_mov_b32_e32 v2, v8
	v_mov_b32_e32 v3, v12
	v_mov_b32_e32 v12, v9
	v_mov_b32_e32 v8, v10
	v_mov_b32_e32 v9, v14
	v_mov_b32_e32 v14, v11
	v_pk_add_f32 v[4:5], v[64:65], v[4:5]
	v_pk_add_f32 v[0:1], v[0:1], v[6:7]
	v_pk_add_f32 v[2:3], v[2:3], v[12:13]
	v_pk_add_f32 v[6:7], v[8:9], v[14:15]
	v_pk_add_f32 v[0:1], v[4:5], v[0:1]
	v_pk_add_f32 v[2:3], v[2:3], v[6:7]
	v_mov_b32_e32 v4, v20
	v_mov_b32_e32 v5, v24
	v_mov_b32_e32 v24, v21
	v_mov_b32_e32 v6, v22
	v_mov_b32_e32 v7, v26
	v_mov_b32_e32 v26, v23
	v_mov_b32_e32 v10, v28
	v_mov_b32_e32 v11, v32
	v_mov_b32_e32 v32, v29
	v_add_f32_e32 v14, v0, v1
	v_add_f32_e32 v15, v2, v3
	v_mov_b32_e32 v12, v30
	v_mov_b32_e32 v13, v34
	v_mov_b32_e32 v34, v31
	v_pk_add_f32 v[0:1], v[4:5], v[24:25]
	v_pk_add_f32 v[2:3], v[6:7], v[26:27]
	v_pk_add_f32 v[4:5], v[10:11], v[32:33]
	ds_bpermute_b32 v10, v148, v14
	ds_bpermute_b32 v11, v148, v15
	v_pk_add_f32 v[6:7], v[12:13], v[34:35]
	v_pk_add_f32 v[0:1], v[0:1], v[2:3]
	v_pk_add_f32 v[2:3], v[4:5], v[6:7]
	v_add_f32_e32 v0, v0, v1
	v_add_f32_e32 v1, v2, v3
	ds_bpermute_b32 v2, v148, v0
	ds_bpermute_b32 v3, v148, v1
	s_waitcnt lgkmcnt(0)
	v_add_f32_e32 v4, v14, v10
	v_add_f32_e32 v5, v15, v11
	ds_bpermute_b32 v6, v149, v4
	ds_bpermute_b32 v7, v149, v5
	v_add_f32_e32 v0, v0, v2
	v_add_f32_e32 v10, v1, v3
	ds_bpermute_b32 v1, v149, v0
	s_waitcnt lgkmcnt(2)
	v_add_f32_e32 v2, v4, v6
	s_waitcnt lgkmcnt(1)
	v_add_f32_e32 v3, v5, v7
	v_fmamk_f32 v2, v2, 0x3a000000, v150
	v_fmamk_f32 v3, v3, 0x3a000000, v150
	v_mov_b32_e32 v9, v16
	v_mov_b32_e32 v8, v36
	v_rsq_f32_e32 v157, v2
	v_rsq_f32_e32 v158, v3
	v_mov_b32_e32 v16, v37
	v_mov_b32_e32 v2, v38
	v_mov_b32_e32 v3, v18
	v_mov_b32_e32 v18, v39
	s_waitcnt lgkmcnt(0)
	v_add_f32_e32 v4, v0, v1
	v_pk_add_f32 v[0:1], v[8:9], v[16:17]
	v_pk_add_f32 v[2:3], v[2:3], v[18:19]
	ds_bpermute_b32 v11, v149, v10
	v_pk_add_f32 v[0:1], v[0:1], v[2:3]
	v_fmamk_f32 v2, v4, 0x3a000000, v150
	v_add_f32_e32 v0, v0, v1
	ds_bpermute_b32 v1, v148, v0
	v_rsq_f32_e32 v159, v2
	s_waitcnt lgkmcnt(1)
	v_add_f32_e32 v2, v10, v11
	v_fmamk_f32 v4, v2, 0x3a000000, v150
	v_mov_b32_e32 v2, v50
	s_waitcnt lgkmcnt(0)
	v_add_f32_e32 v5, v0, v1
	v_mov_b32_e32 v0, v48
	v_mov_b32_e32 v1, v40
	v_mov_b32_e32 v40, v49
	v_mov_b32_e32 v3, v42
	v_mov_b32_e32 v42, v51
	v_pk_add_f32 v[0:1], v[0:1], v[40:41]
	v_pk_add_f32 v[2:3], v[2:3], v[42:43]
	ds_bpermute_b32 v6, v149, v5
	v_pk_add_f32 v[0:1], v[0:1], v[2:3]
	v_rsq_f32_e32 v160, v4
	v_add_f32_e32 v0, v0, v1
	ds_bpermute_b32 v1, v148, v0
	s_waitcnt lgkmcnt(1)
	v_add_f32_e32 v2, v5, v6
	v_fmamk_f32 v2, v2, 0x3a000000, v150
	v_rsq_f32_e32 v161, v2
	v_mov_b32_e32 v2, v54
	s_waitcnt lgkmcnt(0)
	v_add_f32_e32 v4, v0, v1
	v_mov_b32_e32 v0, v52
	v_mov_b32_e32 v1, v44
	v_mov_b32_e32 v44, v53
	v_mov_b32_e32 v3, v46
	v_mov_b32_e32 v46, v55
	v_pk_add_f32 v[0:1], v[0:1], v[44:45]
	v_pk_add_f32 v[2:3], v[2:3], v[46:47]
	ds_bpermute_b32 v5, v149, v4
	v_pk_add_f32 v[0:1], v[0:1], v[2:3]
	v_mov_b32_e32 v2, v58
	v_add_f32_e32 v6, v0, v1
	v_mov_b32_e32 v0, v56
	v_mov_b32_e32 v1, v60
	v_mov_b32_e32 v60, v57
	v_mov_b32_e32 v3, v62
	v_mov_b32_e32 v62, v59
	v_pk_add_f32 v[0:1], v[0:1], v[60:61]
	v_pk_add_f32 v[2:3], v[2:3], v[62:63]
	ds_bpermute_b32 v7, v148, v6
	v_pk_add_f32 v[0:1], v[0:1], v[2:3]
	s_waitcnt lgkmcnt(1)
	v_add_f32_e32 v2, v4, v5
	v_add_f32_e32 v0, v0, v1
	ds_bpermute_b32 v1, v148, v0
	s_waitcnt lgkmcnt(1)
	v_add_f32_e32 v3, v6, v7
	ds_bpermute_b32 v4, v149, v3
	v_fmamk_f32 v2, v2, 0x3a000000, v150
	v_rsq_f32_e32 v162, v2
	s_waitcnt lgkmcnt(1)
	v_add_f32_e32 v0, v0, v1
	ds_bpermute_b32 v1, v149, v0
	s_waitcnt lgkmcnt(1)
	v_add_f32_e32 v2, v3, v4
	v_fmamk_f32 v2, v2, 0x3a000000, v150
	v_rsq_f32_e32 v163, v2
	s_waitcnt lgkmcnt(0)
	v_add_f32_e32 v0, v0, v1
	v_fmamk_f32 v0, v0, 0x3a000000, v150
	v_rsq_f32_e32 v164, v0
	s_branch .LBB0_756

; __device__ __forceinline__ f32x4 ld_nt(const float* p) { return __builtin_nontemporal_load((const f32x4*)p); }
; __device__ __forceinline__ u32x4 ld_nt(const bf16_t* p) { return __builtin_nontemporal_load((const u32x4*)p); }
; __device__ __forceinline__ void st_nt(float* p, f32x4 v) { __builtin_nontemporal_store(v, (f32x4*)p); }
; __device__ __forceinline__ void st_nt(bf16_t* p, u32x4 v) { __builtin_nontemporal_store(v, (u32x4*)p); }
; __device__ __forceinline__ u32x4 pack8(const f32x4 a, const f32x4 b) { u32x4 w; w.x = cvt_pk_bf16(a[0], a[1]); w.y = cvt_pk_bf16(a[2], a[3]); w.z = cvt_pk_bf16(b[0], b[1]); w.w = cvt_pk_bf16(b[2], b[3]); return w; }
; __device__ __forceinline__ void unpack8(const u32x4 w, f32x4& a, f32x4& b) { a = (f32x4){bf_lo(w.x), bf_hi(w.x), bf_lo(w.y), bf_hi(w.y)}; b = (f32x4){bf_lo(w.z), bf_hi(w.z), bf_lo(w.w), bf_hi(w.w)}; }
;     __device__ __forceinline__ void operator()(Acc& acc, const Unit& u, int wr, int wc, int fr, int fq, const float (&rsv)[8]) const {
;         const int row0 = u.pm * BM + wr * 64 + fr, col0 = u.pn * BM + wc * 32 + 8 * fq;
;         u32x4 gs[8][2];
; #pragma unroll
;         for (int g = 0; g < 8; ++g)
; #pragma unroll
;             for (int bj = 0; bj < 2; ++bj) gs[g][bj] = ld_nt(gates + (size_t)(row0 + (g >> 2) * HALF + (g & 3) * 16) * 4096 + 2048 + col0 + bj * HALF);
; #pragma unroll
;         for (int g = 0; g < 8; ++g) { const int ai = g >> 2, m = g & 3; const int row = row0 + ai * HALF + m * 16;
; #pragma unroll
;             for (int bj = 0; bj < 2; ++bj) { f32x4 b0, b1; unpack8(gs[g][bj], b0, b1);
;                 st_nt(merged + (size_t)row * 2048 + col0 + bj * HALF, pack8(acc[ai][bj][m][0] * b0, acc[ai][bj][m][1] * b1)); } }
.LBB0_852:
	v_or_b32_e32 v128, s8, v206
	v_ashrrev_i32_e32 v191, 31, v190
	v_ashrrev_i32_e32 v129, 31, v128
	v_lshlrev_b64 v[130:131], 13, v[190:191]
	v_lshl_add_u64 v[130:131], s[12:13], 0, v[130:131]
	v_lshlrev_b64 v[192:193], 1, v[128:129]
	v_lshl_add_u64 v[128:129], v[130:131], 0, v[192:193]
	v_lshl_add_u64 v[130:131], v[128:129], 0, s[16:17]
	v_add_co_u32_e32 v128, vcc, 0x1000, v128
	v_or_b32_e32 v230, 16, v190
	s_nop 0
	v_addc_co_u32_e32 v129, vcc, 0, v129, vcc
	global_load_dwordx4 v[210:213], v[128:129], off nt
	global_load_dwordx4 v[214:217], v[130:131], off offset:256 nt
	v_ashrrev_i32_e32 v231, 31, v230
	v_lshlrev_b64 v[128:129], 13, v[230:231]
	v_lshl_add_u64 v[128:129], s[12:13], 0, v[128:129]
	v_lshl_add_u64 v[128:129], v[128:129], 0, v[192:193]
	v_lshl_add_u64 v[130:131], v[128:129], 0, s[16:17]
	v_add_co_u32_e32 v128, vcc, 0x1000, v128
	v_or_b32_e32 v234, 32, v190
	s_nop 0
	v_addc_co_u32_e32 v129, vcc, 0, v129, vcc
	global_load_dwordx4 v[218:221], v[128:129], off nt
	global_load_dwordx4 v[222:225], v[130:131], off offset:256 nt
	v_ashrrev_i32_e32 v235, 31, v234
	v_lshlrev_b64 v[128:129], 13, v[234:235]
	v_lshl_add_u64 v[128:129], s[12:13], 0, v[128:129]
	v_lshl_add_u64 v[128:129], v[128:129], 0, v[192:193]
	v_lshl_add_u64 v[130:131], v[128:129], 0, s[16:17]
	v_add_co_u32_e32 v128, vcc, 0x1000, v128
	v_or_b32_e32 v202, 48, v190
	s_nop 0
	v_addc_co_u32_e32 v129, vcc, 0, v129, vcc
	global_load_dwordx4 v[226:229], v[128:129], off nt
	global_load_dwordx4 v[168:171], v[130:131], off offset:256 nt
	v_ashrrev_i32_e32 v203, 31, v202
	v_lshlrev_b64 v[128:129], 13, v[202:203]
	v_lshl_add_u64 v[128:129], s[12:13], 0, v[128:129]
	v_lshl_add_u64 v[128:129], v[128:129], 0, v[192:193]
	v_lshl_add_u64 v[130:131], v[128:129], 0, s[16:17]
	v_add_co_u32_e32 v128, vcc, 0x1000, v128
	v_add_u32_e32 v200, 0x80, v190
	s_nop 0
	v_addc_co_u32_e32 v129, vcc, 0, v129, vcc
	global_load_dwordx4 v[164:167], v[128:129], off nt
	global_load_dwordx4 v[160:163], v[130:131], off offset:256 nt
	v_ashrrev_i32_e32 v201, 31, v200
	v_lshlrev_b64 v[128:129], 13, v[200:201]
	v_lshl_add_u64 v[128:129], s[12:13], 0, v[128:129]
	v_lshl_add_u64 v[128:129], v[128:129], 0, v[192:193]
	v_lshl_add_u64 v[130:131], v[128:129], 0, s[16:17]
	v_add_co_u32_e32 v128, vcc, 0x1000, v128
	v_add_u32_e32 v198, 0x90, v190
	s_nop 0
	v_addc_co_u32_e32 v129, vcc, 0, v129, vcc
	global_load_dwordx4 v[156:159], v[128:129], off nt
	global_load_dwordx4 v[152:155], v[130:131], off offset:256 nt
	v_ashrrev_i32_e32 v199, 31, v198
	v_lshlrev_b64 v[128:129], 13, v[198:199]
	v_lshl_add_u64 v[128:129], s[12:13], 0, v[128:129]
	v_lshl_add_u64 v[128:129], v[128:129], 0, v[192:193]
	v_lshl_add_u64 v[130:131], v[128:129], 0, s[16:17]
	v_add_co_u32_e32 v128, vcc, 0x1000, v128
	v_add_u32_e32 v196, 0xa0, v190
	s_nop 0
	v_addc_co_u32_e32 v129, vcc, 0, v129, vcc
	global_load_dwordx4 v[148:151], v[128:129], off nt
	global_load_dwordx4 v[144:147], v[130:131], off offset:256 nt
	v_ashrrev_i32_e32 v197, 31, v196
	v_lshlrev_b64 v[128:129], 13, v[196:197]
	v_lshl_add_u64 v[128:129], s[12:13], 0, v[128:129]
	v_lshl_add_u64 v[128:129], v[128:129], 0, v[192:193]
	v_lshl_add_u64 v[130:131], v[128:129], 0, s[16:17]
	v_add_co_u32_e32 v128, vcc, 0x1000, v128
	v_add_u32_e32 v194, 0xb0, v190
	s_nop 0
	v_addc_co_u32_e32 v129, vcc, 0, v129, vcc
	global_load_dwordx4 v[140:143], v[128:129], off nt
	global_load_dwordx4 v[136:139], v[130:131], off offset:256 nt
	v_ashrrev_i32_e32 v195, 31, v194
	v_lshlrev_b64 v[128:129], 13, v[194:195]
	v_lshl_add_u64 v[128:129], s[12:13], 0, v[128:129]
	v_lshl_add_u64 v[128:129], v[128:129], 0, v[192:193]
	v_lshl_add_u64 v[130:131], v[128:129], 0, s[16:17]
	v_add_co_u32_e32 v128, vcc, 0x1000, v128
	v_lshlrev_b64 v[190:191], 12, v[190:191]
	s_nop 0
	v_addc_co_u32_e32 v129, vcc, 0, v129, vcc
	global_load_dwordx4 v[132:135], v[128:129], off nt
	s_nop 0
	global_load_dwordx4 v[128:131], v[130:131], off offset:256 nt
	v_lshl_add_u64 v[190:191], s[10:11], 0, v[190:191]
	s_waitcnt vmcnt(0)
	v_lshlrev_b32_e32 v236, 16, v210
	v_and_b32_e32 v237, 0xffff0000, v210
	v_lshlrev_b32_e32 v210, 16, v211
	v_and_b32_e32 v211, 0xffff0000, v211
	v_lshlrev_b32_e32 v238, 16, v212
	v_and_b32_e32 v239, 0xffff0000, v212
	v_lshlrev_b32_e32 v212, 16, v213
	v_and_b32_e32 v213, 0xffff0000, v213
	v_pk_mul_f32 v[126:127], v[126:127], v[210:211]
	v_pk_mul_f32 v[124:125], v[124:125], v[236:237]
	v_pk_mul_f32 v[210:211], v[122:123], v[212:213]
	v_pk_mul_f32 v[122:123], v[120:121], v[238:239]
	v_lshl_add_u64 v[190:191], v[190:191], 0, v[192:193]
	v_cvt_pk_bf16_f32 v120, v124, v125
	v_cvt_pk_bf16_f32 v121, v126, v127
	v_cvt_pk_bf16_f32 v122, v122, v123
	v_cvt_pk_bf16_f32 v123, v210, v211
	global_store_dwordx4 v[190:191], v[120:123], off
	v_lshlrev_b32_e32 v124, 16, v216
	v_and_b32_e32 v125, 0xffff0000, v216
	v_lshlrev_b32_e32 v120, 16, v214
	v_and_b32_e32 v121, 0xffff0000, v214
	v_lshlrev_b32_e32 v122, 16, v215
	v_and_b32_e32 v123, 0xffff0000, v215
	v_lshlrev_b32_e32 v126, 16, v217
	v_and_b32_e32 v127, 0xffff0000, v217
	v_pk_mul_f32 v[118:119], v[118:119], v[122:123]
	v_pk_mul_f32 v[116:117], v[116:117], v[120:121]
	v_pk_mul_f32 v[120:121], v[114:115], v[126:127]
	v_pk_mul_f32 v[114:115], v[112:113], v[124:125]
	v_cvt_pk_bf16_f32 v112, v116, v117
	v_cvt_pk_bf16_f32 v113, v118, v119
	v_cvt_pk_bf16_f32 v114, v114, v115
	v_cvt_pk_bf16_f32 v115, v120, v121
	global_store_dwordx4 v[190:191], v[112:115], off offset:256
	v_lshlrev_b32_e32 v116, 16, v219
	v_and_b32_e32 v117, 0xffff0000, v219
	v_lshlrev_b64 v[112:113], 12, v[230:231]
	v_lshlrev_b32_e32 v114, 16, v218
	v_and_b32_e32 v115, 0xffff0000, v218
	v_lshlrev_b32_e32 v118, 16, v220
; __device__ __forceinline__ void st_nt(float* p, f32x4 v) { __builtin_nontemporal_store(v, (f32x4*)p); }
; __device__ __forceinline__ void st_nt(bf16_t* p, u32x4 v) { __builtin_nontemporal_store(v, (u32x4*)p); }
; __device__ __forceinline__ u32x4 pack8(const f32x4 a, const f32x4 b) { u32x4 w; w.x = cvt_pk_bf16(a[0], a[1]); w.y = cvt_pk_bf16(a[2], a[3]); w.z = cvt_pk_bf16(b[0], b[1]); w.w = cvt_pk_bf16(b[2], b[3]); return w; }
; __device__ __forceinline__ void unpack8(const u32x4 w, f32x4& a, f32x4& b) { a = (f32x4){bf_lo(w.x), bf_hi(w.x), bf_lo(w.y), bf_hi(w.y)}; b = (f32x4){bf_lo(w.z), bf_hi(w.z), bf_lo(w.w), bf_hi(w.w)}; }
;     __device__ __forceinline__ void operator()(Acc& acc, const Unit& u, int wr, int wc, int fr, int fq, const float (&rsv)[8]) const {
;     ...
;         for (int g = 0; g < 8; ++g) { const int ai = g >> 2, m = g & 3; const int row = row0 + ai * HALF + m * 16;
; #pragma unroll
;             for (int bj = 0; bj < 2; ++bj) { f32x4 b0, b1; unpack8(gs[g][bj], b0, b1);
;                 st_nt(merged + (size_t)row * 2048 + col0 + bj * HALF, pack8(acc[ai][bj][m][0] * b0, acc[ai][bj][m][1] * b1)); } }
	v_and_b32_e32 v119, 0xffff0000, v220
	v_lshlrev_b32_e32 v120, 16, v221
	v_and_b32_e32 v121, 0xffff0000, v221
	v_lshl_add_u64 v[112:113], s[10:11], 0, v[112:113]
	v_pk_mul_f32 v[110:111], v[110:111], v[116:117]
	v_pk_mul_f32 v[108:109], v[108:109], v[114:115]
	v_pk_mul_f32 v[114:115], v[106:107], v[120:121]
	v_pk_mul_f32 v[106:107], v[104:105], v[118:119]
	v_lshl_add_u64 v[112:113], v[112:113], 0, v[192:193]
	v_cvt_pk_bf16_f32 v104, v108, v109
	v_cvt_pk_bf16_f32 v105, v110, v111
	v_cvt_pk_bf16_f32 v106, v106, v107
	v_cvt_pk_bf16_f32 v107, v114, v115
	global_store_dwordx4 v[112:113], v[104:107], off
	v_lshlrev_b32_e32 v108, 16, v224
	v_and_b32_e32 v109, 0xffff0000, v224
	v_lshlrev_b32_e32 v104, 16, v222
	v_and_b32_e32 v105, 0xffff0000, v222
	v_lshlrev_b32_e32 v106, 16, v223
	v_and_b32_e32 v107, 0xffff0000, v223
	v_lshlrev_b32_e32 v110, 16, v225
	v_and_b32_e32 v111, 0xffff0000, v225
	v_pk_mul_f32 v[102:103], v[102:103], v[106:107]
	v_pk_mul_f32 v[100:101], v[100:101], v[104:105]
	v_pk_mul_f32 v[104:105], v[98:99], v[110:111]
	v_pk_mul_f32 v[98:99], v[96:97], v[108:109]
	v_cvt_pk_bf16_f32 v96, v100, v101
	v_cvt_pk_bf16_f32 v97, v102, v103
	v_cvt_pk_bf16_f32 v98, v98, v99
	v_cvt_pk_bf16_f32 v99, v104, v105
	global_store_dwordx4 v[112:113], v[96:99], off offset:256
	v_lshlrev_b32_e32 v100, 16, v227
	v_and_b32_e32 v101, 0xffff0000, v227
	v_lshlrev_b64 v[96:97], 12, v[234:235]
	v_lshlrev_b32_e32 v98, 16, v226
	v_and_b32_e32 v99, 0xffff0000, v226
	v_lshlrev_b32_e32 v102, 16, v228
	v_and_b32_e32 v103, 0xffff0000, v228
	v_lshlrev_b32_e32 v104, 16, v229
	v_and_b32_e32 v105, 0xffff0000, v229
	v_lshl_add_u64 v[96:97], s[10:11], 0, v[96:97]
	v_pk_mul_f32 v[94:95], v[94:95], v[100:101]
	v_pk_mul_f32 v[92:93], v[92:93], v[98:99]
	v_pk_mul_f32 v[98:99], v[90:91], v[104:105]
	v_pk_mul_f32 v[90:91], v[88:89], v[102:103]
	v_lshl_add_u64 v[96:97], v[96:97], 0, v[192:193]
	v_cvt_pk_bf16_f32 v88, v92, v93
	v_cvt_pk_bf16_f32 v89, v94, v95
	v_cvt_pk_bf16_f32 v90, v90, v91
	v_cvt_pk_bf16_f32 v91, v98, v99
	global_store_dwordx4 v[96:97], v[88:91], off
	v_lshlrev_b32_e32 v92, 16, v170
	v_and_b32_e32 v93, 0xffff0000, v170
	v_lshlrev_b32_e32 v88, 16, v168
	v_and_b32_e32 v89, 0xffff0000, v168
	v_lshlrev_b32_e32 v90, 16, v169
	v_and_b32_e32 v91, 0xffff0000, v169
	v_lshlrev_b32_e32 v94, 16, v171
	v_and_b32_e32 v95, 0xffff0000, v171
	v_pk_mul_f32 v[86:87], v[86:87], v[90:91]
	v_pk_mul_f32 v[84:85], v[84:85], v[88:89]
	v_pk_mul_f32 v[88:89], v[82:83], v[94:95]
	v_pk_mul_f32 v[82:83], v[80:81], v[92:93]
	v_cvt_pk_bf16_f32 v80, v84, v85
	v_cvt_pk_bf16_f32 v81, v86, v87
	v_cvt_pk_bf16_f32 v82, v82, v83
	v_cvt_pk_bf16_f32 v83, v88, v89
	global_store_dwordx4 v[96:97], v[80:83], off offset:256
	v_lshlrev_b32_e32 v84, 16, v165
	v_and_b32_e32 v85, 0xffff0000, v165
	v_lshlrev_b64 v[80:81], 12, v[202:203]
	v_lshlrev_b32_e32 v82, 16, v164
	v_and_b32_e32 v83, 0xffff0000, v164
	v_lshlrev_b32_e32 v86, 16, v166
	v_and_b32_e32 v87, 0xffff0000, v166
	v_lshlrev_b32_e32 v88, 16, v167
	v_and_b32_e32 v89, 0xffff0000, v167
	v_lshl_add_u64 v[80:81], s[10:11], 0, v[80:81]
	v_pk_mul_f32 v[78:79], v[78:79], v[84:85]
	v_pk_mul_f32 v[76:77], v[76:77], v[82:83]
	v_pk_mul_f32 v[82:83], v[74:75], v[88:89]
	v_pk_mul_f32 v[74:75], v[72:73], v[86:87]
	v_lshl_add_u64 v[80:81], v[80:81], 0, v[192:193]
	v_cvt_pk_bf16_f32 v72, v76, v77
	v_cvt_pk_bf16_f32 v73, v78, v79
	v_cvt_pk_bf16_f32 v74, v74, v75
	v_cvt_pk_bf16_f32 v75, v82, v83
	global_store_dwordx4 v[80:81], v[72:75], off
	v_lshlrev_b32_e32 v76, 16, v162
	v_and_b32_e32 v77, 0xffff0000, v162
	v_lshlrev_b32_e32 v72, 16, v160
	v_and_b32_e32 v73, 0xffff0000, v160
	v_lshlrev_b32_e32 v74, 16, v161
	v_and_b32_e32 v75, 0xffff0000, v161
	v_lshlrev_b32_e32 v78, 16, v163
	v_and_b32_e32 v79, 0xffff0000, v163
	v_pk_mul_f32 v[70:71], v[70:71], v[74:75]
	v_pk_mul_f32 v[68:69], v[68:69], v[72:73]
	v_pk_mul_f32 v[72:73], v[66:67], v[78:79]
	v_pk_mul_f32 v[66:67], v[64:65], v[76:77]
	v_cvt_pk_bf16_f32 v64, v68, v69
	v_cvt_pk_bf16_f32 v65, v70, v71
	v_cvt_pk_bf16_f32 v66, v66, v67
	v_cvt_pk_bf16_f32 v67, v72, v73
	global_store_dwordx4 v[80:81], v[64:67], off offset:256
	v_lshlrev_b32_e32 v68, 16, v157
	v_and_b32_e32 v69, 0xffff0000, v157
	v_lshlrev_b64 v[64:65], 12, v[200:201]
	v_lshlrev_b32_e32 v66, 16, v156
	v_and_b32_e32 v67, 0xffff0000, v156
	v_lshlrev_b32_e32 v70, 16, v158
	v_and_b32_e32 v71, 0xffff0000, v158
	v_lshlrev_b32_e32 v72, 16, v159
	v_and_b32_e32 v73, 0xffff0000, v159
	v_lshl_add_u64 v[64:65], s[10:11], 0, v[64:65]
	v_pk_mul_f32 v[62:63], v[62:63], v[68:69]
	v_pk_mul_f32 v[60:61], v[60:61], v[66:67]
	v_pk_mul_f32 v[66:67], v[58:59], v[72:73]
	v_pk_mul_f32 v[58:59], v[56:57], v[70:71]
	v_lshl_add_u64 v[64:65], v[64:65], 0, v[192:193]
	v_cvt_pk_bf16_f32 v56, v60, v61
	v_cvt_pk_bf16_f32 v57, v62, v63
	v_cvt_pk_bf16_f32 v58, v58, v59
	v_cvt_pk_bf16_f32 v59, v66, v67
	global_store_dwordx4 v[64:65], v[56:59], off
	v_lshlrev_b32_e32 v60, 16, v154
	v_and_b32_e32 v61, 0xffff0000, v154
; __device__ __forceinline__ void st_nt(float* p, f32x4 v) { __builtin_nontemporal_store(v, (f32x4*)p); }
; __device__ __forceinline__ void st_nt(bf16_t* p, u32x4 v) { __builtin_nontemporal_store(v, (u32x4*)p); }
; __device__ __forceinline__ u32x4 pack8(const f32x4 a, const f32x4 b) { u32x4 w; w.x = cvt_pk_bf16(a[0], a[1]); w.y = cvt_pk_bf16(a[2], a[3]); w.z = cvt_pk_bf16(b[0], b[1]); w.w = cvt_pk_bf16(b[2], b[3]); return w; }
; __device__ __forceinline__ void unpack8(const u32x4 w, f32x4& a, f32x4& b) { a = (f32x4){bf_lo(w.x), bf_hi(w.x), bf_lo(w.y), bf_hi(w.y)}; b = (f32x4){bf_lo(w.z), bf_hi(w.z), bf_lo(w.w), bf_hi(w.w)}; }
;     __device__ __forceinline__ void operator()(Acc& acc, const Unit& u, int wr, int wc, int fr, int fq, const float (&rsv)[8]) const {
;     ...
;         for (int g = 0; g < 8; ++g) { const int ai = g >> 2, m = g & 3; const int row = row0 + ai * HALF + m * 16;
; #pragma unroll
;             for (int bj = 0; bj < 2; ++bj) { f32x4 b0, b1; unpack8(gs[g][bj], b0, b1);
;                 st_nt(merged + (size_t)row * 2048 + col0 + bj * HALF, pack8(acc[ai][bj][m][0] * b0, acc[ai][bj][m][1] * b1)); } }
; template <class Epi>
; __device__ __forceinline__ void gemm_phase(LAS unsigned char* lds, const GSched& S, const int K, const int lda, const int ldb, const Epi& E) {
;     ...
;         if (!has_next) break;
	v_lshlrev_b32_e32 v56, 16, v152
	v_and_b32_e32 v57, 0xffff0000, v152
	v_lshlrev_b32_e32 v58, 16, v153
	v_and_b32_e32 v59, 0xffff0000, v153
	v_lshlrev_b32_e32 v62, 16, v155
	v_and_b32_e32 v63, 0xffff0000, v155
	v_pk_mul_f32 v[54:55], v[54:55], v[58:59]
	v_pk_mul_f32 v[52:53], v[52:53], v[56:57]
	v_pk_mul_f32 v[56:57], v[50:51], v[62:63]
	v_pk_mul_f32 v[50:51], v[48:49], v[60:61]
	v_cvt_pk_bf16_f32 v48, v52, v53
	v_cvt_pk_bf16_f32 v49, v54, v55
	v_cvt_pk_bf16_f32 v50, v50, v51
	v_cvt_pk_bf16_f32 v51, v56, v57
	global_store_dwordx4 v[64:65], v[48:51], off offset:256
	v_lshlrev_b32_e32 v52, 16, v149
	v_and_b32_e32 v53, 0xffff0000, v149
	v_lshlrev_b64 v[48:49], 12, v[198:199]
	v_lshlrev_b32_e32 v50, 16, v148
	v_and_b32_e32 v51, 0xffff0000, v148
	v_lshlrev_b32_e32 v54, 16, v150
	v_and_b32_e32 v55, 0xffff0000, v150
	v_lshlrev_b32_e32 v56, 16, v151
	v_and_b32_e32 v57, 0xffff0000, v151
	v_lshl_add_u64 v[48:49], s[10:11], 0, v[48:49]
	v_pk_mul_f32 v[46:47], v[46:47], v[52:53]
	v_pk_mul_f32 v[44:45], v[44:45], v[50:51]
	v_pk_mul_f32 v[50:51], v[42:43], v[56:57]
	v_pk_mul_f32 v[42:43], v[40:41], v[54:55]
	v_lshl_add_u64 v[48:49], v[48:49], 0, v[192:193]
	v_cvt_pk_bf16_f32 v40, v44, v45
	v_cvt_pk_bf16_f32 v41, v46, v47
	v_cvt_pk_bf16_f32 v42, v42, v43
	v_cvt_pk_bf16_f32 v43, v50, v51
	global_store_dwordx4 v[48:49], v[40:43], off
	v_lshlrev_b32_e32 v44, 16, v146
	v_and_b32_e32 v45, 0xffff0000, v146
	v_lshlrev_b32_e32 v40, 16, v144
	v_and_b32_e32 v41, 0xffff0000, v144
	v_lshlrev_b32_e32 v42, 16, v145
	v_and_b32_e32 v43, 0xffff0000, v145
	v_lshlrev_b32_e32 v46, 16, v147
	v_and_b32_e32 v47, 0xffff0000, v147
	v_pk_mul_f32 v[38:39], v[38:39], v[42:43]
	v_pk_mul_f32 v[36:37], v[36:37], v[40:41]
	v_pk_mul_f32 v[40:41], v[34:35], v[46:47]
	v_pk_mul_f32 v[34:35], v[32:33], v[44:45]
	v_cvt_pk_bf16_f32 v32, v36, v37
	v_cvt_pk_bf16_f32 v33, v38, v39
	v_cvt_pk_bf16_f32 v34, v34, v35
	v_cvt_pk_bf16_f32 v35, v40, v41
	global_store_dwordx4 v[48:49], v[32:35], off offset:256
	v_lshlrev_b32_e32 v36, 16, v141
	v_and_b32_e32 v37, 0xffff0000, v141
	v_lshlrev_b64 v[32:33], 12, v[196:197]
	v_lshlrev_b32_e32 v34, 16, v140
	v_and_b32_e32 v35, 0xffff0000, v140
	v_lshlrev_b32_e32 v38, 16, v142
	v_and_b32_e32 v39, 0xffff0000, v142
	v_lshlrev_b32_e32 v40, 16, v143
	v_and_b32_e32 v41, 0xffff0000, v143
	v_lshl_add_u64 v[32:33], s[10:11], 0, v[32:33]
	v_pk_mul_f32 v[30:31], v[30:31], v[36:37]
	v_pk_mul_f32 v[28:29], v[28:29], v[34:35]
	v_pk_mul_f32 v[34:35], v[26:27], v[40:41]
	v_pk_mul_f32 v[26:27], v[24:25], v[38:39]
	v_lshl_add_u64 v[32:33], v[32:33], 0, v[192:193]
	v_cvt_pk_bf16_f32 v24, v28, v29
	v_cvt_pk_bf16_f32 v25, v30, v31
	v_cvt_pk_bf16_f32 v26, v26, v27
	v_cvt_pk_bf16_f32 v27, v34, v35
	global_store_dwordx4 v[32:33], v[24:27], off
	v_lshlrev_b32_e32 v28, 16, v138
	v_and_b32_e32 v29, 0xffff0000, v138
	v_lshlrev_b32_e32 v24, 16, v136
	v_and_b32_e32 v25, 0xffff0000, v136
	v_lshlrev_b32_e32 v26, 16, v137
	v_and_b32_e32 v27, 0xffff0000, v137
	v_lshlrev_b32_e32 v30, 16, v139
	v_and_b32_e32 v31, 0xffff0000, v139
	v_pk_mul_f32 v[22:23], v[22:23], v[26:27]
	v_pk_mul_f32 v[20:21], v[20:21], v[24:25]
	v_pk_mul_f32 v[24:25], v[18:19], v[30:31]
	v_pk_mul_f32 v[18:19], v[16:17], v[28:29]
	v_cvt_pk_bf16_f32 v16, v20, v21
	v_cvt_pk_bf16_f32 v17, v22, v23
	v_cvt_pk_bf16_f32 v18, v18, v19
	v_cvt_pk_bf16_f32 v19, v24, v25
	global_store_dwordx4 v[32:33], v[16:19], off offset:256
	v_lshlrev_b32_e32 v20, 16, v133
	v_and_b32_e32 v21, 0xffff0000, v133
	v_lshlrev_b64 v[16:17], 12, v[194:195]
	v_lshlrev_b32_e32 v18, 16, v132
	v_and_b32_e32 v19, 0xffff0000, v132
	v_lshlrev_b32_e32 v22, 16, v134
	v_and_b32_e32 v23, 0xffff0000, v134
	v_lshlrev_b32_e32 v24, 16, v135
	v_and_b32_e32 v25, 0xffff0000, v135
	v_lshl_add_u64 v[16:17], s[10:11], 0, v[16:17]
	v_pk_mul_f32 v[14:15], v[14:15], v[20:21]
	v_pk_mul_f32 v[12:13], v[12:13], v[18:19]
	v_pk_mul_f32 v[18:19], v[10:11], v[24:25]
	v_pk_mul_f32 v[10:11], v[8:9], v[22:23]
	v_lshl_add_u64 v[16:17], v[16:17], 0, v[192:193]
	v_cvt_pk_bf16_f32 v8, v12, v13
	v_cvt_pk_bf16_f32 v9, v14, v15
	v_cvt_pk_bf16_f32 v10, v10, v11
	v_cvt_pk_bf16_f32 v11, v18, v19
	global_store_dwordx4 v[16:17], v[8:11], off
	v_lshlrev_b32_e32 v12, 16, v130
	v_and_b32_e32 v13, 0xffff0000, v130
	v_lshlrev_b32_e32 v8, 16, v128
	v_and_b32_e32 v9, 0xffff0000, v128
	v_lshlrev_b32_e32 v10, 16, v129
	v_and_b32_e32 v11, 0xffff0000, v129
	v_lshlrev_b32_e32 v14, 16, v131
	v_and_b32_e32 v15, 0xffff0000, v131
	v_pk_mul_f32 v[6:7], v[6:7], v[10:11]
	v_pk_mul_f32 v[4:5], v[4:5], v[8:9]
	v_pk_mul_f32 v[8:9], v[2:3], v[14:15]
	v_pk_mul_f32 v[2:3], v[0:1], v[12:13]
	v_cvt_pk_bf16_f32 v0, v4, v5
	v_cvt_pk_bf16_f32 v1, v6, v7
	v_cvt_pk_bf16_f32 v2, v2, v3
	v_cvt_pk_bf16_f32 v3, v8, v9
	s_and_b64 vcc, exec, s[6:7]
	s_mov_b32 s2, s55
	s_mov_b32 s24, s18
	s_mov_b64 s[26:27], s[20:21]
	s_mov_b64 s[28:29], s[22:23]
	global_store_dwordx4 v[16:17], v[0:3], off offset:256
	s_cbranch_vccnz .LBB0_866

; __device__ __forceinline__ f32x4 ld_nt(const float* p) { return __builtin_nontemporal_load((const f32x4*)p); }
; __device__ __forceinline__ u32x4 ld_nt(const bf16_t* p) { return __builtin_nontemporal_load((const u32x4*)p); }
; __device__ __forceinline__ void st_nt(float* p, f32x4 v) { __builtin_nontemporal_store(v, (f32x4*)p); }
; __device__ __forceinline__ void st_nt(bf16_t* p, u32x4 v) { __builtin_nontemporal_store(v, (u32x4*)p); }
; __device__ __forceinline__ float sigmoidf_(float v) { return __builtin_amdgcn_rcpf(1.0f + __builtin_amdgcn_exp2f(-1.4426950408889634f * v)); }
; __device__ __forceinline__ float sumsq4(const f32x4 v) { return (v[0] * v[0] + v[1] * v[1]) + (v[2] * v[2] + v[3] * v[3]); }
; __device__ __forceinline__ u32x4 pack8(const f32x4 a, const f32x4 b) { u32x4 w; w.x = cvt_pk_bf16(a[0], a[1]); w.y = cvt_pk_bf16(a[2], a[3]); w.z = cvt_pk_bf16(b[0], b[1]); w.w = cvt_pk_bf16(b[2], b[3]); return w; }
;     __device__ __forceinline__ void operator()(Acc& acc, const Unit& u, int wr, int wc, int fr, int fq, const float (&rsv)[8]) const {
;         const int row0 = u.pm * BM + wr * 64 + fr, col0 = u.pn * BM + wc * 32 + 8 * fq;
;         u32x4 hw[4][2], ew[4][2];
; #pragma unroll
;         for (int g = 0; g < 4; ++g) { const int r = row0 + (g >> 2) * HALF + (g & 3) * 16;
; #pragma unroll
;             for (int bj = 0; bj < 2; ++bj) { hw[g][bj] = *(const u32x4*)(hb + (size_t)r * LDHB + 256 + col0 + bj * HALF); ew[g][bj] = ld_nt(etmp + (size_t)r * DM + col0 + bj * HALF); } }
; #pragma unroll
;         for (int g = 0; g < 8; ++g) {
;             const int ai = g >> 2, m = g & 3, s = g & 3; const int row = row0 + ai * HALF + m * 16;
;             const float rs = rsv[ai * 4 + m]; float ss = 0.f;
; #pragma unroll
;             for (int bj = 0; bj < 2; ++bj) { const size_t off = (size_t)row * DM + col0 + bj * HALF;
;                 f32x4 e0, e1, v0, v1; unpack8(ew[s][bj], e0, e1); unpack8(hw[s][bj], v0, v1);
; #pragma unroll
;                 for (int jj = 0; jj < 4; ++jj) { v0[jj] += sigmoidf_(acc[ai][bj][m][0][jj] * rs) * e0[jj]; v1[jj] += sigmoidf_(acc[ai][bj][m][1][jj] * rs) * e1[jj]; }
;                 st_nt(h4b + off, pack8(v0, v1)); ss += sumsq4(v0) + sumsq4(v1); }
.LBB0_1206:
	v_or_b32_e32 v212, s38, v239
	v_ashrrev_i32_e32 v213, 31, v212
	v_mov_b64_e32 v[122:123], s[10:11]
	v_lshlrev_b64 v[216:217], 1, v[212:213]
	v_ashrrev_i32_e32 v215, 31, v214
	v_mad_i64_i32 v[124:125], s[0:1], v214, s71, v[122:123]
	v_lshl_add_u64 v[120:121], s[28:29], 0, v[216:217]
	v_lshl_add_u64 v[124:125], v[124:125], 0, v[216:217]
	v_lshlrev_b64 v[230:231], 12, v[214:215]
	v_lshl_add_u64 v[126:127], v[120:121], 0, v[230:231]
	global_load_dwordx4 v[184:187], v[124:125], off offset:512
	global_load_dwordx4 v[188:191], v[126:127], off nt
	global_load_dwordx4 v[176:179], v[124:125], off offset:768
	global_load_dwordx4 v[180:183], v[126:127], off offset:256 nt
	v_or_b32_e32 v226, 16, v214
	v_ashrrev_i32_e32 v227, 31, v226
	v_mad_i64_i32 v[124:125], s[0:1], v226, s71, v[122:123]
	v_lshl_add_u64 v[124:125], v[124:125], 0, v[216:217]
	v_lshlrev_b64 v[228:229], 12, v[226:227]
	v_or_b32_e32 v222, 32, v214
	v_or_b32_e32 v218, 48, v214
	v_lshl_add_u64 v[126:127], v[120:121], 0, v[228:229]
	global_load_dwordx4 v[168:171], v[124:125], off offset:512
	global_load_dwordx4 v[172:175], v[126:127], off nt
	global_load_dwordx4 v[160:163], v[124:125], off offset:768
	global_load_dwordx4 v[164:167], v[126:127], off offset:256 nt
	v_ashrrev_i32_e32 v223, 31, v222
	v_mad_i64_i32 v[124:125], s[0:1], v222, s71, v[122:123]
	v_ashrrev_i32_e32 v219, 31, v218
	v_lshl_add_u64 v[124:125], v[124:125], 0, v[216:217]
	v_lshlrev_b64 v[224:225], 12, v[222:223]
	v_mad_i64_i32 v[122:123], s[0:1], v218, s71, v[122:123]
	v_lshlrev_b64 v[220:221], 12, v[218:219]
	v_lshl_add_u64 v[126:127], v[120:121], 0, v[224:225]
	global_load_dwordx4 v[152:155], v[124:125], off offset:512
	global_load_dwordx4 v[156:159], v[126:127], off nt
	global_load_dwordx4 v[140:143], v[124:125], off offset:768
	global_load_dwordx4 v[144:147], v[126:127], off offset:256 nt
	v_lshl_add_u64 v[122:123], v[122:123], 0, v[216:217]
	v_lshl_add_u64 v[124:125], v[120:121], 0, v[220:221]
	global_load_dwordx4 v[132:135], v[122:123], off offset:512
	global_load_dwordx4 v[136:139], v[124:125], off nt
	s_nop 0
	global_load_dwordx4 v[120:123], v[122:123], off offset:768
	s_nop 0
	global_load_dwordx4 v[124:127], v[124:125], off offset:256 nt
	v_mul_f32_e32 v148, v243, v148
	v_mul_f32_e32 v149, v243, v149
	v_mul_f32_e32 v150, v243, v150
	v_mul_f32_e32 v151, v243, v151
	v_mul_f32_e32 v148, 0xbfb8aa3b, v148
	v_mul_f32_e32 v128, v243, v128
	v_mul_f32_e32 v149, 0xbfb8aa3b, v149
	v_mul_f32_e32 v129, v243, v129
	v_mul_f32_e32 v150, 0xbfb8aa3b, v150
	v_mul_f32_e32 v130, v243, v130
	v_mul_f32_e32 v151, 0xbfb8aa3b, v151
	v_mul_f32_e32 v131, v243, v131
	v_exp_f32_e32 v148, v148
	v_mul_f32_e32 v128, 0xbfb8aa3b, v128
	v_exp_f32_e32 v149, v149
	v_mul_f32_e32 v129, 0xbfb8aa3b, v129
	v_exp_f32_e32 v150, v150
	v_mul_f32_e32 v130, 0xbfb8aa3b, v130
	v_exp_f32_e32 v151, v151
	v_mul_f32_e32 v131, 0xbfb8aa3b, v131
	v_exp_f32_e32 v128, v128
	v_exp_f32_e32 v129, v129
	v_exp_f32_e32 v130, v130
	v_exp_f32_e32 v131, v131
	v_mul_f32_e32 v116, v243, v116
	v_mul_f32_e32 v117, v243, v117
	v_mul_f32_e32 v116, 0xbfb8aa3b, v116
	v_mul_f32_e32 v112, v243, v112
	v_mul_f32_e32 v117, 0xbfb8aa3b, v117
	v_mul_f32_e32 v113, v243, v113
	v_add_f32_e32 v148, 1.0, v148
	v_add_f32_e32 v149, 1.0, v149
	v_add_f32_e32 v150, 1.0, v150
	v_add_f32_e32 v151, 1.0, v151
	v_exp_f32_e32 v116, v116
	v_mul_f32_e32 v112, 0xbfb8aa3b, v112
	v_exp_f32_e32 v117, v117
	v_mul_f32_e32 v113, 0xbfb8aa3b, v113
	v_rcp_f32_e32 v148, v148
	v_add_f32_e32 v128, 1.0, v128
	v_rcp_f32_e32 v149, v149
	v_add_f32_e32 v129, 1.0, v129
	v_rcp_f32_e32 v150, v150
	v_add_f32_e32 v130, 1.0, v130
	v_rcp_f32_e32 v151, v151
	v_add_f32_e32 v131, 1.0, v131
	v_exp_f32_e32 v112, v112
	v_exp_f32_e32 v113, v113
	v_rcp_f32_e32 v128, v128
	v_rcp_f32_e32 v129, v129
	v_rcp_f32_e32 v130, v130
	v_rcp_f32_e32 v131, v131
	s_waitcnt vmcnt(0)
	v_lshlrev_b32_e32 v252, 16, v184
	v_lshlrev_b32_e32 v232, 16, v188
	v_and_b32_e32 v233, 0xffff0000, v188
	v_and_b32_e32 v253, 0xffff0000, v184
	v_lshlrev_b32_e32 v188, 16, v189
	v_and_b32_e32 v189, 0xffff0000, v189
	v_lshlrev_b32_e32 v184, 16, v185
	v_and_b32_e32 v185, 0xffff0000, v185
	v_add_f32_e32 v116, 1.0, v116
	v_add_f32_e32 v117, 1.0, v117
	v_pk_fma_f32 v[148:149], v[148:149], v[232:233], v[252:253]
	v_lshlrev_b32_e32 v232, 16, v190
	v_and_b32_e32 v233, 0xffff0000, v190
	v_lshlrev_b32_e32 v252, 16, v186
	v_and_b32_e32 v253, 0xffff0000, v186
	v_pk_fma_f32 v[150:151], v[150:151], v[188:189], v[184:185]
	v_lshlrev_b32_e32 v184, 16, v191
	v_and_b32_e32 v185, 0xffff0000, v191
	v_lshlrev_b32_e32 v186, 16, v187
	v_and_b32_e32 v187, 0xffff0000, v187
	v_rcp_f32_e32 v116, v116
	v_add_f32_e32 v112, 1.0, v112
	v_rcp_f32_e32 v117, v117
	v_add_f32_e32 v113, 1.0, v113
	v_pk_fma_f32 v[128:129], v[128:129], v[232:233], v[252:253]
	v_pk_fma_f32 v[130:131], v[130:131], v[184:185], v[186:187]
	v_lshl_add_u64 v[184:185], s[26:27], 0, v[230:231]
	v_rcp_f32_e32 v112, v112
	v_rcp_f32_e32 v113, v113
	v_lshl_add_u64 v[188:189], v[184:185], 0, v[216:217]
	v_cvt_pk_bf16_f32 v184, v148, v149
	v_cvt_pk_bf16_f32 v185, v150, v151
	v_cvt_pk_bf16_f32 v186, v128, v129
	v_cvt_pk_bf16_f32 v187, v130, v131
	global_store_dwordx4 v[188:189], v[184:187], off
	v_pk_mul_f32 v[128:129], v[128:129], v[128:129]
	v_pk_mul_f32 v[130:131], v[130:131], v[130:131]
	v_lshlrev_b32_e32 v184, 16, v180
	v_and_b32_e32 v185, 0xffff0000, v180
	v_lshlrev_b32_e32 v186, 16, v176
	v_and_b32_e32 v187, 0xffff0000, v176
	v_pk_fma_f32 v[116:117], v[116:117], v[184:185], v[186:187]
	v_lshlrev_b32_e32 v184, 16, v182
	v_and_b32_e32 v185, 0xffff0000, v182
	v_lshlrev_b32_e32 v186, 16, v178
	v_and_b32_e32 v187, 0xffff0000, v178
; __device__ __forceinline__ f32x4 ld_nt(const float* p) { return __builtin_nontemporal_load((const f32x4*)p); }
; __device__ __forceinline__ u32x4 ld_nt(const bf16_t* p) { return __builtin_nontemporal_load((const u32x4*)p); }
; __device__ __forceinline__ void st_nt(float* p, f32x4 v) { __builtin_nontemporal_store(v, (f32x4*)p); }
; __device__ __forceinline__ void st_nt(bf16_t* p, u32x4 v) { __builtin_nontemporal_store(v, (u32x4*)p); }
; __device__ __forceinline__ float sigmoidf_(float v) { return __builtin_amdgcn_rcpf(1.0f + __builtin_amdgcn_exp2f(-1.4426950408889634f * v)); }
; __device__ __forceinline__ float sumsq4(const f32x4 v) { return (v[0] * v[0] + v[1] * v[1]) + (v[2] * v[2] + v[3] * v[3]); }
; __device__ __forceinline__ u32x4 pack8(const f32x4 a, const f32x4 b) { u32x4 w; w.x = cvt_pk_bf16(a[0], a[1]); w.y = cvt_pk_bf16(a[2], a[3]); w.z = cvt_pk_bf16(b[0], b[1]); w.w = cvt_pk_bf16(b[2], b[3]); return w; }
; __device__ __forceinline__ void unpack8(const u32x4 w, f32x4& a, f32x4& b) { a = (f32x4){bf_lo(w.x), bf_hi(w.x), bf_lo(w.y), bf_hi(w.y)}; b = (f32x4){bf_lo(w.z), bf_hi(w.z), bf_lo(w.w), bf_hi(w.w)}; }
;     __device__ __forceinline__ void operator()(Acc& acc, const Unit& u, int wr, int wc, int fr, int fq, const float (&rsv)[8]) const {
;     ...
;             for (int bj = 0; bj < 2; ++bj) { const size_t off = (size_t)row * DM + col0 + bj * HALF;
;                 f32x4 e0, e1, v0, v1; unpack8(ew[s][bj], e0, e1); unpack8(hw[s][bj], v0, v1);
; #pragma unroll
;                 for (int jj = 0; jj < 4; ++jj) { v0[jj] += sigmoidf_(acc[ai][bj][m][0][jj] * rs) * e0[jj]; v1[jj] += sigmoidf_(acc[ai][bj][m][1][jj] * rs) * e1[jj]; }
;                 st_nt(h4b + off, pack8(v0, v1)); ss += sumsq4(v0) + sumsq4(v1); }
;             ss += __shfl_xor(ss, 16); ss += __shfl_xor(ss, 32);
;             if (fq == 0) part_out[(size_t)row * 32 + u.pn * 4 + wc] = ss;
;             asm volatile("" ::: "memory");
;             if (g + 4 < 8) { const int r = row0 + ((g + 4) >> 2) * HALF + ((g + 4) & 3) * 16;
; #pragma unroll
;                 for (int bj = 0; bj < 2; ++bj) { hw[s][bj] = *(const u32x4*)(hb + (size_t)r * LDHB + 256 + col0 + bj * HALF); ew[s][bj] = ld_nt(etmp + (size_t)r * DM + col0 + bj * HALF); } }
	v_pk_fma_f32 v[184:185], v[112:113], v[184:185], v[186:187]
	v_mul_f32_e32 v113, v243, v114
	v_mul_f32_e32 v113, 0xbfb8aa3b, v113
	v_exp_f32_e32 v113, v113
	v_mul_f32_e32 v112, v243, v118
	v_mul_f32_e32 v112, 0xbfb8aa3b, v112
	v_exp_f32_e32 v112, v112
	v_add_f32_e32 v113, 1.0, v113
	v_rcp_f32_e32 v114, v113
	v_mul_f32_e32 v113, v243, v119
	v_mul_f32_e32 v113, 0xbfb8aa3b, v113
	v_exp_f32_e32 v113, v113
	v_add_f32_e32 v112, 1.0, v112
	v_rcp_f32_e32 v112, v112
	v_lshlrev_b32_e32 v118, 16, v181
	v_add_f32_e32 v113, 1.0, v113
	v_rcp_f32_e32 v113, v113
	v_and_b32_e32 v119, 0xffff0000, v181
	v_lshlrev_b32_e32 v176, 16, v177
	v_and_b32_e32 v177, 0xffff0000, v177
	v_pk_fma_f32 v[118:119], v[112:113], v[118:119], v[176:177]
	v_mul_f32_e32 v112, v243, v115
	v_mul_f32_e32 v112, 0xbfb8aa3b, v112
	v_exp_f32_e32 v112, v112
	v_and_b32_e32 v113, 0xffff0000, v183
	v_lshlrev_b32_e32 v176, 16, v179
	v_and_b32_e32 v177, 0xffff0000, v179
	v_add_f32_e32 v112, 1.0, v112
	v_rcp_f32_e32 v115, v112
	v_lshlrev_b32_e32 v112, 16, v183
	v_pk_mul_f32 v[148:149], v[148:149], v[148:149]
	v_pk_mul_f32 v[150:151], v[150:151], v[150:151]
	v_pk_fma_f32 v[176:177], v[114:115], v[112:113], v[176:177]
	v_cvt_pk_bf16_f32 v112, v116, v117
	v_cvt_pk_bf16_f32 v113, v118, v119
	v_cvt_pk_bf16_f32 v114, v184, v185
	v_cvt_pk_bf16_f32 v115, v176, v177
	global_store_dwordx4 v[188:189], v[112:115], off offset:256
	s_nop 1
	v_pk_mul_f32 v[112:113], v[116:117], v[116:117]
	v_pk_mul_f32 v[114:115], v[118:119], v[118:119]
	v_add_f32_e32 v112, v112, v113
	v_add_f32_e32 v114, v114, v115
	v_pk_mul_f32 v[116:117], v[184:185], v[184:185]
	v_pk_mul_f32 v[118:119], v[176:177], v[176:177]
	v_add_f32_e32 v112, v112, v114
	v_add_f32_e32 v113, v130, v131
	v_add_f32_e32 v114, v128, v129
	v_add_f32_e32 v118, v118, v119
	v_add_f32_e32 v116, v116, v117
	v_add_f32_e32 v113, v114, v113
	v_add_f32_e32 v114, v150, v151
	v_add_f32_e32 v115, v148, v149
	v_add_f32_e32 v116, v116, v118
	v_add_f32_e32 v114, v115, v114
	v_add_f32_e32 v112, v112, v116
	v_add_f32_e32 v113, v114, v113
	v_add_f32_e32 v112, v113, v112
	ds_bpermute_b32 v113, v234, v112
	s_waitcnt lgkmcnt(0)
	v_add_f32_e32 v112, v112, v113
	ds_bpermute_b32 v113, v235, v112
	s_and_saveexec_b64 s[38:39], s[4:5]
	s_cbranch_execz .LBB0_1208
	s_waitcnt lgkmcnt(0)
	v_add_f32_e32 v114, v112, v113
	s_lshl_b32 s0, s56, 2
	v_lshlrev_b64 v[112:113], 7, v[214:215]
	s_ashr_i32 s1, s0, 31
	v_lshl_add_u64 v[112:113], s[30:31], 0, v[112:113]
	v_lshl_add_u64 v[112:113], s[0:1], 2, v[112:113]
	s_lshl_b32 s24, s57, 2
	v_lshl_add_u64 v[112:113], v[112:113], 0, s[24:25]
	global_store_dword v[112:113], v114, off
.LBB0_1208:
	s_or_b64 exec, exec, s[38:39]
	v_add_u32_e32 v176, 0x80, v214
	v_ashrrev_i32_e32 v177, 31, v176
	s_waitcnt lgkmcnt(0)
	v_mov_b64_e32 v[112:113], s[10:11]
	v_lshlrev_b64 v[178:179], 12, v[176:177]
	v_mad_i64_i32 v[112:113], s[0:1], v176, s71, v[112:113]
	v_lshl_add_u64 v[114:115], s[28:29], 0, v[178:179]
	v_lshl_add_u64 v[112:113], v[112:113], 0, v[216:217]
	v_lshl_add_u64 v[116:117], v[114:115], 0, v[216:217]
	global_load_dwordx4 v[128:131], v[112:113], off offset:512
	s_nop 0
	global_load_dwordx4 v[112:115], v[112:113], off offset:768
	s_nop 0
	global_load_dwordx4 v[148:151], v[116:117], off nt
	s_nop 0
	global_load_dwordx4 v[116:119], v[116:117], off offset:256 nt
	v_mul_f32_e32 v108, v244, v108
	v_mul_f32_e32 v109, v244, v109
	v_mul_f32_e32 v108, 0xbfb8aa3b, v108
	v_mul_f32_e32 v104, v244, v104
	v_mul_f32_e32 v109, 0xbfb8aa3b, v109
	v_mul_f32_e32 v105, v244, v105
	v_exp_f32_e32 v108, v108
	v_mul_f32_e32 v104, 0xbfb8aa3b, v104
	v_exp_f32_e32 v109, v109
	v_mul_f32_e32 v105, 0xbfb8aa3b, v105
	v_exp_f32_e32 v104, v104
	v_exp_f32_e32 v105, v105
	v_add_f32_e32 v108, 1.0, v108
	v_add_f32_e32 v109, 1.0, v109
	v_rcp_f32_e32 v108, v108
	v_add_f32_e32 v104, 1.0, v104
	v_rcp_f32_e32 v109, v109
	v_add_f32_e32 v105, 1.0, v105
	v_rcp_f32_e32 v104, v104
	v_rcp_f32_e32 v105, v105
	v_mul_f32_e32 v110, v244, v110
	v_lshlrev_b32_e32 v180, 16, v172
	v_and_b32_e32 v181, 0xffff0000, v172
	v_lshlrev_b32_e32 v182, 16, v168
	v_and_b32_e32 v183, 0xffff0000, v168
	v_mul_f32_e32 v110, 0xbfb8aa3b, v110
	v_pk_fma_f32 v[108:109], v[108:109], v[180:181], v[182:183]
	v_lshlrev_b32_e32 v180, 16, v174
	v_and_b32_e32 v181, 0xffff0000, v174
	v_exp_f32_e32 v110, v110
	v_lshlrev_b32_e32 v182, 16, v170
	v_and_b32_e32 v183, 0xffff0000, v170
	v_pk_fma_f32 v[180:181], v[104:105], v[180:181], v[182:183]
	v_mul_f32_e32 v105, v244, v106
	v_mul_f32_e32 v105, 0xbfb8aa3b, v105
	v_mul_f32_e32 v106, v244, v111
	v_exp_f32_e32 v105, v105
	v_mul_f32_e32 v106, 0xbfb8aa3b, v106
	v_add_f32_e32 v104, 1.0, v110
	v_exp_f32_e32 v110, v106
	v_mul_f32_e32 v100, v244, v100
	v_mul_f32_e32 v101, v244, v101
	v_mul_f32_e32 v100, 0xbfb8aa3b, v100
	v_mul_f32_e32 v96, v244, v96
	v_mul_f32_e32 v101, 0xbfb8aa3b, v101
	v_mul_f32_e32 v97, v244, v97
	v_exp_f32_e32 v100, v100
	v_mul_f32_e32 v96, 0xbfb8aa3b, v96
	v_exp_f32_e32 v101, v101
	v_mul_f32_e32 v97, 0xbfb8aa3b, v97
	v_add_f32_e32 v105, 1.0, v105
	v_mul_f32_e32 v107, v244, v107
	v_exp_f32_e32 v96, v96
	v_exp_f32_e32 v97, v97
	v_rcp_f32_e32 v106, v105
	v_add_f32_e32 v105, 1.0, v110
	v_mul_f32_e32 v107, 0xbfb8aa3b, v107
	v_rcp_f32_e32 v104, v104
	v_rcp_f32_e32 v105, v105
	v_exp_f32_e32 v107, v107
	v_add_f32_e32 v100, 1.0, v100
	v_add_f32_e32 v101, 1.0, v101
	v_rcp_f32_e32 v100, v100
	v_add_f32_e32 v96, 1.0, v96
	v_rcp_f32_e32 v101, v101
	v_add_f32_e32 v97, 1.0, v97
	v_lshlrev_b32_e32 v110, 16, v173
	v_and_b32_e32 v111, 0xffff0000, v173
	v_lshlrev_b32_e32 v168, 16, v169
	v_and_b32_e32 v169, 0xffff0000, v169
	v_rcp_f32_e32 v96, v96
	v_rcp_f32_e32 v97, v97
; __device__ __forceinline__ f32x4 ld_nt(const float* p) { return __builtin_nontemporal_load((const f32x4*)p); }
; __device__ __forceinline__ u32x4 ld_nt(const bf16_t* p) { return __builtin_nontemporal_load((const u32x4*)p); }
; __device__ __forceinline__ void st_nt(float* p, f32x4 v) { __builtin_nontemporal_store(v, (f32x4*)p); }
; __device__ __forceinline__ void st_nt(bf16_t* p, u32x4 v) { __builtin_nontemporal_store(v, (u32x4*)p); }
; __device__ __forceinline__ float sigmoidf_(float v) { return __builtin_amdgcn_rcpf(1.0f + __builtin_amdgcn_exp2f(-1.4426950408889634f * v)); }
; __device__ __forceinline__ float sumsq4(const f32x4 v) { return (v[0] * v[0] + v[1] * v[1]) + (v[2] * v[2] + v[3] * v[3]); }
; __device__ __forceinline__ u32x4 pack8(const f32x4 a, const f32x4 b) { u32x4 w; w.x = cvt_pk_bf16(a[0], a[1]); w.y = cvt_pk_bf16(a[2], a[3]); w.z = cvt_pk_bf16(b[0], b[1]); w.w = cvt_pk_bf16(b[2], b[3]); return w; }
;     __device__ __forceinline__ void operator()(Acc& acc, const Unit& u, int wr, int wc, int fr, int fq, const float (&rsv)[8]) const {
;     ...
; #pragma unroll
;         for (int g = 0; g < 8; ++g) {
;             const int ai = g >> 2, m = g & 3, s = g & 3; const int row = row0 + ai * HALF + m * 16;
;             const float rs = rsv[ai * 4 + m]; float ss = 0.f;
; #pragma unroll
;             for (int bj = 0; bj < 2; ++bj) { const size_t off = (size_t)row * DM + col0 + bj * HALF;
;                 f32x4 e0, e1, v0, v1; unpack8(ew[s][bj], e0, e1); unpack8(hw[s][bj], v0, v1);
; #pragma unroll
;                 for (int jj = 0; jj < 4; ++jj) { v0[jj] += sigmoidf_(acc[ai][bj][m][0][jj] * rs) * e0[jj]; v1[jj] += sigmoidf_(acc[ai][bj][m][1][jj] * rs) * e1[jj]; }
;                 st_nt(h4b + off, pack8(v0, v1)); ss += sumsq4(v0) + sumsq4(v1); }
;             ss += __shfl_xor(ss, 16); ss += __shfl_xor(ss, 32);
;             if (fq == 0) part_out[(size_t)row * 32 + u.pn * 4 + wc] = ss;
;             asm volatile("" ::: "memory");
;             if (g + 4 < 8) { const int r = row0 + ((g + 4) >> 2) * HALF + ((g + 4) & 3) * 16;
; #pragma unroll
;                 for (int bj = 0; bj < 2; ++bj) { hw[s][bj] = *(const u32x4*)(hb + (size_t)r * LDHB + 256 + col0 + bj * HALF); ew[s][bj] = ld_nt(etmp + (size_t)r * DM + col0 + bj * HALF); } }
	v_pk_fma_f32 v[110:111], v[104:105], v[110:111], v[168:169]
	v_add_f32_e32 v104, 1.0, v107
	v_mul_f32_e32 v102, v244, v102
	v_rcp_f32_e32 v107, v104
	v_lshlrev_b32_e32 v104, 16, v175
	v_and_b32_e32 v105, 0xffff0000, v175
	v_lshlrev_b32_e32 v174, 16, v164
	v_and_b32_e32 v175, 0xffff0000, v164
	v_lshlrev_b32_e32 v182, 16, v160
	v_and_b32_e32 v183, 0xffff0000, v160
	v_mul_f32_e32 v102, 0xbfb8aa3b, v102
	v_pk_fma_f32 v[100:101], v[100:101], v[174:175], v[182:183]
	v_lshlrev_b32_e32 v174, 16, v166
	v_and_b32_e32 v175, 0xffff0000, v166
	v_exp_f32_e32 v102, v102
	v_lshlrev_b32_e32 v182, 16, v162
	v_and_b32_e32 v183, 0xffff0000, v162
	v_pk_fma_f32 v[174:175], v[96:97], v[174:175], v[182:183]
	v_mul_f32_e32 v97, v244, v98
	v_mul_f32_e32 v97, 0xbfb8aa3b, v97
	v_mul_f32_e32 v98, v244, v103
	v_exp_f32_e32 v97, v97
	v_mul_f32_e32 v98, 0xbfb8aa3b, v98
	v_add_f32_e32 v96, 1.0, v102
	v_exp_f32_e32 v102, v98
	v_add_f32_e32 v97, 1.0, v97
	v_mul_f32_e32 v99, v244, v99
	v_rcp_f32_e32 v98, v97
	v_add_f32_e32 v97, 1.0, v102
	v_mul_f32_e32 v99, 0xbfb8aa3b, v99
	v_rcp_f32_e32 v96, v96
	v_rcp_f32_e32 v97, v97
	v_exp_f32_e32 v99, v99
	v_lshlrev_b32_e32 v102, 16, v165
	v_and_b32_e32 v103, 0xffff0000, v165
	v_lshlrev_b32_e32 v160, 16, v161
	v_and_b32_e32 v161, 0xffff0000, v161
	v_pk_fma_f32 v[102:103], v[96:97], v[102:103], v[160:161]
	v_add_f32_e32 v96, 1.0, v99
	v_rcp_f32_e32 v99, v96
	v_lshlrev_b32_e32 v168, 16, v171
	v_and_b32_e32 v169, 0xffff0000, v171
	v_lshlrev_b32_e32 v96, 16, v167
	v_and_b32_e32 v97, 0xffff0000, v167
	v_lshlrev_b32_e32 v160, 16, v163
	v_and_b32_e32 v161, 0xffff0000, v163
	v_pk_fma_f32 v[168:169], v[106:107], v[104:105], v[168:169]
	v_lshl_add_u64 v[104:105], s[26:27], 0, v[228:229]
	v_pk_fma_f32 v[160:161], v[98:99], v[96:97], v[160:161]
	v_pk_mul_f32 v[96:97], v[100:101], v[100:101]
	v_pk_mul_f32 v[98:99], v[102:103], v[102:103]
	v_lshl_add_u64 v[170:171], v[104:105], 0, v[216:217]
	v_cvt_pk_bf16_f32 v104, v108, v109
	v_cvt_pk_bf16_f32 v105, v110, v111
	v_pk_mul_f32 v[106:107], v[108:109], v[108:109]
	v_pk_mul_f32 v[108:109], v[110:111], v[110:111]
	v_pk_mul_f32 v[110:111], v[180:181], v[180:181]
	v_pk_mul_f32 v[172:173], v[168:169], v[168:169]
	v_add_f32_e32 v98, v98, v99
	v_add_f32_e32 v96, v96, v97
	v_pk_mul_f32 v[162:163], v[174:175], v[174:175]
	v_pk_mul_f32 v[164:165], v[160:161], v[160:161]
	v_add_f32_e32 v96, v96, v98
	v_add_f32_e32 v97, v172, v173
	v_add_f32_e32 v98, v110, v111
	v_add_f32_e32 v164, v164, v165
	v_add_f32_e32 v162, v162, v163
	v_add_f32_e32 v97, v98, v97
	v_add_f32_e32 v98, v108, v109
	v_add_f32_e32 v99, v106, v107
	v_add_f32_e32 v162, v162, v164
	v_add_f32_e32 v98, v99, v98
	v_add_f32_e32 v96, v96, v162
	v_add_f32_e32 v97, v98, v97
	v_add_f32_e32 v96, v97, v96
	ds_bpermute_b32 v97, v234, v96
	v_cvt_pk_bf16_f32 v106, v180, v181
	v_cvt_pk_bf16_f32 v107, v168, v169
	v_cvt_pk_bf16_f32 v98, v100, v101
	v_cvt_pk_bf16_f32 v99, v102, v103
	s_waitcnt lgkmcnt(0)
	v_add_f32_e32 v96, v96, v97
	ds_bpermute_b32 v97, v235, v96
	v_cvt_pk_bf16_f32 v100, v174, v175
	v_cvt_pk_bf16_f32 v101, v160, v161
	global_store_dwordx4 v[170:171], v[104:107], off
	global_store_dwordx4 v[170:171], v[98:101], off offset:256
	s_and_saveexec_b64 s[38:39], s[4:5]
	s_cbranch_execz .LBB0_1210
	s_waitcnt lgkmcnt(0)
	v_add_f32_e32 v98, v96, v97
	s_lshl_b32 s0, s56, 2
	v_lshlrev_b64 v[96:97], 7, v[226:227]
	s_ashr_i32 s1, s0, 31
	v_lshl_add_u64 v[96:97], s[30:31], 0, v[96:97]
	v_lshl_add_u64 v[96:97], s[0:1], 2, v[96:97]
	s_lshl_b32 s24, s57, 2
	v_lshl_add_u64 v[96:97], v[96:97], 0, s[24:25]
	global_store_dword v[96:97], v98, off
.LBB0_1210:
	s_or_b64 exec, exec, s[38:39]
	v_or_b32_e32 v160, 16, v176
	v_ashrrev_i32_e32 v161, 31, v160
	s_waitcnt lgkmcnt(0)
	v_mov_b64_e32 v[96:97], s[10:11]
	v_lshlrev_b64 v[162:163], 12, v[160:161]
	v_mad_i64_i32 v[96:97], s[0:1], v160, s71, v[96:97]
	v_lshl_add_u64 v[98:99], s[28:29], 0, v[162:163]
	v_lshl_add_u64 v[96:97], v[96:97], 0, v[216:217]
	v_lshl_add_u64 v[100:101], v[98:99], 0, v[216:217]
	global_load_dwordx4 v[104:107], v[96:97], off offset:512
	s_nop 0
	global_load_dwordx4 v[96:99], v[96:97], off offset:768
	s_nop 0
	global_load_dwordx4 v[108:111], v[100:101], off nt
	s_nop 0
	global_load_dwordx4 v[100:103], v[100:101], off offset:256 nt
	v_mul_f32_e32 v92, v245, v92
	v_mul_f32_e32 v93, v245, v93
	v_mul_f32_e32 v92, 0xbfb8aa3b, v92
	v_mul_f32_e32 v88, v245, v88
	v_mul_f32_e32 v93, 0xbfb8aa3b, v93
	v_mul_f32_e32 v89, v245, v89
	v_exp_f32_e32 v92, v92
	v_mul_f32_e32 v88, 0xbfb8aa3b, v88
	v_exp_f32_e32 v93, v93
	v_mul_f32_e32 v89, 0xbfb8aa3b, v89
	v_exp_f32_e32 v88, v88
	v_exp_f32_e32 v89, v89
	v_add_f32_e32 v92, 1.0, v92
	v_add_f32_e32 v93, 1.0, v93
	v_rcp_f32_e32 v92, v92
	v_add_f32_e32 v88, 1.0, v88
	v_rcp_f32_e32 v93, v93
	v_add_f32_e32 v89, 1.0, v89
	v_rcp_f32_e32 v88, v88
	v_rcp_f32_e32 v89, v89
	v_mul_f32_e32 v94, v245, v94
	v_lshlrev_b32_e32 v164, 16, v156
	v_and_b32_e32 v165, 0xffff0000, v156
	v_lshlrev_b32_e32 v166, 16, v152
	v_and_b32_e32 v167, 0xffff0000, v152
	v_mul_f32_e32 v94, 0xbfb8aa3b, v94
	v_pk_fma_f32 v[92:93], v[92:93], v[164:165], v[166:167]
	v_lshlrev_b32_e32 v164, 16, v158
	v_and_b32_e32 v165, 0xffff0000, v158
	v_exp_f32_e32 v94, v94
	v_lshlrev_b32_e32 v166, 16, v154
	v_and_b32_e32 v167, 0xffff0000, v154
	v_pk_fma_f32 v[164:165], v[88:89], v[164:165], v[166:167]
	v_mul_f32_e32 v89, v245, v90
	v_mul_f32_e32 v89, 0xbfb8aa3b, v89
	v_mul_f32_e32 v90, v245, v95
	v_exp_f32_e32 v89, v89
	v_mul_f32_e32 v90, 0xbfb8aa3b, v90
	v_add_f32_e32 v88, 1.0, v94
	v_exp_f32_e32 v94, v90
	v_mul_f32_e32 v84, v245, v84
	v_mul_f32_e32 v85, v245, v85
	v_mul_f32_e32 v84, 0xbfb8aa3b, v84
	v_mul_f32_e32 v80, v245, v80
; __device__ __forceinline__ void st_nt(float* p, f32x4 v) { __builtin_nontemporal_store(v, (f32x4*)p); }
; __device__ __forceinline__ void st_nt(bf16_t* p, u32x4 v) { __builtin_nontemporal_store(v, (u32x4*)p); }
; __device__ __forceinline__ float sigmoidf_(float v) { return __builtin_amdgcn_rcpf(1.0f + __builtin_amdgcn_exp2f(-1.4426950408889634f * v)); }
; __device__ __forceinline__ float sumsq4(const f32x4 v) { return (v[0] * v[0] + v[1] * v[1]) + (v[2] * v[2] + v[3] * v[3]); }
; __device__ __forceinline__ u32x4 pack8(const f32x4 a, const f32x4 b) { u32x4 w; w.x = cvt_pk_bf16(a[0], a[1]); w.y = cvt_pk_bf16(a[2], a[3]); w.z = cvt_pk_bf16(b[0], b[1]); w.w = cvt_pk_bf16(b[2], b[3]); return w; }
; __device__ __forceinline__ void unpack8(const u32x4 w, f32x4& a, f32x4& b) { a = (f32x4){bf_lo(w.x), bf_hi(w.x), bf_lo(w.y), bf_hi(w.y)}; b = (f32x4){bf_lo(w.z), bf_hi(w.z), bf_lo(w.w), bf_hi(w.w)}; }
;     __device__ __forceinline__ void operator()(Acc& acc, const Unit& u, int wr, int wc, int fr, int fq, const float (&rsv)[8]) const {
;     ...
; #pragma unroll
;         for (int g = 0; g < 8; ++g) {
;             const int ai = g >> 2, m = g & 3, s = g & 3; const int row = row0 + ai * HALF + m * 16;
;             const float rs = rsv[ai * 4 + m]; float ss = 0.f;
; #pragma unroll
;             for (int bj = 0; bj < 2; ++bj) { const size_t off = (size_t)row * DM + col0 + bj * HALF;
;                 f32x4 e0, e1, v0, v1; unpack8(ew[s][bj], e0, e1); unpack8(hw[s][bj], v0, v1);
; #pragma unroll
;                 for (int jj = 0; jj < 4; ++jj) { v0[jj] += sigmoidf_(acc[ai][bj][m][0][jj] * rs) * e0[jj]; v1[jj] += sigmoidf_(acc[ai][bj][m][1][jj] * rs) * e1[jj]; }
;                 st_nt(h4b + off, pack8(v0, v1)); ss += sumsq4(v0) + sumsq4(v1); }
;             ss += __shfl_xor(ss, 16); ss += __shfl_xor(ss, 32);
;             if (fq == 0) part_out[(size_t)row * 32 + u.pn * 4 + wc] = ss;
;             asm volatile("" ::: "memory");
	v_mul_f32_e32 v85, 0xbfb8aa3b, v85
	v_mul_f32_e32 v81, v245, v81
	v_exp_f32_e32 v84, v84
	v_mul_f32_e32 v80, 0xbfb8aa3b, v80
	v_exp_f32_e32 v85, v85
	v_mul_f32_e32 v81, 0xbfb8aa3b, v81
	v_add_f32_e32 v89, 1.0, v89
	v_mul_f32_e32 v91, v245, v91
	v_exp_f32_e32 v80, v80
	v_exp_f32_e32 v81, v81
	v_rcp_f32_e32 v90, v89
	v_add_f32_e32 v89, 1.0, v94
	v_mul_f32_e32 v91, 0xbfb8aa3b, v91
	v_rcp_f32_e32 v88, v88
	v_rcp_f32_e32 v89, v89
	v_exp_f32_e32 v91, v91
	v_add_f32_e32 v84, 1.0, v84
	v_add_f32_e32 v85, 1.0, v85
	v_rcp_f32_e32 v84, v84
	v_add_f32_e32 v80, 1.0, v80
	v_rcp_f32_e32 v85, v85
	v_add_f32_e32 v81, 1.0, v81
	v_lshlrev_b32_e32 v94, 16, v157
	v_and_b32_e32 v95, 0xffff0000, v157
	v_lshlrev_b32_e32 v152, 16, v153
	v_and_b32_e32 v153, 0xffff0000, v153
	v_rcp_f32_e32 v80, v80
	v_rcp_f32_e32 v81, v81
	v_pk_fma_f32 v[94:95], v[88:89], v[94:95], v[152:153]
	v_add_f32_e32 v88, 1.0, v91
	v_mul_f32_e32 v86, v245, v86
	v_rcp_f32_e32 v91, v88
	v_lshlrev_b32_e32 v88, 16, v159
	v_and_b32_e32 v89, 0xffff0000, v159
	v_lshlrev_b32_e32 v158, 16, v144
	v_and_b32_e32 v159, 0xffff0000, v144
	v_lshlrev_b32_e32 v166, 16, v140
	v_and_b32_e32 v167, 0xffff0000, v140
	v_mul_f32_e32 v86, 0xbfb8aa3b, v86
	v_pk_fma_f32 v[84:85], v[84:85], v[158:159], v[166:167]
	v_lshlrev_b32_e32 v158, 16, v146
	v_and_b32_e32 v159, 0xffff0000, v146
	v_exp_f32_e32 v86, v86
	v_lshlrev_b32_e32 v166, 16, v142
	v_and_b32_e32 v167, 0xffff0000, v142
	v_pk_fma_f32 v[158:159], v[80:81], v[158:159], v[166:167]
	v_mul_f32_e32 v81, v245, v82
	v_mul_f32_e32 v81, 0xbfb8aa3b, v81
	v_mul_f32_e32 v82, v245, v87
	v_exp_f32_e32 v81, v81
	v_mul_f32_e32 v82, 0xbfb8aa3b, v82
	v_add_f32_e32 v80, 1.0, v86
	v_exp_f32_e32 v86, v82
	v_add_f32_e32 v81, 1.0, v81
	v_mul_f32_e32 v83, v245, v83
	v_rcp_f32_e32 v82, v81
	v_add_f32_e32 v81, 1.0, v86
	v_mul_f32_e32 v83, 0xbfb8aa3b, v83
	v_rcp_f32_e32 v80, v80
	v_rcp_f32_e32 v81, v81
	v_exp_f32_e32 v83, v83
	v_lshlrev_b32_e32 v86, 16, v145
	v_and_b32_e32 v87, 0xffff0000, v145
	v_lshlrev_b32_e32 v140, 16, v141
	v_and_b32_e32 v141, 0xffff0000, v141
	v_pk_fma_f32 v[86:87], v[80:81], v[86:87], v[140:141]
	v_add_f32_e32 v80, 1.0, v83
	v_rcp_f32_e32 v83, v80
	v_lshlrev_b32_e32 v152, 16, v155
	v_and_b32_e32 v153, 0xffff0000, v155
	v_lshlrev_b32_e32 v80, 16, v147
	v_and_b32_e32 v81, 0xffff0000, v147
	v_lshlrev_b32_e32 v140, 16, v143
	v_and_b32_e32 v141, 0xffff0000, v143
	v_pk_fma_f32 v[152:153], v[90:91], v[88:89], v[152:153]
	v_lshl_add_u64 v[88:89], s[26:27], 0, v[224:225]
	v_pk_fma_f32 v[140:141], v[82:83], v[80:81], v[140:141]
	v_pk_mul_f32 v[80:81], v[84:85], v[84:85]
	v_pk_mul_f32 v[82:83], v[86:87], v[86:87]
	v_lshl_add_u64 v[154:155], v[88:89], 0, v[216:217]
	v_cvt_pk_bf16_f32 v88, v92, v93
	v_cvt_pk_bf16_f32 v89, v94, v95
	v_pk_mul_f32 v[90:91], v[92:93], v[92:93]
	v_pk_mul_f32 v[92:93], v[94:95], v[94:95]
	v_pk_mul_f32 v[94:95], v[164:165], v[164:165]
	v_pk_mul_f32 v[156:157], v[152:153], v[152:153]
	v_add_f32_e32 v82, v82, v83
	v_add_f32_e32 v80, v80, v81
	v_pk_mul_f32 v[142:143], v[158:159], v[158:159]
	v_pk_mul_f32 v[144:145], v[140:141], v[140:141]
	v_add_f32_e32 v80, v80, v82
	v_add_f32_e32 v81, v156, v157
	v_add_f32_e32 v82, v94, v95
	v_add_f32_e32 v144, v144, v145
	v_add_f32_e32 v142, v142, v143
	v_add_f32_e32 v81, v82, v81
	v_add_f32_e32 v82, v92, v93
	v_add_f32_e32 v83, v90, v91
	v_add_f32_e32 v142, v142, v144
	v_add_f32_e32 v82, v83, v82
	v_add_f32_e32 v80, v80, v142
	v_add_f32_e32 v81, v82, v81
	v_add_f32_e32 v80, v81, v80
	ds_bpermute_b32 v81, v234, v80
	v_cvt_pk_bf16_f32 v90, v164, v165
	v_cvt_pk_bf16_f32 v91, v152, v153
	v_cvt_pk_bf16_f32 v82, v84, v85
	v_cvt_pk_bf16_f32 v83, v86, v87
	s_waitcnt lgkmcnt(0)
	v_add_f32_e32 v80, v80, v81
	ds_bpermute_b32 v81, v235, v80
	v_cvt_pk_bf16_f32 v84, v158, v159
	v_cvt_pk_bf16_f32 v85, v140, v141
	global_store_dwordx4 v[154:155], v[88:91], off
	global_store_dwordx4 v[154:155], v[82:85], off offset:256
	s_and_saveexec_b64 s[38:39], s[4:5]
	s_cbranch_execz .LBB0_1212
	s_waitcnt lgkmcnt(0)
	v_add_f32_e32 v82, v80, v81
	s_lshl_b32 s0, s56, 2
	v_lshlrev_b64 v[80:81], 7, v[222:223]
	s_ashr_i32 s1, s0, 31
	v_lshl_add_u64 v[80:81], s[30:31], 0, v[80:81]
	v_lshl_add_u64 v[80:81], s[0:1], 2, v[80:81]
	s_lshl_b32 s24, s57, 2
	v_lshl_add_u64 v[80:81], v[80:81], 0, s[24:25]
	global_store_dword v[80:81], v82, off
; __device__ __forceinline__ f32x4 ld_nt(const float* p) { return __builtin_nontemporal_load((const f32x4*)p); }
; __device__ __forceinline__ u32x4 ld_nt(const bf16_t* p) { return __builtin_nontemporal_load((const u32x4*)p); }
; __device__ __forceinline__ void st_nt(float* p, f32x4 v) { __builtin_nontemporal_store(v, (f32x4*)p); }
; __device__ __forceinline__ void st_nt(bf16_t* p, u32x4 v) { __builtin_nontemporal_store(v, (u32x4*)p); }
; __device__ __forceinline__ float sigmoidf_(float v) { return __builtin_amdgcn_rcpf(1.0f + __builtin_amdgcn_exp2f(-1.4426950408889634f * v)); }
; __device__ __forceinline__ float sumsq4(const f32x4 v) { return (v[0] * v[0] + v[1] * v[1]) + (v[2] * v[2] + v[3] * v[3]); }
; __device__ __forceinline__ u32x4 pack8(const f32x4 a, const f32x4 b) { u32x4 w; w.x = cvt_pk_bf16(a[0], a[1]); w.y = cvt_pk_bf16(a[2], a[3]); w.z = cvt_pk_bf16(b[0], b[1]); w.w = cvt_pk_bf16(b[2], b[3]); return w; }
;     __device__ __forceinline__ void operator()(Acc& acc, const Unit& u, int wr, int wc, int fr, int fq, const float (&rsv)[8]) const {
;     ...
; #pragma unroll
;         for (int g = 0; g < 8; ++g) {
;             const int ai = g >> 2, m = g & 3, s = g & 3; const int row = row0 + ai * HALF + m * 16;
;             const float rs = rsv[ai * 4 + m]; float ss = 0.f;
; #pragma unroll
;             for (int bj = 0; bj < 2; ++bj) { const size_t off = (size_t)row * DM + col0 + bj * HALF;
;                 f32x4 e0, e1, v0, v1; unpack8(ew[s][bj], e0, e1); unpack8(hw[s][bj], v0, v1);
; #pragma unroll
;                 for (int jj = 0; jj < 4; ++jj) { v0[jj] += sigmoidf_(acc[ai][bj][m][0][jj] * rs) * e0[jj]; v1[jj] += sigmoidf_(acc[ai][bj][m][1][jj] * rs) * e1[jj]; }
;                 st_nt(h4b + off, pack8(v0, v1)); ss += sumsq4(v0) + sumsq4(v1); }
;             ss += __shfl_xor(ss, 16); ss += __shfl_xor(ss, 32);
;             if (fq == 0) part_out[(size_t)row * 32 + u.pn * 4 + wc] = ss;
;             asm volatile("" ::: "memory");
;             if (g + 4 < 8) { const int r = row0 + ((g + 4) >> 2) * HALF + ((g + 4) & 3) * 16;
; #pragma unroll
;                 for (int bj = 0; bj < 2; ++bj) { hw[s][bj] = *(const u32x4*)(hb + (size_t)r * LDHB + 256 + col0 + bj * HALF); ew[s][bj] = ld_nt(etmp + (size_t)r * DM + col0 + bj * HALF); } }
.LBB0_1212:
	s_or_b64 exec, exec, s[38:39]
	v_or_b32_e32 v140, 32, v176
	v_ashrrev_i32_e32 v141, 31, v140
	s_waitcnt lgkmcnt(0)
	v_mov_b64_e32 v[80:81], s[10:11]
	v_lshlrev_b64 v[142:143], 12, v[140:141]
	v_mad_i64_i32 v[80:81], s[0:1], v140, s71, v[80:81]
	v_lshl_add_u64 v[82:83], s[28:29], 0, v[142:143]
	v_lshl_add_u64 v[80:81], v[80:81], 0, v[216:217]
	v_lshl_add_u64 v[84:85], v[82:83], 0, v[216:217]
	global_load_dwordx4 v[88:91], v[80:81], off offset:512
	s_nop 0
	global_load_dwordx4 v[80:83], v[80:81], off offset:768
	s_nop 0
	global_load_dwordx4 v[92:95], v[84:85], off nt
	s_nop 0
	global_load_dwordx4 v[84:87], v[84:85], off offset:256 nt
	v_mul_f32_e32 v76, v246, v76
	v_mul_f32_e32 v77, v246, v77
	v_mul_f32_e32 v76, 0xbfb8aa3b, v76
	v_mul_f32_e32 v72, v246, v72
	v_mul_f32_e32 v77, 0xbfb8aa3b, v77
	v_mul_f32_e32 v73, v246, v73
	v_exp_f32_e32 v76, v76
	v_mul_f32_e32 v72, 0xbfb8aa3b, v72
	v_exp_f32_e32 v77, v77
	v_mul_f32_e32 v73, 0xbfb8aa3b, v73
	v_exp_f32_e32 v72, v72
	v_exp_f32_e32 v73, v73
	v_add_f32_e32 v76, 1.0, v76
	v_add_f32_e32 v77, 1.0, v77
	v_rcp_f32_e32 v76, v76
	v_add_f32_e32 v72, 1.0, v72
	v_rcp_f32_e32 v77, v77
	v_add_f32_e32 v73, 1.0, v73
	v_rcp_f32_e32 v72, v72
	v_rcp_f32_e32 v73, v73
	v_mul_f32_e32 v78, v246, v78
	v_lshlrev_b32_e32 v144, 16, v136
	v_and_b32_e32 v145, 0xffff0000, v136
	v_lshlrev_b32_e32 v146, 16, v132
	v_and_b32_e32 v147, 0xffff0000, v132
	v_mul_f32_e32 v78, 0xbfb8aa3b, v78
	v_pk_fma_f32 v[76:77], v[76:77], v[144:145], v[146:147]
	v_lshlrev_b32_e32 v144, 16, v138
	v_and_b32_e32 v145, 0xffff0000, v138
	v_exp_f32_e32 v78, v78
	v_lshlrev_b32_e32 v146, 16, v134
	v_and_b32_e32 v147, 0xffff0000, v134
	v_pk_fma_f32 v[144:145], v[72:73], v[144:145], v[146:147]
	v_mul_f32_e32 v73, v246, v74
	v_mul_f32_e32 v73, 0xbfb8aa3b, v73
	v_mul_f32_e32 v74, v246, v79
	v_exp_f32_e32 v73, v73
	v_mul_f32_e32 v74, 0xbfb8aa3b, v74
	v_add_f32_e32 v72, 1.0, v78
	v_exp_f32_e32 v78, v74
	v_mul_f32_e32 v68, v246, v68
	v_mul_f32_e32 v69, v246, v69
	v_mul_f32_e32 v68, 0xbfb8aa3b, v68
	v_mul_f32_e32 v64, v246, v64
	v_mul_f32_e32 v69, 0xbfb8aa3b, v69
	v_mul_f32_e32 v65, v246, v65
	v_exp_f32_e32 v68, v68
	v_mul_f32_e32 v64, 0xbfb8aa3b, v64
	v_exp_f32_e32 v69, v69
	v_mul_f32_e32 v65, 0xbfb8aa3b, v65
	v_add_f32_e32 v73, 1.0, v73
	v_mul_f32_e32 v75, v246, v75
	v_exp_f32_e32 v64, v64
	v_exp_f32_e32 v65, v65
	v_rcp_f32_e32 v74, v73
	v_add_f32_e32 v73, 1.0, v78
	v_mul_f32_e32 v75, 0xbfb8aa3b, v75
	v_rcp_f32_e32 v72, v72
	v_rcp_f32_e32 v73, v73
	v_exp_f32_e32 v75, v75
	v_add_f32_e32 v68, 1.0, v68
	v_add_f32_e32 v69, 1.0, v69
	v_rcp_f32_e32 v68, v68
	v_add_f32_e32 v64, 1.0, v64
	v_rcp_f32_e32 v69, v69
	v_add_f32_e32 v65, 1.0, v65
	v_lshlrev_b32_e32 v78, 16, v137
	v_and_b32_e32 v79, 0xffff0000, v137
	v_lshlrev_b32_e32 v132, 16, v133
	v_and_b32_e32 v133, 0xffff0000, v133
	v_rcp_f32_e32 v64, v64
	v_rcp_f32_e32 v65, v65
	v_pk_fma_f32 v[78:79], v[72:73], v[78:79], v[132:133]
	v_add_f32_e32 v72, 1.0, v75
	v_mul_f32_e32 v70, v246, v70
	v_rcp_f32_e32 v75, v72
	v_lshlrev_b32_e32 v72, 16, v139
	v_and_b32_e32 v73, 0xffff0000, v139
	v_lshlrev_b32_e32 v138, 16, v124
	v_and_b32_e32 v139, 0xffff0000, v124
	v_lshlrev_b32_e32 v146, 16, v120
	v_and_b32_e32 v147, 0xffff0000, v120
	v_mul_f32_e32 v70, 0xbfb8aa3b, v70
	v_pk_fma_f32 v[68:69], v[68:69], v[138:139], v[146:147]
	v_lshlrev_b32_e32 v138, 16, v126
	v_and_b32_e32 v139, 0xffff0000, v126
	v_exp_f32_e32 v70, v70
	v_lshlrev_b32_e32 v146, 16, v122
	v_and_b32_e32 v147, 0xffff0000, v122
	v_pk_fma_f32 v[138:139], v[64:65], v[138:139], v[146:147]
	v_mul_f32_e32 v65, v246, v66
	v_mul_f32_e32 v65, 0xbfb8aa3b, v65
	v_mul_f32_e32 v66, v246, v71
	v_exp_f32_e32 v65, v65
	v_mul_f32_e32 v66, 0xbfb8aa3b, v66
	v_add_f32_e32 v64, 1.0, v70
	v_exp_f32_e32 v70, v66
	v_add_f32_e32 v65, 1.0, v65
	v_mul_f32_e32 v67, v246, v67
	v_rcp_f32_e32 v66, v65
	v_add_f32_e32 v65, 1.0, v70
	v_mul_f32_e32 v67, 0xbfb8aa3b, v67
	v_rcp_f32_e32 v64, v64
	v_rcp_f32_e32 v65, v65
	v_exp_f32_e32 v67, v67
	v_lshlrev_b32_e32 v70, 16, v125
	v_and_b32_e32 v71, 0xffff0000, v125
	v_lshlrev_b32_e32 v120, 16, v121
	v_and_b32_e32 v121, 0xffff0000, v121
	v_pk_fma_f32 v[70:71], v[64:65], v[70:71], v[120:121]
	v_add_f32_e32 v64, 1.0, v67
	v_rcp_f32_e32 v67, v64
	v_lshlrev_b32_e32 v132, 16, v135
	v_and_b32_e32 v133, 0xffff0000, v135
	v_lshlrev_b32_e32 v64, 16, v127
	v_and_b32_e32 v65, 0xffff0000, v127
	v_lshlrev_b32_e32 v120, 16, v123
	v_and_b32_e32 v121, 0xffff0000, v123
	v_pk_fma_f32 v[132:133], v[74:75], v[72:73], v[132:133]
	v_lshl_add_u64 v[72:73], s[26:27], 0, v[220:221]
	v_pk_fma_f32 v[120:121], v[66:67], v[64:65], v[120:121]
	v_pk_mul_f32 v[64:65], v[68:69], v[68:69]
	v_pk_mul_f32 v[66:67], v[70:71], v[70:71]
	v_lshl_add_u64 v[134:135], v[72:73], 0, v[216:217]
	v_cvt_pk_bf16_f32 v72, v76, v77
	v_cvt_pk_bf16_f32 v73, v78, v79
	v_pk_mul_f32 v[74:75], v[76:77], v[76:77]
	v_pk_mul_f32 v[76:77], v[78:79], v[78:79]
	v_pk_mul_f32 v[78:79], v[144:145], v[144:145]
	v_pk_mul_f32 v[136:137], v[132:133], v[132:133]
	v_add_f32_e32 v66, v66, v67
	v_add_f32_e32 v64, v64, v65
	v_pk_mul_f32 v[122:123], v[138:139], v[138:139]
	v_pk_mul_f32 v[124:125], v[120:121], v[120:121]
	v_add_f32_e32 v64, v64, v66
	v_add_f32_e32 v65, v136, v137
	v_add_f32_e32 v66, v78, v79
	v_add_f32_e32 v124, v124, v125
	v_add_f32_e32 v122, v122, v123
	v_add_f32_e32 v65, v66, v65
	v_add_f32_e32 v66, v76, v77
	v_add_f32_e32 v67, v74, v75
	v_add_f32_e32 v122, v122, v124
	v_add_f32_e32 v66, v67, v66
	v_add_f32_e32 v64, v64, v122
	v_add_f32_e32 v65, v66, v65
	v_add_f32_e32 v64, v65, v64
	ds_bpermute_b32 v65, v234, v64
	v_cvt_pk_bf16_f32 v74, v144, v145
	v_cvt_pk_bf16_f32 v75, v132, v133
	v_cvt_pk_bf16_f32 v66, v68, v69
	v_cvt_pk_bf16_f32 v67, v70, v71
	s_waitcnt lgkmcnt(0)
	v_add_f32_e32 v64, v64, v65
	ds_bpermute_b32 v65, v235, v64
	v_cvt_pk_bf16_f32 v68, v138, v139
	v_cvt_pk_bf16_f32 v69, v120, v121
	global_store_dwordx4 v[134:135], v[72:75], off
	global_store_dwordx4 v[134:135], v[66:69], off offset:256
	s_and_saveexec_b64 s[38:39], s[4:5]
	s_cbranch_execz .LBB0_1214
	s_waitcnt lgkmcnt(0)
	v_add_f32_e32 v66, v64, v65
	s_lshl_b32 s0, s56, 2
	v_lshlrev_b64 v[64:65], 7, v[218:219]
	s_ashr_i32 s1, s0, 31
	v_lshl_add_u64 v[64:65], s[30:31], 0, v[64:65]
	v_lshl_add_u64 v[64:65], s[0:1], 2, v[64:65]
	s_lshl_b32 s24, s57, 2
	v_lshl_add_u64 v[64:65], v[64:65], 0, s[24:25]
	global_store_dword v[64:65], v66, off
; __device__ __forceinline__ f32x4 ld_nt(const float* p) { return __builtin_nontemporal_load((const f32x4*)p); }
; __device__ __forceinline__ u32x4 ld_nt(const bf16_t* p) { return __builtin_nontemporal_load((const u32x4*)p); }
; __device__ __forceinline__ void st_nt(float* p, f32x4 v) { __builtin_nontemporal_store(v, (f32x4*)p); }
; __device__ __forceinline__ void st_nt(bf16_t* p, u32x4 v) { __builtin_nontemporal_store(v, (u32x4*)p); }
; __device__ __forceinline__ float sigmoidf_(float v) { return __builtin_amdgcn_rcpf(1.0f + __builtin_amdgcn_exp2f(-1.4426950408889634f * v)); }
; __device__ __forceinline__ float sumsq4(const f32x4 v) { return (v[0] * v[0] + v[1] * v[1]) + (v[2] * v[2] + v[3] * v[3]); }
; __device__ __forceinline__ u32x4 pack8(const f32x4 a, const f32x4 b) { u32x4 w; w.x = cvt_pk_bf16(a[0], a[1]); w.y = cvt_pk_bf16(a[2], a[3]); w.z = cvt_pk_bf16(b[0], b[1]); w.w = cvt_pk_bf16(b[2], b[3]); return w; }
;     __device__ __forceinline__ void operator()(Acc& acc, const Unit& u, int wr, int wc, int fr, int fq, const float (&rsv)[8]) const {
;     ...
; #pragma unroll
;         for (int g = 0; g < 8; ++g) {
;             const int ai = g >> 2, m = g & 3, s = g & 3; const int row = row0 + ai * HALF + m * 16;
;             const float rs = rsv[ai * 4 + m]; float ss = 0.f;
; #pragma unroll
;             for (int bj = 0; bj < 2; ++bj) { const size_t off = (size_t)row * DM + col0 + bj * HALF;
;                 f32x4 e0, e1, v0, v1; unpack8(ew[s][bj], e0, e1); unpack8(hw[s][bj], v0, v1);
; #pragma unroll
;                 for (int jj = 0; jj < 4; ++jj) { v0[jj] += sigmoidf_(acc[ai][bj][m][0][jj] * rs) * e0[jj]; v1[jj] += sigmoidf_(acc[ai][bj][m][1][jj] * rs) * e1[jj]; }
;                 st_nt(h4b + off, pack8(v0, v1)); ss += sumsq4(v0) + sumsq4(v1); }
;             ss += __shfl_xor(ss, 16); ss += __shfl_xor(ss, 32);
;             if (fq == 0) part_out[(size_t)row * 32 + u.pn * 4 + wc] = ss;
;             asm volatile("" ::: "memory");
;             if (g + 4 < 8) { const int r = row0 + ((g + 4) >> 2) * HALF + ((g + 4) & 3) * 16;
; #pragma unroll
;                 for (int bj = 0; bj < 2; ++bj) { hw[s][bj] = *(const u32x4*)(hb + (size_t)r * LDHB + 256 + col0 + bj * HALF); ew[s][bj] = ld_nt(etmp + (size_t)r * DM + col0 + bj * HALF); } }
.LBB0_1214:
	s_or_b64 exec, exec, s[38:39]
	v_or_b32_e32 v120, 48, v176
	v_ashrrev_i32_e32 v121, 31, v120
	s_waitcnt lgkmcnt(0)
	v_mov_b64_e32 v[64:65], s[10:11]
	v_lshlrev_b64 v[122:123], 12, v[120:121]
	v_mad_i64_i32 v[64:65], s[0:1], v120, s71, v[64:65]
	v_lshl_add_u64 v[66:67], s[28:29], 0, v[122:123]
	v_lshl_add_u64 v[64:65], v[64:65], 0, v[216:217]
	v_lshl_add_u64 v[68:69], v[66:67], 0, v[216:217]
	global_load_dwordx4 v[72:75], v[64:65], off offset:512
	s_nop 0
	global_load_dwordx4 v[64:67], v[64:65], off offset:768
	s_nop 0
	global_load_dwordx4 v[76:79], v[68:69], off nt
	s_nop 0
	global_load_dwordx4 v[68:71], v[68:69], off offset:256 nt
	v_mul_f32_e32 v60, v247, v60
	v_mul_f32_e32 v61, v247, v61
	v_mul_f32_e32 v52, v247, v52
	v_mul_f32_e32 v53, v247, v53
	v_mul_f32_e32 v60, 0xbfb8aa3b, v60
	v_mul_f32_e32 v56, v247, v56
	v_mul_f32_e32 v61, 0xbfb8aa3b, v61
	v_mul_f32_e32 v57, v247, v57
	v_mul_f32_e32 v52, 0xbfb8aa3b, v52
	v_mul_f32_e32 v48, v247, v48
	v_mul_f32_e32 v53, 0xbfb8aa3b, v53
	v_mul_f32_e32 v49, v247, v49
	v_exp_f32_e32 v60, v60
	v_mul_f32_e32 v56, 0xbfb8aa3b, v56
	v_exp_f32_e32 v61, v61
	v_mul_f32_e32 v57, 0xbfb8aa3b, v57
	v_exp_f32_e32 v52, v52
	v_mul_f32_e32 v48, 0xbfb8aa3b, v48
	v_exp_f32_e32 v53, v53
	v_mul_f32_e32 v49, 0xbfb8aa3b, v49
	v_exp_f32_e32 v56, v56
	v_exp_f32_e32 v57, v57
	v_exp_f32_e32 v48, v48
	v_exp_f32_e32 v49, v49
	v_add_f32_e32 v60, 1.0, v60
	v_add_f32_e32 v61, 1.0, v61
	v_add_f32_e32 v52, 1.0, v52
	v_add_f32_e32 v53, 1.0, v53
	v_rcp_f32_e32 v60, v60
	v_add_f32_e32 v56, 1.0, v56
	v_rcp_f32_e32 v61, v61
	v_add_f32_e32 v57, 1.0, v57
	v_rcp_f32_e32 v52, v52
	v_add_f32_e32 v48, 1.0, v48
	v_rcp_f32_e32 v53, v53
	v_add_f32_e32 v49, 1.0, v49
	v_rcp_f32_e32 v56, v56
	v_rcp_f32_e32 v57, v57
	v_rcp_f32_e32 v48, v48
	v_rcp_f32_e32 v49, v49
	v_mul_f32_e32 v62, v247, v62
	v_mul_f32_e32 v54, v247, v54
	s_waitcnt vmcnt(19)
	v_lshlrev_b32_e32 v124, 16, v148
	v_and_b32_e32 v125, 0xffff0000, v148
	v_lshlrev_b32_e32 v126, 16, v128
	v_and_b32_e32 v127, 0xffff0000, v128
	v_mul_f32_e32 v62, 0xbfb8aa3b, v62
	s_waitcnt vmcnt(18)
	v_lshlrev_b32_e32 v132, 16, v116
	v_and_b32_e32 v133, 0xffff0000, v116
	v_lshlrev_b32_e32 v134, 16, v112
	v_and_b32_e32 v135, 0xffff0000, v112
	v_mul_f32_e32 v54, 0xbfb8aa3b, v54
	v_pk_fma_f32 v[60:61], v[60:61], v[124:125], v[126:127]
	v_lshlrev_b32_e32 v124, 16, v150
	v_and_b32_e32 v125, 0xffff0000, v150
	v_exp_f32_e32 v62, v62
	v_lshlrev_b32_e32 v126, 16, v130
	v_and_b32_e32 v127, 0xffff0000, v130
	v_pk_fma_f32 v[52:53], v[52:53], v[132:133], v[134:135]
	v_lshlrev_b32_e32 v132, 16, v118
	v_and_b32_e32 v133, 0xffff0000, v118
	v_exp_f32_e32 v54, v54
	v_lshlrev_b32_e32 v134, 16, v114
	v_and_b32_e32 v135, 0xffff0000, v114
	v_pk_fma_f32 v[124:125], v[56:57], v[124:125], v[126:127]
	v_mul_f32_e32 v57, v247, v58
	v_pk_fma_f32 v[132:133], v[48:49], v[132:133], v[134:135]
	v_mul_f32_e32 v49, v247, v50
	v_mul_f32_e32 v57, 0xbfb8aa3b, v57
	v_mul_f32_e32 v58, v247, v63
	v_mul_f32_e32 v49, 0xbfb8aa3b, v49
	v_mul_f32_e32 v50, v247, v55
	v_exp_f32_e32 v57, v57
	v_mul_f32_e32 v58, 0xbfb8aa3b, v58
	v_exp_f32_e32 v49, v49
	v_mul_f32_e32 v50, 0xbfb8aa3b, v50
	v_add_f32_e32 v56, 1.0, v62
	v_exp_f32_e32 v62, v58
	v_add_f32_e32 v48, 1.0, v54
	v_exp_f32_e32 v54, v50
	v_add_f32_e32 v57, 1.0, v57
	v_mul_f32_e32 v59, v247, v59
	v_add_f32_e32 v49, 1.0, v49
	v_mul_f32_e32 v51, v247, v51
	v_rcp_f32_e32 v58, v57
	v_add_f32_e32 v57, 1.0, v62
	v_mul_f32_e32 v59, 0xbfb8aa3b, v59
	v_rcp_f32_e32 v50, v49
	v_add_f32_e32 v49, 1.0, v54
	v_mul_f32_e32 v51, 0xbfb8aa3b, v51
	v_rcp_f32_e32 v56, v56
	v_rcp_f32_e32 v57, v57
	v_exp_f32_e32 v59, v59
	v_rcp_f32_e32 v48, v48
	v_rcp_f32_e32 v49, v49
	v_exp_f32_e32 v51, v51
	v_lshlrev_b32_e32 v62, 16, v149
	v_and_b32_e32 v63, 0xffff0000, v149
	v_lshlrev_b32_e32 v126, 16, v129
	v_and_b32_e32 v127, 0xffff0000, v129
	v_lshlrev_b32_e32 v54, 16, v117
	v_and_b32_e32 v55, 0xffff0000, v117
	v_lshlrev_b32_e32 v112, 16, v113
	v_and_b32_e32 v113, 0xffff0000, v113
	v_pk_fma_f32 v[62:63], v[56:57], v[62:63], v[126:127]
	v_add_f32_e32 v56, 1.0, v59
	v_pk_fma_f32 v[54:55], v[48:49], v[54:55], v[112:113]
	v_add_f32_e32 v48, 1.0, v51
	v_rcp_f32_e32 v59, v56
	v_rcp_f32_e32 v51, v48
	v_lshlrev_b32_e32 v56, 16, v151
	v_and_b32_e32 v57, 0xffff0000, v151
	v_lshlrev_b32_e32 v126, 16, v131
	v_and_b32_e32 v127, 0xffff0000, v131
	v_lshlrev_b32_e32 v48, 16, v119
	v_and_b32_e32 v49, 0xffff0000, v119
	v_lshlrev_b32_e32 v112, 16, v115
	v_and_b32_e32 v113, 0xffff0000, v115
	v_pk_fma_f32 v[126:127], v[58:59], v[56:57], v[126:127]
	v_lshl_add_u64 v[56:57], s[26:27], 0, v[178:179]
	v_pk_fma_f32 v[112:113], v[50:51], v[48:49], v[112:113]
	v_pk_mul_f32 v[48:49], v[52:53], v[52:53]
	v_pk_mul_f32 v[50:51], v[54:55], v[54:55]
	v_lshl_add_u64 v[128:129], v[56:57], 0, v[216:217]
	v_cvt_pk_bf16_f32 v56, v60, v61
	v_cvt_pk_bf16_f32 v57, v62, v63
	v_pk_mul_f32 v[58:59], v[60:61], v[60:61]
	v_pk_mul_f32 v[60:61], v[62:63], v[62:63]
	v_pk_mul_f32 v[62:63], v[124:125], v[124:125]
	v_pk_mul_f32 v[130:131], v[126:127], v[126:127]
	v_add_f32_e32 v50, v50, v51
	v_add_f32_e32 v48, v48, v49
	v_pk_mul_f32 v[114:115], v[132:133], v[132:133]
	v_pk_mul_f32 v[116:117], v[112:113], v[112:113]
	v_add_f32_e32 v48, v48, v50
	v_add_f32_e32 v49, v130, v131
	v_add_f32_e32 v50, v62, v63
	v_add_f32_e32 v116, v116, v117
	v_add_f32_e32 v114, v114, v115
	v_add_f32_e32 v49, v50, v49
	v_add_f32_e32 v50, v60, v61
	v_add_f32_e32 v51, v58, v59
	v_add_f32_e32 v114, v114, v116
	v_add_f32_e32 v50, v51, v50
	v_add_f32_e32 v48, v48, v114
	v_add_f32_e32 v49, v50, v49
	v_add_f32_e32 v48, v49, v48
	ds_bpermute_b32 v49, v234, v48
	v_cvt_pk_bf16_f32 v58, v124, v125
	v_cvt_pk_bf16_f32 v59, v126, v127
	v_cvt_pk_bf16_f32 v50, v52, v53
	v_cvt_pk_bf16_f32 v51, v54, v55
	s_waitcnt lgkmcnt(0)
	v_add_f32_e32 v48, v48, v49
	ds_bpermute_b32 v49, v235, v48
	v_cvt_pk_bf16_f32 v52, v132, v133
	v_cvt_pk_bf16_f32 v53, v112, v113
	global_store_dwordx4 v[128:129], v[56:59], off
	global_store_dwordx4 v[128:129], v[50:53], off offset:256
	s_and_saveexec_b64 s[38:39], s[4:5]
	s_cbranch_execz .LBB0_1216
	s_waitcnt lgkmcnt(0)
	v_add_f32_e32 v50, v48, v49
	s_lshl_b32 s0, s56, 2
	v_lshlrev_b64 v[48:49], 7, v[176:177]
	s_ashr_i32 s1, s0, 31
	v_lshl_add_u64 v[48:49], s[30:31], 0, v[48:49]
	v_lshl_add_u64 v[48:49], s[0:1], 2, v[48:49]
	s_lshl_b32 s24, s57, 2
	v_lshl_add_u64 v[48:49], v[48:49], 0, s[24:25]
	global_store_dword v[48:49], v50, off
; __device__ __forceinline__ void st_nt(float* p, f32x4 v) { __builtin_nontemporal_store(v, (f32x4*)p); }
; __device__ __forceinline__ void st_nt(bf16_t* p, u32x4 v) { __builtin_nontemporal_store(v, (u32x4*)p); }
; __device__ __forceinline__ float sigmoidf_(float v) { return __builtin_amdgcn_rcpf(1.0f + __builtin_amdgcn_exp2f(-1.4426950408889634f * v)); }
; __device__ __forceinline__ float sumsq4(const f32x4 v) { return (v[0] * v[0] + v[1] * v[1]) + (v[2] * v[2] + v[3] * v[3]); }
; __device__ __forceinline__ u32x4 pack8(const f32x4 a, const f32x4 b) { u32x4 w; w.x = cvt_pk_bf16(a[0], a[1]); w.y = cvt_pk_bf16(a[2], a[3]); w.z = cvt_pk_bf16(b[0], b[1]); w.w = cvt_pk_bf16(b[2], b[3]); return w; }
; __device__ __forceinline__ void unpack8(const u32x4 w, f32x4& a, f32x4& b) { a = (f32x4){bf_lo(w.x), bf_hi(w.x), bf_lo(w.y), bf_hi(w.y)}; b = (f32x4){bf_lo(w.z), bf_hi(w.z), bf_lo(w.w), bf_hi(w.w)}; }
;     __device__ __forceinline__ void operator()(Acc& acc, const Unit& u, int wr, int wc, int fr, int fq, const float (&rsv)[8]) const {
;     ...
; #pragma unroll
;         for (int g = 0; g < 8; ++g) {
;             const int ai = g >> 2, m = g & 3, s = g & 3; const int row = row0 + ai * HALF + m * 16;
;             const float rs = rsv[ai * 4 + m]; float ss = 0.f;
; #pragma unroll
;             for (int bj = 0; bj < 2; ++bj) { const size_t off = (size_t)row * DM + col0 + bj * HALF;
;                 f32x4 e0, e1, v0, v1; unpack8(ew[s][bj], e0, e1); unpack8(hw[s][bj], v0, v1);
; #pragma unroll
;                 for (int jj = 0; jj < 4; ++jj) { v0[jj] += sigmoidf_(acc[ai][bj][m][0][jj] * rs) * e0[jj]; v1[jj] += sigmoidf_(acc[ai][bj][m][1][jj] * rs) * e1[jj]; }
;                 st_nt(h4b + off, pack8(v0, v1)); ss += sumsq4(v0) + sumsq4(v1); }
;             ss += __shfl_xor(ss, 16); ss += __shfl_xor(ss, 32);
;             if (fq == 0) part_out[(size_t)row * 32 + u.pn * 4 + wc] = ss;
;             asm volatile("" ::: "memory");
.LBB0_1216:
	s_or_b64 exec, exec, s[38:39]
	v_mul_f32_e32 v44, v248, v44
	v_mul_f32_e32 v45, v248, v45
	v_mul_f32_e32 v36, v248, v36
	v_mul_f32_e32 v37, v248, v37
	v_mul_f32_e32 v44, 0xbfb8aa3b, v44
	v_mul_f32_e32 v40, v248, v40
	v_mul_f32_e32 v45, 0xbfb8aa3b, v45
	v_mul_f32_e32 v41, v248, v41
	v_mul_f32_e32 v36, 0xbfb8aa3b, v36
	v_mul_f32_e32 v32, v248, v32
	v_mul_f32_e32 v37, 0xbfb8aa3b, v37
	v_mul_f32_e32 v33, v248, v33
	v_exp_f32_e32 v44, v44
	v_mul_f32_e32 v40, 0xbfb8aa3b, v40
	v_exp_f32_e32 v45, v45
	v_mul_f32_e32 v41, 0xbfb8aa3b, v41
	v_exp_f32_e32 v36, v36
	v_mul_f32_e32 v32, 0xbfb8aa3b, v32
	v_exp_f32_e32 v37, v37
	v_mul_f32_e32 v33, 0xbfb8aa3b, v33
	v_exp_f32_e32 v40, v40
	v_exp_f32_e32 v41, v41
	v_exp_f32_e32 v32, v32
	v_exp_f32_e32 v33, v33
	v_add_f32_e32 v44, 1.0, v44
	v_add_f32_e32 v45, 1.0, v45
	v_add_f32_e32 v36, 1.0, v36
	v_add_f32_e32 v37, 1.0, v37
	v_rcp_f32_e32 v44, v44
	v_add_f32_e32 v40, 1.0, v40
	v_rcp_f32_e32 v45, v45
	v_add_f32_e32 v41, 1.0, v41
	v_rcp_f32_e32 v36, v36
	v_add_f32_e32 v32, 1.0, v32
	v_rcp_f32_e32 v37, v37
	v_add_f32_e32 v33, 1.0, v33
	v_rcp_f32_e32 v40, v40
	v_rcp_f32_e32 v41, v41
	v_rcp_f32_e32 v32, v32
	v_rcp_f32_e32 v33, v33
	v_mul_f32_e32 v46, v248, v46
	v_mul_f32_e32 v38, v248, v38
	s_waitcnt vmcnt(15)
	v_lshlrev_b32_e32 v48, 16, v108
	s_waitcnt lgkmcnt(0)
	v_and_b32_e32 v49, 0xffff0000, v108
	v_lshlrev_b32_e32 v50, 16, v104
	v_and_b32_e32 v51, 0xffff0000, v104
	v_mul_f32_e32 v46, 0xbfb8aa3b, v46
	s_waitcnt vmcnt(14)
	v_lshlrev_b32_e32 v56, 16, v100
	v_and_b32_e32 v57, 0xffff0000, v100
	v_lshlrev_b32_e32 v58, 16, v96
	v_and_b32_e32 v59, 0xffff0000, v96
	v_mul_f32_e32 v38, 0xbfb8aa3b, v38
	v_pk_fma_f32 v[44:45], v[44:45], v[48:49], v[50:51]
	v_lshlrev_b32_e32 v48, 16, v110
	v_and_b32_e32 v49, 0xffff0000, v110
	v_exp_f32_e32 v46, v46
	v_lshlrev_b32_e32 v50, 16, v106
	v_and_b32_e32 v51, 0xffff0000, v106
	v_pk_fma_f32 v[36:37], v[36:37], v[56:57], v[58:59]
	v_lshlrev_b32_e32 v56, 16, v102
	v_and_b32_e32 v57, 0xffff0000, v102
	v_exp_f32_e32 v38, v38
	v_lshlrev_b32_e32 v58, 16, v98
	v_and_b32_e32 v59, 0xffff0000, v98
	v_pk_fma_f32 v[48:49], v[40:41], v[48:49], v[50:51]
	v_mul_f32_e32 v41, v248, v42
	v_pk_fma_f32 v[56:57], v[32:33], v[56:57], v[58:59]
	v_mul_f32_e32 v33, v248, v34
	v_mul_f32_e32 v41, 0xbfb8aa3b, v41
	v_mul_f32_e32 v42, v248, v47
	v_mul_f32_e32 v33, 0xbfb8aa3b, v33
	v_mul_f32_e32 v34, v248, v39
	v_exp_f32_e32 v41, v41
	v_mul_f32_e32 v42, 0xbfb8aa3b, v42
	v_exp_f32_e32 v33, v33
	v_mul_f32_e32 v34, 0xbfb8aa3b, v34
	v_add_f32_e32 v40, 1.0, v46
	v_exp_f32_e32 v46, v42
	v_add_f32_e32 v32, 1.0, v38
	v_exp_f32_e32 v38, v34
	v_add_f32_e32 v41, 1.0, v41
	v_mul_f32_e32 v43, v248, v43
	v_add_f32_e32 v33, 1.0, v33
	v_mul_f32_e32 v35, v248, v35
	v_rcp_f32_e32 v42, v41
	v_add_f32_e32 v41, 1.0, v46
	v_mul_f32_e32 v43, 0xbfb8aa3b, v43
	v_rcp_f32_e32 v34, v33
	v_add_f32_e32 v33, 1.0, v38
	v_mul_f32_e32 v35, 0xbfb8aa3b, v35
	v_rcp_f32_e32 v40, v40
	v_rcp_f32_e32 v41, v41
	v_exp_f32_e32 v43, v43
	v_rcp_f32_e32 v32, v32
	v_rcp_f32_e32 v33, v33
	v_exp_f32_e32 v35, v35
	v_lshlrev_b32_e32 v46, 16, v109
	v_and_b32_e32 v47, 0xffff0000, v109
	v_lshlrev_b32_e32 v50, 16, v105
	v_and_b32_e32 v51, 0xffff0000, v105
	v_lshlrev_b32_e32 v38, 16, v101
	v_and_b32_e32 v39, 0xffff0000, v101
	v_lshlrev_b32_e32 v58, 16, v97
	v_and_b32_e32 v59, 0xffff0000, v97
	v_pk_fma_f32 v[46:47], v[40:41], v[46:47], v[50:51]
	v_add_f32_e32 v40, 1.0, v43
	v_pk_fma_f32 v[38:39], v[32:33], v[38:39], v[58:59]
	v_add_f32_e32 v32, 1.0, v35
	v_rcp_f32_e32 v43, v40
	v_rcp_f32_e32 v35, v32
	v_lshlrev_b32_e32 v40, 16, v111
	v_and_b32_e32 v41, 0xffff0000, v111
	v_lshlrev_b32_e32 v50, 16, v107
	v_and_b32_e32 v51, 0xffff0000, v107
	v_lshlrev_b32_e32 v32, 16, v103
	v_and_b32_e32 v33, 0xffff0000, v103
	v_lshlrev_b32_e32 v58, 16, v99
	v_and_b32_e32 v59, 0xffff0000, v99
	v_pk_fma_f32 v[50:51], v[42:43], v[40:41], v[50:51]
	v_lshl_add_u64 v[40:41], s[26:27], 0, v[162:163]
	v_pk_fma_f32 v[58:59], v[34:35], v[32:33], v[58:59]
	v_pk_mul_f32 v[32:33], v[36:37], v[36:37]
	v_pk_mul_f32 v[34:35], v[38:39], v[38:39]
	v_lshl_add_u64 v[52:53], v[212:213], 1, v[40:41]
	v_cvt_pk_bf16_f32 v40, v44, v45
	v_cvt_pk_bf16_f32 v41, v46, v47
	v_pk_mul_f32 v[42:43], v[44:45], v[44:45]
	v_pk_mul_f32 v[44:45], v[46:47], v[46:47]
	v_pk_mul_f32 v[46:47], v[48:49], v[48:49]
	v_pk_mul_f32 v[54:55], v[50:51], v[50:51]
	v_add_f32_e32 v34, v34, v35
	v_add_f32_e32 v32, v32, v33
	v_pk_mul_f32 v[60:61], v[56:57], v[56:57]
	v_pk_mul_f32 v[62:63], v[58:59], v[58:59]
	v_add_f32_e32 v32, v32, v34
	v_add_f32_e32 v33, v54, v55
	v_add_f32_e32 v34, v46, v47
	v_add_f32_e32 v62, v62, v63
	v_add_f32_e32 v60, v60, v61
	v_add_f32_e32 v33, v34, v33
	v_add_f32_e32 v34, v44, v45
	v_add_f32_e32 v35, v42, v43
	v_add_f32_e32 v60, v60, v62
	v_add_f32_e32 v34, v35, v34
	v_add_f32_e32 v32, v32, v60
	v_add_f32_e32 v33, v34, v33
	v_add_f32_e32 v32, v33, v32
	ds_bpermute_b32 v33, v234, v32
	v_cvt_pk_bf16_f32 v42, v48, v49
	v_cvt_pk_bf16_f32 v43, v50, v51
	v_cvt_pk_bf16_f32 v34, v36, v37
	s_waitcnt lgkmcnt(0)
	v_add_f32_e32 v32, v32, v33
	ds_bpermute_b32 v33, v235, v32
	v_cvt_pk_bf16_f32 v35, v38, v39
	v_cvt_pk_bf16_f32 v36, v56, v57
	v_cvt_pk_bf16_f32 v37, v58, v59
	global_store_dwordx4 v[52:53], v[40:43], off
	global_store_dwordx4 v[52:53], v[34:37], off offset:256
	s_and_saveexec_b64 s[38:39], s[4:5]
	s_cbranch_execz .LBB0_1218
	s_waitcnt lgkmcnt(0)
	v_add_f32_e32 v34, v32, v33
	s_lshl_b32 s0, s56, 2
	v_lshlrev_b64 v[32:33], 7, v[160:161]
	s_ashr_i32 s1, s0, 31
	v_lshl_add_u64 v[32:33], s[30:31], 0, v[32:33]
	v_lshl_add_u64 v[32:33], s[0:1], 2, v[32:33]
	s_lshl_b32 s24, s57, 2
	v_lshl_add_u64 v[32:33], v[32:33], 0, s[24:25]
	global_store_dword v[32:33], v34, off
; __device__ __forceinline__ void st_nt(float* p, f32x4 v) { __builtin_nontemporal_store(v, (f32x4*)p); }
; __device__ __forceinline__ void st_nt(bf16_t* p, u32x4 v) { __builtin_nontemporal_store(v, (u32x4*)p); }
; __device__ __forceinline__ float sigmoidf_(float v) { return __builtin_amdgcn_rcpf(1.0f + __builtin_amdgcn_exp2f(-1.4426950408889634f * v)); }
; __device__ __forceinline__ float sumsq4(const f32x4 v) { return (v[0] * v[0] + v[1] * v[1]) + (v[2] * v[2] + v[3] * v[3]); }
; __device__ __forceinline__ u32x4 pack8(const f32x4 a, const f32x4 b) { u32x4 w; w.x = cvt_pk_bf16(a[0], a[1]); w.y = cvt_pk_bf16(a[2], a[3]); w.z = cvt_pk_bf16(b[0], b[1]); w.w = cvt_pk_bf16(b[2], b[3]); return w; }
; __device__ __forceinline__ void unpack8(const u32x4 w, f32x4& a, f32x4& b) { a = (f32x4){bf_lo(w.x), bf_hi(w.x), bf_lo(w.y), bf_hi(w.y)}; b = (f32x4){bf_lo(w.z), bf_hi(w.z), bf_lo(w.w), bf_hi(w.w)}; }
;     __device__ __forceinline__ void operator()(Acc& acc, const Unit& u, int wr, int wc, int fr, int fq, const float (&rsv)[8]) const {
;     ...
; #pragma unroll
;         for (int g = 0; g < 8; ++g) {
;             const int ai = g >> 2, m = g & 3, s = g & 3; const int row = row0 + ai * HALF + m * 16;
;             const float rs = rsv[ai * 4 + m]; float ss = 0.f;
; #pragma unroll
;             for (int bj = 0; bj < 2; ++bj) { const size_t off = (size_t)row * DM + col0 + bj * HALF;
;                 f32x4 e0, e1, v0, v1; unpack8(ew[s][bj], e0, e1); unpack8(hw[s][bj], v0, v1);
; #pragma unroll
;                 for (int jj = 0; jj < 4; ++jj) { v0[jj] += sigmoidf_(acc[ai][bj][m][0][jj] * rs) * e0[jj]; v1[jj] += sigmoidf_(acc[ai][bj][m][1][jj] * rs) * e1[jj]; }
;                 st_nt(h4b + off, pack8(v0, v1)); ss += sumsq4(v0) + sumsq4(v1); }
;             ss += __shfl_xor(ss, 16); ss += __shfl_xor(ss, 32);
;             if (fq == 0) part_out[(size_t)row * 32 + u.pn * 4 + wc] = ss;
;             asm volatile("" ::: "memory");
.LBB0_1218:
	s_or_b64 exec, exec, s[38:39]
	v_mul_f32_e32 v28, v249, v28
	v_mul_f32_e32 v29, v249, v29
	v_mul_f32_e32 v20, v249, v20
	v_mul_f32_e32 v21, v249, v21
	v_mul_f32_e32 v28, 0xbfb8aa3b, v28
	v_mul_f32_e32 v24, v249, v24
	v_mul_f32_e32 v29, 0xbfb8aa3b, v29
	v_mul_f32_e32 v25, v249, v25
	v_mul_f32_e32 v20, 0xbfb8aa3b, v20
	v_mul_f32_e32 v16, v249, v16
	v_mul_f32_e32 v21, 0xbfb8aa3b, v21
	v_mul_f32_e32 v17, v249, v17
	v_exp_f32_e32 v28, v28
	v_mul_f32_e32 v24, 0xbfb8aa3b, v24
	v_exp_f32_e32 v29, v29
	v_mul_f32_e32 v25, 0xbfb8aa3b, v25
	v_exp_f32_e32 v20, v20
	v_mul_f32_e32 v16, 0xbfb8aa3b, v16
	v_exp_f32_e32 v21, v21
	v_mul_f32_e32 v17, 0xbfb8aa3b, v17
	v_exp_f32_e32 v24, v24
	v_exp_f32_e32 v25, v25
	v_exp_f32_e32 v16, v16
	v_exp_f32_e32 v17, v17
	v_add_f32_e32 v28, 1.0, v28
	v_add_f32_e32 v29, 1.0, v29
	v_add_f32_e32 v20, 1.0, v20
	v_add_f32_e32 v21, 1.0, v21
	v_rcp_f32_e32 v28, v28
	v_add_f32_e32 v24, 1.0, v24
	v_rcp_f32_e32 v29, v29
	v_add_f32_e32 v25, 1.0, v25
	v_rcp_f32_e32 v20, v20
	v_add_f32_e32 v16, 1.0, v16
	v_rcp_f32_e32 v21, v21
	v_add_f32_e32 v17, 1.0, v17
	v_rcp_f32_e32 v24, v24
	v_rcp_f32_e32 v25, v25
	v_rcp_f32_e32 v16, v16
	v_rcp_f32_e32 v17, v17
	v_mul_f32_e32 v30, v249, v30
	v_mul_f32_e32 v22, v249, v22
	s_waitcnt vmcnt(11)
	v_lshlrev_b32_e32 v32, 16, v92
	s_waitcnt lgkmcnt(0)
	v_and_b32_e32 v33, 0xffff0000, v92
	v_lshlrev_b32_e32 v34, 16, v88
	v_and_b32_e32 v35, 0xffff0000, v88
	v_mul_f32_e32 v30, 0xbfb8aa3b, v30
	s_waitcnt vmcnt(10)
	v_lshlrev_b32_e32 v40, 16, v84
	v_and_b32_e32 v41, 0xffff0000, v84
	v_lshlrev_b32_e32 v42, 16, v80
	v_and_b32_e32 v43, 0xffff0000, v80
	v_mul_f32_e32 v22, 0xbfb8aa3b, v22
	v_pk_fma_f32 v[28:29], v[28:29], v[32:33], v[34:35]
	v_lshlrev_b32_e32 v32, 16, v94
	v_and_b32_e32 v33, 0xffff0000, v94
	v_exp_f32_e32 v30, v30
	v_lshlrev_b32_e32 v34, 16, v90
	v_and_b32_e32 v35, 0xffff0000, v90
	v_pk_fma_f32 v[20:21], v[20:21], v[40:41], v[42:43]
	v_lshlrev_b32_e32 v40, 16, v86
	v_and_b32_e32 v41, 0xffff0000, v86
	v_exp_f32_e32 v22, v22
	v_lshlrev_b32_e32 v42, 16, v82
	v_and_b32_e32 v43, 0xffff0000, v82
	v_pk_fma_f32 v[32:33], v[24:25], v[32:33], v[34:35]
	v_mul_f32_e32 v25, v249, v26
	v_pk_fma_f32 v[40:41], v[16:17], v[40:41], v[42:43]
	v_mul_f32_e32 v17, v249, v18
	v_mul_f32_e32 v25, 0xbfb8aa3b, v25
	v_mul_f32_e32 v26, v249, v31
	v_mul_f32_e32 v17, 0xbfb8aa3b, v17
	v_mul_f32_e32 v18, v249, v23
	v_exp_f32_e32 v25, v25
	v_mul_f32_e32 v26, 0xbfb8aa3b, v26
	v_exp_f32_e32 v17, v17
	v_mul_f32_e32 v18, 0xbfb8aa3b, v18
	v_add_f32_e32 v24, 1.0, v30
	v_exp_f32_e32 v30, v26
	v_add_f32_e32 v16, 1.0, v22
	v_exp_f32_e32 v22, v18
	v_add_f32_e32 v25, 1.0, v25
	v_mul_f32_e32 v27, v249, v27
	v_add_f32_e32 v17, 1.0, v17
	v_mul_f32_e32 v19, v249, v19
	v_rcp_f32_e32 v26, v25
	v_add_f32_e32 v25, 1.0, v30
	v_mul_f32_e32 v27, 0xbfb8aa3b, v27
	v_rcp_f32_e32 v18, v17
	v_add_f32_e32 v17, 1.0, v22
	v_mul_f32_e32 v19, 0xbfb8aa3b, v19
	v_rcp_f32_e32 v24, v24
	v_rcp_f32_e32 v25, v25
	v_exp_f32_e32 v27, v27
	v_rcp_f32_e32 v16, v16
	v_rcp_f32_e32 v17, v17
	v_exp_f32_e32 v19, v19
	v_lshlrev_b32_e32 v30, 16, v93
	v_and_b32_e32 v31, 0xffff0000, v93
	v_lshlrev_b32_e32 v34, 16, v89
	v_and_b32_e32 v35, 0xffff0000, v89
	v_lshlrev_b32_e32 v22, 16, v85
	v_and_b32_e32 v23, 0xffff0000, v85
	v_lshlrev_b32_e32 v42, 16, v81
	v_and_b32_e32 v43, 0xffff0000, v81
	v_pk_fma_f32 v[30:31], v[24:25], v[30:31], v[34:35]
	v_add_f32_e32 v24, 1.0, v27
	v_pk_fma_f32 v[22:23], v[16:17], v[22:23], v[42:43]
	v_add_f32_e32 v16, 1.0, v19
	v_rcp_f32_e32 v27, v24
	v_rcp_f32_e32 v19, v16
	v_lshlrev_b32_e32 v24, 16, v95
	v_and_b32_e32 v25, 0xffff0000, v95
	v_lshlrev_b32_e32 v34, 16, v91
	v_and_b32_e32 v35, 0xffff0000, v91
	v_lshlrev_b32_e32 v16, 16, v87
	v_and_b32_e32 v17, 0xffff0000, v87
	v_lshlrev_b32_e32 v42, 16, v83
	v_and_b32_e32 v43, 0xffff0000, v83
	v_pk_fma_f32 v[34:35], v[26:27], v[24:25], v[34:35]
	v_lshl_add_u64 v[24:25], s[26:27], 0, v[142:143]
	v_pk_fma_f32 v[42:43], v[18:19], v[16:17], v[42:43]
	v_pk_mul_f32 v[16:17], v[20:21], v[20:21]
	v_pk_mul_f32 v[18:19], v[22:23], v[22:23]
	v_lshl_add_u64 v[36:37], v[212:213], 1, v[24:25]
	v_cvt_pk_bf16_f32 v24, v28, v29
	v_cvt_pk_bf16_f32 v25, v30, v31
	v_pk_mul_f32 v[26:27], v[28:29], v[28:29]
	v_pk_mul_f32 v[28:29], v[30:31], v[30:31]
	v_pk_mul_f32 v[30:31], v[32:33], v[32:33]
	v_pk_mul_f32 v[38:39], v[34:35], v[34:35]
	v_add_f32_e32 v18, v18, v19
	v_add_f32_e32 v16, v16, v17
	v_pk_mul_f32 v[44:45], v[40:41], v[40:41]
	v_pk_mul_f32 v[46:47], v[42:43], v[42:43]
	v_add_f32_e32 v16, v16, v18
	v_add_f32_e32 v17, v38, v39
	v_add_f32_e32 v18, v30, v31
	v_add_f32_e32 v46, v46, v47
	v_add_f32_e32 v44, v44, v45
	v_add_f32_e32 v17, v18, v17
	v_add_f32_e32 v18, v28, v29
	v_add_f32_e32 v19, v26, v27
	v_add_f32_e32 v44, v44, v46
	v_add_f32_e32 v18, v19, v18
	v_add_f32_e32 v16, v16, v44
	v_add_f32_e32 v17, v18, v17
	v_add_f32_e32 v16, v17, v16
	ds_bpermute_b32 v17, v234, v16
	v_cvt_pk_bf16_f32 v26, v32, v33
	v_cvt_pk_bf16_f32 v27, v34, v35
	v_cvt_pk_bf16_f32 v18, v20, v21
	s_waitcnt lgkmcnt(0)
	v_add_f32_e32 v16, v16, v17
	ds_bpermute_b32 v17, v235, v16
	v_cvt_pk_bf16_f32 v19, v22, v23
	v_cvt_pk_bf16_f32 v20, v40, v41
	v_cvt_pk_bf16_f32 v21, v42, v43
	global_store_dwordx4 v[36:37], v[24:27], off
	global_store_dwordx4 v[36:37], v[18:21], off offset:256
	s_and_saveexec_b64 s[38:39], s[4:5]
	s_cbranch_execz .LBB0_1220
	s_waitcnt lgkmcnt(0)
	v_add_f32_e32 v18, v16, v17
	s_lshl_b32 s0, s56, 2
	v_lshlrev_b64 v[16:17], 7, v[140:141]
	s_ashr_i32 s1, s0, 31
	v_lshl_add_u64 v[16:17], s[30:31], 0, v[16:17]
	v_lshl_add_u64 v[16:17], s[0:1], 2, v[16:17]
	s_lshl_b32 s24, s57, 2
	v_lshl_add_u64 v[16:17], v[16:17], 0, s[24:25]
	global_store_dword v[16:17], v18, off
; __device__ __forceinline__ void st_nt(float* p, f32x4 v) { __builtin_nontemporal_store(v, (f32x4*)p); }
; __device__ __forceinline__ void st_nt(bf16_t* p, u32x4 v) { __builtin_nontemporal_store(v, (u32x4*)p); }
; __device__ __forceinline__ float sigmoidf_(float v) { return __builtin_amdgcn_rcpf(1.0f + __builtin_amdgcn_exp2f(-1.4426950408889634f * v)); }
; __device__ __forceinline__ float sumsq4(const f32x4 v) { return (v[0] * v[0] + v[1] * v[1]) + (v[2] * v[2] + v[3] * v[3]); }
; __device__ __forceinline__ u32x4 pack8(const f32x4 a, const f32x4 b) { u32x4 w; w.x = cvt_pk_bf16(a[0], a[1]); w.y = cvt_pk_bf16(a[2], a[3]); w.z = cvt_pk_bf16(b[0], b[1]); w.w = cvt_pk_bf16(b[2], b[3]); return w; }
; __device__ __forceinline__ void unpack8(const u32x4 w, f32x4& a, f32x4& b) { a = (f32x4){bf_lo(w.x), bf_hi(w.x), bf_lo(w.y), bf_hi(w.y)}; b = (f32x4){bf_lo(w.z), bf_hi(w.z), bf_lo(w.w), bf_hi(w.w)}; }
;     __device__ __forceinline__ void operator()(Acc& acc, const Unit& u, int wr, int wc, int fr, int fq, const float (&rsv)[8]) const {
;     ...
; #pragma unroll
;         for (int g = 0; g < 8; ++g) {
;             const int ai = g >> 2, m = g & 3, s = g & 3; const int row = row0 + ai * HALF + m * 16;
;             const float rs = rsv[ai * 4 + m]; float ss = 0.f;
; #pragma unroll
;             for (int bj = 0; bj < 2; ++bj) { const size_t off = (size_t)row * DM + col0 + bj * HALF;
;                 f32x4 e0, e1, v0, v1; unpack8(ew[s][bj], e0, e1); unpack8(hw[s][bj], v0, v1);
; #pragma unroll
;                 for (int jj = 0; jj < 4; ++jj) { v0[jj] += sigmoidf_(acc[ai][bj][m][0][jj] * rs) * e0[jj]; v1[jj] += sigmoidf_(acc[ai][bj][m][1][jj] * rs) * e1[jj]; }
;                 st_nt(h4b + off, pack8(v0, v1)); ss += sumsq4(v0) + sumsq4(v1); }
;             ss += __shfl_xor(ss, 16); ss += __shfl_xor(ss, 32);
;             if (fq == 0) part_out[(size_t)row * 32 + u.pn * 4 + wc] = ss;
;             asm volatile("" ::: "memory");
.LBB0_1220:
	s_or_b64 exec, exec, s[38:39]
	v_mul_f32_e32 v12, v250, v12
	v_mul_f32_e32 v13, v250, v13
	v_mul_f32_e32 v4, v250, v4
	v_mul_f32_e32 v5, v250, v5
	v_mul_f32_e32 v12, 0xbfb8aa3b, v12
	v_mul_f32_e32 v8, v250, v8
	v_mul_f32_e32 v13, 0xbfb8aa3b, v13
	v_mul_f32_e32 v9, v250, v9
	v_mul_f32_e32 v4, 0xbfb8aa3b, v4
	v_mul_f32_e32 v0, v250, v0
	v_mul_f32_e32 v5, 0xbfb8aa3b, v5
	v_mul_f32_e32 v1, v250, v1
	v_exp_f32_e32 v12, v12
	v_mul_f32_e32 v8, 0xbfb8aa3b, v8
	v_exp_f32_e32 v13, v13
	v_mul_f32_e32 v9, 0xbfb8aa3b, v9
	v_exp_f32_e32 v4, v4
	v_mul_f32_e32 v0, 0xbfb8aa3b, v0
	v_exp_f32_e32 v5, v5
	v_mul_f32_e32 v1, 0xbfb8aa3b, v1
	v_exp_f32_e32 v8, v8
	v_exp_f32_e32 v9, v9
	v_exp_f32_e32 v0, v0
	v_exp_f32_e32 v1, v1
	v_add_f32_e32 v12, 1.0, v12
	v_add_f32_e32 v13, 1.0, v13
	v_add_f32_e32 v4, 1.0, v4
	v_add_f32_e32 v5, 1.0, v5
	v_rcp_f32_e32 v12, v12
	v_add_f32_e32 v8, 1.0, v8
	v_rcp_f32_e32 v13, v13
	v_add_f32_e32 v9, 1.0, v9
	v_rcp_f32_e32 v4, v4
	v_add_f32_e32 v0, 1.0, v0
	v_rcp_f32_e32 v5, v5
	v_add_f32_e32 v1, 1.0, v1
	v_rcp_f32_e32 v8, v8
	v_rcp_f32_e32 v9, v9
	v_rcp_f32_e32 v0, v0
	v_rcp_f32_e32 v1, v1
	v_mul_f32_e32 v14, v250, v14
	v_mul_f32_e32 v6, v250, v6
	s_waitcnt vmcnt(7)
	v_lshlrev_b32_e32 v16, 16, v76
	s_waitcnt lgkmcnt(0)
	v_and_b32_e32 v17, 0xffff0000, v76
	v_lshlrev_b32_e32 v18, 16, v72
	v_and_b32_e32 v19, 0xffff0000, v72
	v_mul_f32_e32 v14, 0xbfb8aa3b, v14
	s_waitcnt vmcnt(6)
	v_lshlrev_b32_e32 v24, 16, v68
	v_and_b32_e32 v25, 0xffff0000, v68
	v_lshlrev_b32_e32 v26, 16, v64
	v_and_b32_e32 v27, 0xffff0000, v64
	v_mul_f32_e32 v6, 0xbfb8aa3b, v6
	v_pk_fma_f32 v[12:13], v[12:13], v[16:17], v[18:19]
	v_lshlrev_b32_e32 v16, 16, v78
	v_and_b32_e32 v17, 0xffff0000, v78
	v_exp_f32_e32 v14, v14
	v_lshlrev_b32_e32 v18, 16, v74
	v_and_b32_e32 v19, 0xffff0000, v74
	v_pk_fma_f32 v[4:5], v[4:5], v[24:25], v[26:27]
	v_lshlrev_b32_e32 v24, 16, v70
	v_and_b32_e32 v25, 0xffff0000, v70
	v_exp_f32_e32 v6, v6
	v_lshlrev_b32_e32 v26, 16, v66
	v_and_b32_e32 v27, 0xffff0000, v66
	v_pk_fma_f32 v[16:17], v[8:9], v[16:17], v[18:19]
	v_mul_f32_e32 v9, v250, v10
	v_pk_fma_f32 v[24:25], v[0:1], v[24:25], v[26:27]
	v_mul_f32_e32 v1, v250, v2
	v_mul_f32_e32 v9, 0xbfb8aa3b, v9
	v_mul_f32_e32 v10, v250, v15
	v_mul_f32_e32 v1, 0xbfb8aa3b, v1
	v_mul_f32_e32 v2, v250, v7
	v_exp_f32_e32 v9, v9
	v_mul_f32_e32 v10, 0xbfb8aa3b, v10
	v_exp_f32_e32 v1, v1
	v_mul_f32_e32 v2, 0xbfb8aa3b, v2
	v_add_f32_e32 v8, 1.0, v14
	v_exp_f32_e32 v14, v10
	v_add_f32_e32 v0, 1.0, v6
	v_exp_f32_e32 v6, v2
	v_add_f32_e32 v9, 1.0, v9
	v_mul_f32_e32 v11, v250, v11
	v_add_f32_e32 v1, 1.0, v1
	v_mul_f32_e32 v3, v250, v3
	v_rcp_f32_e32 v10, v9
	v_add_f32_e32 v9, 1.0, v14
	v_mul_f32_e32 v11, 0xbfb8aa3b, v11
	v_rcp_f32_e32 v2, v1
	v_add_f32_e32 v1, 1.0, v6
	v_mul_f32_e32 v3, 0xbfb8aa3b, v3
	v_rcp_f32_e32 v8, v8
	v_rcp_f32_e32 v9, v9
	v_exp_f32_e32 v11, v11
	v_rcp_f32_e32 v0, v0
	v_rcp_f32_e32 v1, v1
	v_exp_f32_e32 v3, v3
	v_lshlrev_b32_e32 v14, 16, v77
	v_and_b32_e32 v15, 0xffff0000, v77
	v_lshlrev_b32_e32 v18, 16, v73
	v_and_b32_e32 v19, 0xffff0000, v73
	v_lshlrev_b32_e32 v6, 16, v69
	v_and_b32_e32 v7, 0xffff0000, v69
	v_lshlrev_b32_e32 v26, 16, v65
	v_and_b32_e32 v27, 0xffff0000, v65
	v_pk_fma_f32 v[14:15], v[8:9], v[14:15], v[18:19]
	v_add_f32_e32 v8, 1.0, v11
	v_pk_fma_f32 v[6:7], v[0:1], v[6:7], v[26:27]
	v_add_f32_e32 v0, 1.0, v3
	v_rcp_f32_e32 v11, v8
	v_rcp_f32_e32 v3, v0
	v_lshlrev_b32_e32 v8, 16, v79
	v_and_b32_e32 v9, 0xffff0000, v79
	v_lshlrev_b32_e32 v18, 16, v75
	v_and_b32_e32 v19, 0xffff0000, v75
	v_lshlrev_b32_e32 v0, 16, v71
	v_and_b32_e32 v1, 0xffff0000, v71
	v_lshlrev_b32_e32 v26, 16, v67
	v_and_b32_e32 v27, 0xffff0000, v67
	v_pk_fma_f32 v[18:19], v[10:11], v[8:9], v[18:19]
	v_lshl_add_u64 v[8:9], s[26:27], 0, v[122:123]
	v_pk_fma_f32 v[26:27], v[2:3], v[0:1], v[26:27]
	v_pk_mul_f32 v[0:1], v[4:5], v[4:5]
	v_pk_mul_f32 v[2:3], v[6:7], v[6:7]
	v_lshl_add_u64 v[20:21], v[212:213], 1, v[8:9]
	v_cvt_pk_bf16_f32 v8, v12, v13
	v_cvt_pk_bf16_f32 v9, v14, v15
	v_pk_mul_f32 v[10:11], v[12:13], v[12:13]
	v_pk_mul_f32 v[12:13], v[14:15], v[14:15]
	v_pk_mul_f32 v[14:15], v[16:17], v[16:17]
	v_pk_mul_f32 v[22:23], v[18:19], v[18:19]
	v_add_f32_e32 v2, v2, v3
	v_add_f32_e32 v0, v0, v1
	v_pk_mul_f32 v[28:29], v[24:25], v[24:25]
	v_pk_mul_f32 v[30:31], v[26:27], v[26:27]
	v_add_f32_e32 v0, v0, v2
	v_add_f32_e32 v1, v22, v23
	v_add_f32_e32 v2, v14, v15
	v_add_f32_e32 v30, v30, v31
	v_add_f32_e32 v28, v28, v29
	v_add_f32_e32 v1, v2, v1
	v_add_f32_e32 v2, v12, v13
	v_add_f32_e32 v3, v10, v11
	v_add_f32_e32 v28, v28, v30
	v_add_f32_e32 v2, v3, v2
	v_add_f32_e32 v0, v0, v28
	v_add_f32_e32 v1, v2, v1
	v_add_f32_e32 v0, v1, v0
	ds_bpermute_b32 v1, v234, v0
	v_cvt_pk_bf16_f32 v10, v16, v17
	v_cvt_pk_bf16_f32 v11, v18, v19
	v_cvt_pk_bf16_f32 v2, v4, v5
	s_waitcnt lgkmcnt(0)
	v_add_f32_e32 v0, v0, v1
	ds_bpermute_b32 v1, v235, v0
	v_cvt_pk_bf16_f32 v3, v6, v7
	v_cvt_pk_bf16_f32 v4, v24, v25
	v_cvt_pk_bf16_f32 v5, v26, v27
	global_store_dwordx4 v[20:21], v[8:11], off
	global_store_dwordx4 v[20:21], v[2:5], off offset:256
	s_and_saveexec_b64 s[38:39], s[4:5]
	s_cbranch_execz .LBB0_1222
	s_waitcnt lgkmcnt(0)
	v_add_f32_e32 v2, v0, v1
	s_lshl_b32 s0, s56, 2
	v_lshlrev_b64 v[0:1], 7, v[120:121]
	s_ashr_i32 s1, s0, 31
	v_lshl_add_u64 v[0:1], s[30:31], 0, v[0:1]
	v_lshl_add_u64 v[0:1], s[0:1], 2, v[0:1]
	s_lshl_b32 s24, s57, 2
	v_lshl_add_u64 v[0:1], v[0:1], 0, s[24:25]
	global_store_dword v[0:1], v2, off
